# row-pass loops of P3/P10: 16-byte-per-lane loads and stores, three register sets (loads three batches ahead)
# baseline (speedup 1.0000x reference)
;     __device__ __forceinline__ const float* in(int i) const { return karg_in(i); }
; __device__ __forceinline__ const float* xrow_ptr(const Ctx& C, int row) { return row < MPROMPT ? C.in(0) + (size_t)row * DM : C.in(1) + (size_t)(row - MPROMPT) * DM; }
; __device__ __forceinline__ v4f ld4_bf16(const bf16* p) { const v2u w = *(const v2u*)p; return (v4f){bf_lo(w.x), bf_hi(w.x), bf_lo(w.y), bf_hi(w.y)}; }
; __device__ __forceinline__ float ssq4(v4f v) { return (v.x * v.x + v.y * v.y) + (v.z * v.z + v.w * v.w); }
; #define FTID const int ftid_ = fresh_tid()
; template <int R, bool BASE_F32, bool OUT_F32>
; __device__ __forceinline__ void rows_res(const Ctx& C, int m0, int stride, int mx, const float* gpost, float scale, int lane) {
;     ...
;     const bf16* D = C.D(); bf16* XN = C.XN();
; #pragma unroll
;     for (int r = 0; r < R; ++r) { mr[r] = (r == 4) ? mx : m0 + r * stride; ok[r] = (r == 4) ? (mx < M) : (mr[r] < MPROMPT); const int mm = ok[r] ? mr[r] : 0;
; #pragma unroll
;         for (int j = 0; j < 4; ++j) d[r][j] = ld4_bf16(D + (size_t)mm * DM + 4 * lane + 256 * j);
;         if (BASE_F32) { const float* x = xrow_ptr(C, mm);
; #pragma unroll
;             for (int j = 0; j < 4; ++j) b[r][j] = ld4_f32(x + 4 * lane + 256 * j);
;         } else { const float inv = C.RS()[mm];
; #pragma unroll
;             for (int j = 0; j < 4; ++j) b[r][j] = ld4_bf16(XN + (size_t)mm * DM + 4 * lane + 256 * j) * inv;
;         } }
; #pragma unroll
;     for (int r = 0; r < R; ++r) { float s = 0.f;
; #pragma unroll
;         for (int j = 0; j < 4; ++j) s += ssq4(d[r][j]);
;         r1[r] = s; }
; #pragma unroll
;     for (int r = 0; r < R; ++r) r1[r] = rsqrtf(wave_sum(r1[r]) * (1.f / DM) + EPS) * scale;
; __global__ void __launch_bounds__(NTHREADS, 2) fwd_kernel(Args args) {
;     ...
;     { FTID; const float* gp = C.in(8); { const int gw_ = GWV, ngw_ = NGWV, nit = (MPROMPT + 4 * ngw_ - 1) / (4 * ngw_);
;       for (int it = 0; it < nit - 1; ++it) rows_res<4, false, false>(C, gw_ + 4 * it * ngw_, ngw_, M, gp, 0.5f, LANE);
.LBB0_366:
	s_or_b64 exec, exec, s[6:7]
	s_waitcnt lgkmcnt(0)
	v_mov_b32_e32 v0, v182
	s_mov_b64 s[0:1], s[80:81]
	s_barrier
	s_load_dwordx2 s[14:15], s[0:1], 0x40
	v_readfirstlane_b32 s0, v0
	s_ashr_i32 s47, s0, 6
	v_readlane_b32 s0, v232, 0
	s_add_i32 s42, s47, s0
	v_readlane_b32 s0, v232, 1
	v_and_b32_e32 v189, 63, v0
	v_readlane_b32 s1, v232, 2
	v_lshlrev_b32_e32 v0, 2, v189
	v_mov_b32_e32 v1, 0
	v_cndmask_b32_e64 v2, 0, 1, s[0:1]
	v_cmp_ne_u32_e64 s[6:7], 1, v2
	s_andn2_b64 vcc, exec, s[0:1]
	v_lshlrev_b32_e32 v2, 2, v0
	v_cmp_ne_u32_e64 s[8:9], 0, v189
	v_lshlrev_b32_e32 v0, 1, v0
	s_load_dwordx2 s[98:99], s[80:81], 0x110
	s_load_dwordx2 s[100:101], s[80:81], 0x40
	v_and_b32_e32 v176, 63, v182
	v_lshlrev_b32_e32 v170, 4, v176
	s_lshl_b32 vcc_lo, s42, 11
	v_add_u32_e32 v170, vcc_lo, v170
	v_add_u32_e32 v171, 0x3000000, v170
	v_add_u32_e32 v170, 0x7100000, v170
	v_mov_b32_e32 v173, v171
	s_lshl_b32 vcc_lo, s42, 2
	v_mov_b32_e32 v172, 0x2a80000
	v_add_u32_e32 v172, vcc_lo, v172
	v_mov_b32_e32 v174, v172
	v_lshlrev_b32_e32 v176, 5, v176
	v_mov_b32_e32 v138, 0x358637bd
	s_waitcnt lgkmcnt(0)
	global_load_dwordx4 v[192:195], v176, s[100:101]
	global_load_dwordx4 v[196:199], v176, s[100:101] offset:16
	global_load_dwordx4 v[200:203], v176, s[100:101] offset:2048
	global_load_dwordx4 v[204:207], v176, s[100:101] offset:2064
	global_load_dword v52, v172, s[98:99]
	global_load_dwordx4 v[20:23], v170, s[98:99]
	global_load_dwordx4 v[24:27], v170, s[98:99] offset:1024
	global_load_dwordx4 v[36:39], v171, s[98:99]
	global_load_dwordx4 v[40:43], v171, s[98:99] offset:1024
	v_add_u32_e32 v170, 0x400000, v170
	v_add_u32_e32 v171, 0x400000, v171
	v_add_u32_e32 v172, 0x2000, v172
	global_load_dword v54, v172, s[98:99]
	global_load_dwordx4 v[28:31], v170, s[98:99]
	global_load_dwordx4 v[32:35], v170, s[98:99] offset:1024
	global_load_dwordx4 v[44:47], v171, s[98:99]
	global_load_dwordx4 v[48:51], v171, s[98:99] offset:1024
	v_add_u32_e32 v170, 0x400000, v170
	v_add_u32_e32 v171, 0x400000, v171
	v_add_u32_e32 v172, 0x2000, v172
	global_load_dword v88, v172, s[98:99]
	global_load_dwordx4 v[56:59], v170, s[98:99]
	global_load_dwordx4 v[60:63], v170, s[98:99] offset:1024
	global_load_dwordx4 v[72:75], v171, s[98:99]
	global_load_dwordx4 v[76:79], v171, s[98:99] offset:1024
	v_add_u32_e32 v170, 0x400000, v170
	v_add_u32_e32 v171, 0x400000, v171
	v_add_u32_e32 v172, 0x2000, v172
	global_load_dword v90, v172, s[98:99]
	global_load_dwordx4 v[64:67], v170, s[98:99]
	global_load_dwordx4 v[68:71], v170, s[98:99] offset:1024
	global_load_dwordx4 v[80:83], v171, s[98:99]
	global_load_dwordx4 v[84:87], v171, s[98:99] offset:1024
	v_add_u32_e32 v170, 0x400000, v170
	v_add_u32_e32 v171, 0x400000, v171
	v_add_u32_e32 v172, 0x2000, v172
	global_load_dword v12, v172, s[98:99]
	global_load_dwordx4 v[208:211], v170, s[98:99]
	global_load_dwordx4 v[212:215], v170, s[98:99] offset:1024
	global_load_dwordx4 v[224:227], v171, s[98:99]
	global_load_dwordx4 v[228:231], v171, s[98:99] offset:1024
	v_add_u32_e32 v170, 0x400000, v170
	v_add_u32_e32 v171, 0x400000, v171
	v_add_u32_e32 v172, 0x2000, v172
	global_load_dword v14, v172, s[98:99]
	global_load_dwordx4 v[216:219], v170, s[98:99]
	global_load_dwordx4 v[220:223], v170, s[98:99] offset:1024
	global_load_dwordx4 v[4:7], v171, s[98:99]
	global_load_dwordx4 v[8:11], v171, s[98:99] offset:1024
	v_add_u32_e32 v170, 0x400000, v170
	v_add_u32_e32 v171, 0x400000, v171
	v_add_u32_e32 v172, 0x2000, v172
	s_waitcnt vmcnt(27)
	v_lshlrev_b32_e32 v96, 16, v20
	v_and_b32_e32 v97, 0xffff0000, v20
	v_lshlrev_b32_e32 v98, 16, v21
	v_and_b32_e32 v99, 0xffff0000, v21
	v_lshlrev_b32_e32 v100, 16, v22
	v_and_b32_e32 v101, 0xffff0000, v22
	v_lshlrev_b32_e32 v102, 16, v23
	v_and_b32_e32 v103, 0xffff0000, v23
	v_lshlrev_b32_e32 v104, 16, v24
	v_and_b32_e32 v105, 0xffff0000, v24
	v_lshlrev_b32_e32 v106, 16, v25
	v_and_b32_e32 v107, 0xffff0000, v25
	v_lshlrev_b32_e32 v108, 16, v26
	v_and_b32_e32 v109, 0xffff0000, v26
	v_lshlrev_b32_e32 v110, 16, v27
	v_and_b32_e32 v111, 0xffff0000, v27
	v_pk_mul_f32 v[128:129], v[96:97], v[96:97]
	v_pk_fma_f32 v[128:129], v[98:99], v[98:99], v[128:129]
	v_pk_fma_f32 v[128:129], v[100:101], v[100:101], v[128:129]
	v_pk_fma_f32 v[128:129], v[102:103], v[102:103], v[128:129]
	v_pk_fma_f32 v[128:129], v[104:105], v[104:105], v[128:129]
	v_pk_fma_f32 v[128:129], v[106:107], v[106:107], v[128:129]
	v_pk_fma_f32 v[128:129], v[108:109], v[108:109], v[128:129]
	v_pk_fma_f32 v[128:129], v[110:111], v[110:111], v[128:129]
	s_nop 0
	v_add_f32_e32 v128, v128, v129
	s_waitcnt vmcnt(22)
	v_lshlrev_b32_e32 v112, 16, v28
	v_and_b32_e32 v113, 0xffff0000, v28
	v_lshlrev_b32_e32 v114, 16, v29
	v_and_b32_e32 v115, 0xffff0000, v29
	v_lshlrev_b32_e32 v116, 16, v30
	v_and_b32_e32 v117, 0xffff0000, v30
	v_lshlrev_b32_e32 v118, 16, v31
	v_and_b32_e32 v119, 0xffff0000, v31
	v_lshlrev_b32_e32 v120, 16, v32
	v_and_b32_e32 v121, 0xffff0000, v32
	v_lshlrev_b32_e32 v122, 16, v33
	v_and_b32_e32 v123, 0xffff0000, v33
	v_lshlrev_b32_e32 v124, 16, v34
	v_and_b32_e32 v125, 0xffff0000, v34
	v_lshlrev_b32_e32 v126, 16, v35
	v_and_b32_e32 v127, 0xffff0000, v35
	v_pk_mul_f32 v[130:131], v[112:113], v[112:113]
	v_pk_fma_f32 v[130:131], v[114:115], v[114:115], v[130:131]
	v_pk_fma_f32 v[130:131], v[116:117], v[116:117], v[130:131]
	v_pk_fma_f32 v[130:131], v[118:119], v[118:119], v[130:131]
	v_pk_fma_f32 v[130:131], v[120:121], v[120:121], v[130:131]
	v_pk_fma_f32 v[130:131], v[122:123], v[122:123], v[130:131]
	v_pk_fma_f32 v[130:131], v[124:125], v[124:125], v[130:131]
	v_pk_fma_f32 v[130:131], v[126:127], v[126:127], v[130:131]
	s_nop 0
	v_add_f32_e32 v130, v130, v131
	s_nop 1
	v_add_f32_dpp v128, v128, v128 quad_perm:[1,0,3,2] row_mask:0xf bank_mask:0xf
	v_add_f32_dpp v130, v130, v130 quad_perm:[1,0,3,2] row_mask:0xf bank_mask:0xf
	s_nop 0
	v_add_f32_dpp v128, v128, v128 quad_perm:[2,3,0,1] row_mask:0xf bank_mask:0xf
	v_add_f32_dpp v130, v130, v130 quad_perm:[2,3,0,1] row_mask:0xf bank_mask:0xf
	s_nop 0
	v_add_f32_dpp v128, v128, v128 row_half_mirror row_mask:0xf bank_mask:0xf
	v_add_f32_dpp v130, v130, v130 row_half_mirror row_mask:0xf bank_mask:0xf
	s_nop 0
	v_add_f32_dpp v128, v128, v128 row_mirror row_mask:0xf bank_mask:0xf
	v_add_f32_dpp v130, v130, v130 row_mirror row_mask:0xf bank_mask:0xf
	s_nop 0
	ds_bpermute_b32 v136, v187, v128
	ds_bpermute_b32 v137, v187, v130
	s_waitcnt lgkmcnt(0)
;     __device__ __forceinline__ float* out() const { return (float*)karg_in(33); }
; __device__ __forceinline__ float ssq4(v4f v) { return (v.x * v.x + v.y * v.y) + (v.z * v.z + v.w * v.w); }
; template <int R, bool BASE_F32, bool OUT_F32>
; __device__ __forceinline__ void rows_res(const Ctx& C, int m0, int stride, int mx, const float* gpost, float scale, int lane) {
;     ...
;     for (int r = 0; r < R; ++r) r1[r] = rsqrtf(wave_sum(r1[r]) * (1.f / DM) + EPS) * scale;
; #pragma unroll
;     for (int j = 0; j < 4; ++j) { const v4f gp = ld4_f32(gpost + 4 * lane + 256 * j);
; #pragma unroll
;         for (int r = 0; r < R; ++r) d[r][j] = b[r][j] + d[r][j] * r1[r] * gp; }
;     if (OUT_F32) { float* Y = C.out();
; #pragma unroll
;         for (int r = 0; r < R; ++r)
; #pragma unroll
;             for (int j = 0; j < 4; ++j) if (ok[r]) *(v4f*)(Y + (size_t)mr[r] * DM + 4 * lane + 256 * j) = d[r][j];
;     } else { float* rs = C.RS(); float t[R];
; #pragma unroll
;         for (int r = 0; r < R; ++r) { float s = 0.f;
; #pragma unroll
;             for (int j = 0; j < 4; ++j) s += ssq4(d[r][j]);
;             t[r] = s; }
	v_add_f32_e32 v128, v128, v136
	v_add_f32_e32 v130, v130, v137
	ds_bpermute_b32 v136, v188, v128
	ds_bpermute_b32 v137, v188, v130
	s_waitcnt lgkmcnt(0)
	v_add_f32_e32 v128, v128, v136
	v_add_f32_e32 v130, v130, v137
	v_fmamk_f32 v128, v128, 0x3a800000, v138
	v_fmamk_f32 v130, v130, 0x3a800000, v138
	s_nop 0
	v_rsq_f32_e32 v128, v128
	v_rsq_f32_e32 v130, v130
	s_nop 1
	v_mul_f32_e32 v128, 0.5, v128
	v_mul_f32_e32 v130, 0.5, v130
	s_waitcnt vmcnt(20)
	v_pk_mul_f32 v[96:97], v[128:129], v[96:97] op_sel_hi:[0,1]
	v_pk_mul_f32 v[98:99], v[128:129], v[98:99] op_sel_hi:[0,1]
	v_pk_mul_f32 v[100:101], v[128:129], v[100:101] op_sel_hi:[0,1]
	v_pk_mul_f32 v[102:103], v[128:129], v[102:103] op_sel_hi:[0,1]
	v_pk_mul_f32 v[104:105], v[128:129], v[104:105] op_sel_hi:[0,1]
	v_pk_mul_f32 v[106:107], v[128:129], v[106:107] op_sel_hi:[0,1]
	v_pk_mul_f32 v[108:109], v[128:129], v[108:109] op_sel_hi:[0,1]
	v_pk_mul_f32 v[110:111], v[128:129], v[110:111] op_sel_hi:[0,1]
	v_pk_mul_f32 v[96:97], v[96:97], v[192:193]
	v_pk_mul_f32 v[98:99], v[98:99], v[194:195]
	v_pk_mul_f32 v[100:101], v[100:101], v[196:197]
	v_pk_mul_f32 v[102:103], v[102:103], v[198:199]
	v_pk_mul_f32 v[104:105], v[104:105], v[200:201]
	v_pk_mul_f32 v[106:107], v[106:107], v[202:203]
	v_pk_mul_f32 v[108:109], v[108:109], v[204:205]
	v_pk_mul_f32 v[110:111], v[110:111], v[206:207]
	v_lshlrev_b32_e32 v20, 16, v36
	v_and_b32_e32 v21, 0xffff0000, v36
	v_lshlrev_b32_e32 v22, 16, v37
	v_and_b32_e32 v23, 0xffff0000, v37
	v_lshlrev_b32_e32 v24, 16, v38
	v_and_b32_e32 v25, 0xffff0000, v38
	v_lshlrev_b32_e32 v26, 16, v39
	v_and_b32_e32 v27, 0xffff0000, v39
	v_pk_fma_f32 v[96:97], v[52:53], v[20:21], v[96:97] op_sel_hi:[0,1,1]
	v_pk_fma_f32 v[98:99], v[52:53], v[22:23], v[98:99] op_sel_hi:[0,1,1]
	v_pk_fma_f32 v[100:101], v[52:53], v[24:25], v[100:101] op_sel_hi:[0,1,1]
	v_pk_fma_f32 v[102:103], v[52:53], v[26:27], v[102:103] op_sel_hi:[0,1,1]
	v_lshlrev_b32_e32 v20, 16, v40
	v_and_b32_e32 v21, 0xffff0000, v40
	v_lshlrev_b32_e32 v22, 16, v41
	v_and_b32_e32 v23, 0xffff0000, v41
	v_lshlrev_b32_e32 v24, 16, v42
	v_and_b32_e32 v25, 0xffff0000, v42
	v_lshlrev_b32_e32 v26, 16, v43
	v_and_b32_e32 v27, 0xffff0000, v43
	v_pk_fma_f32 v[104:105], v[52:53], v[20:21], v[104:105] op_sel_hi:[0,1,1]
	v_pk_fma_f32 v[106:107], v[52:53], v[22:23], v[106:107] op_sel_hi:[0,1,1]
	v_pk_fma_f32 v[108:109], v[52:53], v[24:25], v[108:109] op_sel_hi:[0,1,1]
	v_pk_fma_f32 v[110:111], v[52:53], v[26:27], v[110:111] op_sel_hi:[0,1,1]
	v_pk_mul_f32 v[132:133], v[96:97], v[96:97]
	v_pk_fma_f32 v[132:133], v[98:99], v[98:99], v[132:133]
	v_pk_fma_f32 v[132:133], v[100:101], v[100:101], v[132:133]
	v_pk_fma_f32 v[132:133], v[102:103], v[102:103], v[132:133]
	v_pk_fma_f32 v[132:133], v[104:105], v[104:105], v[132:133]
	v_pk_fma_f32 v[132:133], v[106:107], v[106:107], v[132:133]
	v_pk_fma_f32 v[132:133], v[108:109], v[108:109], v[132:133]
	v_pk_fma_f32 v[132:133], v[110:111], v[110:111], v[132:133]
	s_nop 0
	v_add_f32_e32 v132, v132, v133
	v_pk_mul_f32 v[112:113], v[130:131], v[112:113] op_sel_hi:[0,1]
	v_pk_mul_f32 v[114:115], v[130:131], v[114:115] op_sel_hi:[0,1]
	v_pk_mul_f32 v[116:117], v[130:131], v[116:117] op_sel_hi:[0,1]
	v_pk_mul_f32 v[118:119], v[130:131], v[118:119] op_sel_hi:[0,1]
	v_pk_mul_f32 v[120:121], v[130:131], v[120:121] op_sel_hi:[0,1]
	v_pk_mul_f32 v[122:123], v[130:131], v[122:123] op_sel_hi:[0,1]
	v_pk_mul_f32 v[124:125], v[130:131], v[124:125] op_sel_hi:[0,1]
	v_pk_mul_f32 v[126:127], v[130:131], v[126:127] op_sel_hi:[0,1]
	v_pk_mul_f32 v[112:113], v[112:113], v[192:193]
	v_pk_mul_f32 v[114:115], v[114:115], v[194:195]
	v_pk_mul_f32 v[116:117], v[116:117], v[196:197]
	v_pk_mul_f32 v[118:119], v[118:119], v[198:199]
	v_pk_mul_f32 v[120:121], v[120:121], v[200:201]
	v_pk_mul_f32 v[122:123], v[122:123], v[202:203]
	v_pk_mul_f32 v[124:125], v[124:125], v[204:205]
	v_pk_mul_f32 v[126:127], v[126:127], v[206:207]
	v_lshlrev_b32_e32 v28, 16, v44
	v_and_b32_e32 v29, 0xffff0000, v44
	v_lshlrev_b32_e32 v30, 16, v45
	v_and_b32_e32 v31, 0xffff0000, v45
	v_lshlrev_b32_e32 v32, 16, v46
	v_and_b32_e32 v33, 0xffff0000, v46
	v_lshlrev_b32_e32 v34, 16, v47
	v_and_b32_e32 v35, 0xffff0000, v47
	v_pk_fma_f32 v[112:113], v[54:55], v[28:29], v[112:113] op_sel_hi:[0,1,1]
	v_pk_fma_f32 v[114:115], v[54:55], v[30:31], v[114:115] op_sel_hi:[0,1,1]
	v_pk_fma_f32 v[116:117], v[54:55], v[32:33], v[116:117] op_sel_hi:[0,1,1]
	v_pk_fma_f32 v[118:119], v[54:55], v[34:35], v[118:119] op_sel_hi:[0,1,1]
	v_lshlrev_b32_e32 v28, 16, v48
	v_and_b32_e32 v29, 0xffff0000, v48
	v_lshlrev_b32_e32 v30, 16, v49
	v_and_b32_e32 v31, 0xffff0000, v49
	v_lshlrev_b32_e32 v32, 16, v50
	v_and_b32_e32 v33, 0xffff0000, v50
	v_lshlrev_b32_e32 v34, 16, v51
	v_and_b32_e32 v35, 0xffff0000, v51
	v_pk_fma_f32 v[120:121], v[54:55], v[28:29], v[120:121] op_sel_hi:[0,1,1]
	v_pk_fma_f32 v[122:123], v[54:55], v[30:31], v[122:123] op_sel_hi:[0,1,1]
	v_pk_fma_f32 v[124:125], v[54:55], v[32:33], v[124:125] op_sel_hi:[0,1,1]
	v_pk_fma_f32 v[126:127], v[54:55], v[34:35], v[126:127] op_sel_hi:[0,1,1]
	v_pk_mul_f32 v[134:135], v[112:113], v[112:113]
	v_pk_fma_f32 v[134:135], v[114:115], v[114:115], v[134:135]
	v_pk_fma_f32 v[134:135], v[116:117], v[116:117], v[134:135]
	v_pk_fma_f32 v[134:135], v[118:119], v[118:119], v[134:135]
	v_pk_fma_f32 v[134:135], v[120:121], v[120:121], v[134:135]
	v_pk_fma_f32 v[134:135], v[122:123], v[122:123], v[134:135]
	v_pk_fma_f32 v[134:135], v[124:125], v[124:125], v[134:135]
	v_pk_fma_f32 v[134:135], v[126:127], v[126:127], v[134:135]
	s_nop 0
	v_add_f32_e32 v134, v134, v135
	s_nop 1
	v_add_f32_dpp v132, v132, v132 quad_perm:[1,0,3,2] row_mask:0xf bank_mask:0xf
	v_add_f32_dpp v134, v134, v134 quad_perm:[1,0,3,2] row_mask:0xf bank_mask:0xf
	s_nop 0
	v_add_f32_dpp v132, v132, v132 quad_perm:[2,3,0,1] row_mask:0xf bank_mask:0xf
	v_add_f32_dpp v134, v134, v134 quad_perm:[2,3,0,1] row_mask:0xf bank_mask:0xf
	s_nop 0
	v_add_f32_dpp v132, v132, v132 row_half_mirror row_mask:0xf bank_mask:0xf
	v_add_f32_dpp v134, v134, v134 row_half_mirror row_mask:0xf bank_mask:0xf
	s_nop 0
	v_add_f32_dpp v132, v132, v132 row_mirror row_mask:0xf bank_mask:0xf
	v_add_f32_dpp v134, v134, v134 row_mirror row_mask:0xf bank_mask:0xf
	s_nop 0
	ds_bpermute_b32 v136, v187, v132
	ds_bpermute_b32 v137, v187, v134
	s_waitcnt lgkmcnt(0)
; __device__ __forceinline__ const float* xrow_ptr(const Ctx& C, int row) { return row < MPROMPT ? C.in(0) + (size_t)row * DM : C.in(1) + (size_t)(row - MPROMPT) * DM; }
; __device__ __forceinline__ v4f ld4_bf16(const bf16* p) { const v2u w = *(const v2u*)p; return (v4f){bf_lo(w.x), bf_hi(w.x), bf_lo(w.y), bf_hi(w.y)}; }
; __device__ __forceinline__ void st4_bf16(bf16* p, v4f o) { v2u w; w.x = cvt_pk_nv(o.x, o.y); w.y = cvt_pk_nv(o.z, o.w); *(v2u*)p = w; }
; __device__ __forceinline__ float ssq4(v4f v) { return (v.x * v.x + v.y * v.y) + (v.z * v.z + v.w * v.w); }
; template <int R, bool BASE_F32, bool OUT_F32>
; __device__ __forceinline__ void rows_res(const Ctx& C, int m0, int stride, int mx, const float* gpost, float scale, int lane) {
;     ...
;     for (int r = 0; r < R; ++r) { mr[r] = (r == 4) ? mx : m0 + r * stride; ok[r] = (r == 4) ? (mx < M) : (mr[r] < MPROMPT); const int mm = ok[r] ? mr[r] : 0;
; #pragma unroll
;         for (int j = 0; j < 4; ++j) d[r][j] = ld4_bf16(D + (size_t)mm * DM + 4 * lane + 256 * j);
;         if (BASE_F32) { const float* x = xrow_ptr(C, mm);
; #pragma unroll
;             for (int j = 0; j < 4; ++j) b[r][j] = ld4_f32(x + 4 * lane + 256 * j);
;         } else { const float inv = C.RS()[mm];
; #pragma unroll
;             for (int j = 0; j < 4; ++j) b[r][j] = ld4_bf16(XN + (size_t)mm * DM + 4 * lane + 256 * j) * inv;
;         } }
;     ...
;     } else { float* rs = C.RS(); float t[R];
; #pragma unroll
;         for (int r = 0; r < R; ++r) { float s = 0.f;
; #pragma unroll
;             for (int j = 0; j < 4; ++j) s += ssq4(d[r][j]);
;             t[r] = s; }
; #pragma unroll
;         for (int r = 0; r < R; ++r) t[r] = wave_sum(t[r]) * (1.f / DM) + EPS;
; #pragma unroll
;         for (int r = 0; r < R; ++r) { const float rstd = rsqrtf(t[r]);
; #pragma unroll
;             for (int j = 0; j < 4; ++j) if (ok[r]) st4_bf16(XN + (size_t)mr[r] * DM + 4 * lane + 256 * j, d[r][j] * rstd);
;             if (lane == 0 && ok[r]) rs[mr[r]] = sqrtf(t[r]); }
	v_add_f32_e32 v132, v132, v136
	v_add_f32_e32 v134, v134, v137
	ds_bpermute_b32 v136, v188, v132
	ds_bpermute_b32 v137, v188, v134
	s_waitcnt lgkmcnt(0)
	v_add_f32_e32 v132, v132, v136
	v_add_f32_e32 v134, v134, v137
	v_fmamk_f32 v164, v132, 0x3a800000, v138
	v_fmamk_f32 v167, v134, 0x3a800000, v138
	s_nop 0
	v_rsq_f32_e32 v132, v164
	v_rsq_f32_e32 v134, v167
	v_sqrt_f32_e32 v165, v164
	v_sqrt_f32_e32 v168, v167
	s_nop 1
	v_pk_mul_f32 v[140:141], v[96:97], v[132:133] op_sel_hi:[1,0]
	v_cvt_pk_bf16_f32 v148, v140, v141
	v_pk_mul_f32 v[142:143], v[98:99], v[132:133] op_sel_hi:[1,0]
	v_cvt_pk_bf16_f32 v149, v142, v143
	v_pk_mul_f32 v[144:145], v[100:101], v[132:133] op_sel_hi:[1,0]
	v_cvt_pk_bf16_f32 v150, v144, v145
	v_pk_mul_f32 v[146:147], v[102:103], v[132:133] op_sel_hi:[1,0]
	v_cvt_pk_bf16_f32 v151, v146, v147
	v_pk_mul_f32 v[140:141], v[104:105], v[132:133] op_sel_hi:[1,0]
	v_cvt_pk_bf16_f32 v152, v140, v141
	v_pk_mul_f32 v[142:143], v[106:107], v[132:133] op_sel_hi:[1,0]
	v_cvt_pk_bf16_f32 v153, v142, v143
	v_pk_mul_f32 v[144:145], v[108:109], v[132:133] op_sel_hi:[1,0]
	v_cvt_pk_bf16_f32 v154, v144, v145
	v_pk_mul_f32 v[146:147], v[110:111], v[132:133] op_sel_hi:[1,0]
	v_cvt_pk_bf16_f32 v155, v146, v147
	global_store_dwordx4 v173, v[148:151], s[98:99]
	global_store_dwordx4 v173, v[152:155], s[98:99] offset:1024
	v_add_u32_e32 v173, 0x400000, v173
	v_pk_mul_f32 v[140:141], v[112:113], v[134:135] op_sel_hi:[1,0]
	v_cvt_pk_bf16_f32 v156, v140, v141
	v_pk_mul_f32 v[142:143], v[114:115], v[134:135] op_sel_hi:[1,0]
	v_cvt_pk_bf16_f32 v157, v142, v143
	v_pk_mul_f32 v[144:145], v[116:117], v[134:135] op_sel_hi:[1,0]
	v_cvt_pk_bf16_f32 v158, v144, v145
	v_pk_mul_f32 v[146:147], v[118:119], v[134:135] op_sel_hi:[1,0]
	v_cvt_pk_bf16_f32 v159, v146, v147
	v_pk_mul_f32 v[140:141], v[120:121], v[134:135] op_sel_hi:[1,0]
	v_cvt_pk_bf16_f32 v160, v140, v141
	v_pk_mul_f32 v[142:143], v[122:123], v[134:135] op_sel_hi:[1,0]
	v_cvt_pk_bf16_f32 v161, v142, v143
	v_pk_mul_f32 v[144:145], v[124:125], v[134:135] op_sel_hi:[1,0]
	v_cvt_pk_bf16_f32 v162, v144, v145
	v_pk_mul_f32 v[146:147], v[126:127], v[134:135] op_sel_hi:[1,0]
	v_cvt_pk_bf16_f32 v163, v146, v147
	global_store_dwordx4 v173, v[156:159], s[98:99]
	global_store_dwordx4 v173, v[160:163], s[98:99] offset:1024
	v_add_u32_e32 v173, 0x400000, v173
	v_add_u32_e32 v166, -1, v165
	v_fma_f32 v140, -v166, v165, v164
	v_cmp_ge_f32_e32 vcc, 0, v140
	v_add_u32_e32 v141, 1, v165
	v_cndmask_b32_e32 v166, v165, v166, vcc
	v_fma_f32 v140, -v141, v165, v164
	v_cmp_lt_f32_e32 vcc, 0, v140
	s_nop 1
	v_cndmask_b32_e32 v165, v166, v141, vcc
	v_add_u32_e32 v169, -1, v168
	v_fma_f32 v142, -v169, v168, v167
	v_cmp_ge_f32_e32 vcc, 0, v142
	v_add_u32_e32 v143, 1, v168
	v_cndmask_b32_e32 v169, v168, v169, vcc
	v_fma_f32 v142, -v143, v168, v167
	v_cmp_lt_f32_e32 vcc, 0, v142
	s_nop 1
	v_cndmask_b32_e32 v168, v169, v143, vcc
	s_mov_b64 exec, 1
	global_store_dword v174, v165, s[98:99]
	v_add_u32_e32 v174, 0x2000, v174
	global_store_dword v174, v168, s[98:99]
	v_add_u32_e32 v174, 0x2000, v174
	s_mov_b64 exec, -1
	global_load_dword v52, v172, s[98:99]
	global_load_dwordx4 v[20:23], v170, s[98:99]
	global_load_dwordx4 v[24:27], v170, s[98:99] offset:1024
	global_load_dwordx4 v[36:39], v171, s[98:99]
	global_load_dwordx4 v[40:43], v171, s[98:99] offset:1024
	v_add_u32_e32 v170, 0x400000, v170
	v_add_u32_e32 v171, 0x400000, v171
	v_add_u32_e32 v172, 0x2000, v172
	global_load_dword v54, v172, s[98:99]
	global_load_dwordx4 v[28:31], v170, s[98:99]
	global_load_dwordx4 v[32:35], v170, s[98:99] offset:1024
	global_load_dwordx4 v[44:47], v171, s[98:99]
	global_load_dwordx4 v[48:51], v171, s[98:99] offset:1024
	v_add_u32_e32 v170, 0x400000, v170
	v_add_u32_e32 v171, 0x400000, v171
	v_add_u32_e32 v172, 0x2000, v172
	s_waitcnt vmcnt(33)
	v_lshlrev_b32_e32 v96, 16, v56
	v_and_b32_e32 v97, 0xffff0000, v56
	v_lshlrev_b32_e32 v98, 16, v57
	v_and_b32_e32 v99, 0xffff0000, v57
	v_lshlrev_b32_e32 v100, 16, v58
	v_and_b32_e32 v101, 0xffff0000, v58
	v_lshlrev_b32_e32 v102, 16, v59
	v_and_b32_e32 v103, 0xffff0000, v59
	v_lshlrev_b32_e32 v104, 16, v60
	v_and_b32_e32 v105, 0xffff0000, v60
	v_lshlrev_b32_e32 v106, 16, v61
	v_and_b32_e32 v107, 0xffff0000, v61
	v_lshlrev_b32_e32 v108, 16, v62
	v_and_b32_e32 v109, 0xffff0000, v62
	v_lshlrev_b32_e32 v110, 16, v63
	v_and_b32_e32 v111, 0xffff0000, v63
	v_pk_mul_f32 v[128:129], v[96:97], v[96:97]
	v_pk_fma_f32 v[128:129], v[98:99], v[98:99], v[128:129]
	v_pk_fma_f32 v[128:129], v[100:101], v[100:101], v[128:129]
	v_pk_fma_f32 v[128:129], v[102:103], v[102:103], v[128:129]
	v_pk_fma_f32 v[128:129], v[104:105], v[104:105], v[128:129]
	v_pk_fma_f32 v[128:129], v[106:107], v[106:107], v[128:129]
	v_pk_fma_f32 v[128:129], v[108:109], v[108:109], v[128:129]
	v_pk_fma_f32 v[128:129], v[110:111], v[110:111], v[128:129]
	s_nop 0
	v_add_f32_e32 v128, v128, v129
	s_waitcnt vmcnt(28)
; __device__ __forceinline__ float ssq4(v4f v) { return (v.x * v.x + v.y * v.y) + (v.z * v.z + v.w * v.w); }
; template <int R, bool BASE_F32, bool OUT_F32>
; __device__ __forceinline__ void rows_res(const Ctx& C, int m0, int stride, int mx, const float* gpost, float scale, int lane) {
;     ...
;     for (int r = 0; r < R; ++r) { float s = 0.f;
; #pragma unroll
;         for (int j = 0; j < 4; ++j) s += ssq4(d[r][j]);
;         r1[r] = s; }
; #pragma unroll
;     for (int r = 0; r < R; ++r) r1[r] = rsqrtf(wave_sum(r1[r]) * (1.f / DM) + EPS) * scale;
; #pragma unroll
;     for (int j = 0; j < 4; ++j) { const v4f gp = ld4_f32(gpost + 4 * lane + 256 * j);
; #pragma unroll
;         for (int r = 0; r < R; ++r) d[r][j] = b[r][j] + d[r][j] * r1[r] * gp; }
	v_lshlrev_b32_e32 v112, 16, v64
	v_and_b32_e32 v113, 0xffff0000, v64
	v_lshlrev_b32_e32 v114, 16, v65
	v_and_b32_e32 v115, 0xffff0000, v65
	v_lshlrev_b32_e32 v116, 16, v66
	v_and_b32_e32 v117, 0xffff0000, v66
	v_lshlrev_b32_e32 v118, 16, v67
	v_and_b32_e32 v119, 0xffff0000, v67
	v_lshlrev_b32_e32 v120, 16, v68
	v_and_b32_e32 v121, 0xffff0000, v68
	v_lshlrev_b32_e32 v122, 16, v69
	v_and_b32_e32 v123, 0xffff0000, v69
	v_lshlrev_b32_e32 v124, 16, v70
	v_and_b32_e32 v125, 0xffff0000, v70
	v_lshlrev_b32_e32 v126, 16, v71
	v_and_b32_e32 v127, 0xffff0000, v71
	v_pk_mul_f32 v[130:131], v[112:113], v[112:113]
	v_pk_fma_f32 v[130:131], v[114:115], v[114:115], v[130:131]
	v_pk_fma_f32 v[130:131], v[116:117], v[116:117], v[130:131]
	v_pk_fma_f32 v[130:131], v[118:119], v[118:119], v[130:131]
	v_pk_fma_f32 v[130:131], v[120:121], v[120:121], v[130:131]
	v_pk_fma_f32 v[130:131], v[122:123], v[122:123], v[130:131]
	v_pk_fma_f32 v[130:131], v[124:125], v[124:125], v[130:131]
	v_pk_fma_f32 v[130:131], v[126:127], v[126:127], v[130:131]
	s_nop 0
	v_add_f32_e32 v130, v130, v131
	s_nop 1
	v_add_f32_dpp v128, v128, v128 quad_perm:[1,0,3,2] row_mask:0xf bank_mask:0xf
	v_add_f32_dpp v130, v130, v130 quad_perm:[1,0,3,2] row_mask:0xf bank_mask:0xf
	s_nop 0
	v_add_f32_dpp v128, v128, v128 quad_perm:[2,3,0,1] row_mask:0xf bank_mask:0xf
	v_add_f32_dpp v130, v130, v130 quad_perm:[2,3,0,1] row_mask:0xf bank_mask:0xf
	s_nop 0
	v_add_f32_dpp v128, v128, v128 row_half_mirror row_mask:0xf bank_mask:0xf
	v_add_f32_dpp v130, v130, v130 row_half_mirror row_mask:0xf bank_mask:0xf
	s_nop 0
	v_add_f32_dpp v128, v128, v128 row_mirror row_mask:0xf bank_mask:0xf
	v_add_f32_dpp v130, v130, v130 row_mirror row_mask:0xf bank_mask:0xf
	s_nop 0
	ds_bpermute_b32 v136, v187, v128
	ds_bpermute_b32 v137, v187, v130
	s_waitcnt lgkmcnt(0)
	v_add_f32_e32 v128, v128, v136
	v_add_f32_e32 v130, v130, v137
	ds_bpermute_b32 v136, v188, v128
	ds_bpermute_b32 v137, v188, v130
	s_waitcnt lgkmcnt(0)
	v_add_f32_e32 v128, v128, v136
	v_add_f32_e32 v130, v130, v137
	v_fmamk_f32 v128, v128, 0x3a800000, v138
	v_fmamk_f32 v130, v130, 0x3a800000, v138
	s_nop 0
	v_rsq_f32_e32 v128, v128
	v_rsq_f32_e32 v130, v130
	s_nop 1
	v_mul_f32_e32 v128, 0.5, v128
	v_mul_f32_e32 v130, 0.5, v130
	s_waitcnt vmcnt(26)
	v_pk_mul_f32 v[96:97], v[128:129], v[96:97] op_sel_hi:[0,1]
	v_pk_mul_f32 v[98:99], v[128:129], v[98:99] op_sel_hi:[0,1]
	v_pk_mul_f32 v[100:101], v[128:129], v[100:101] op_sel_hi:[0,1]
	v_pk_mul_f32 v[102:103], v[128:129], v[102:103] op_sel_hi:[0,1]
	v_pk_mul_f32 v[104:105], v[128:129], v[104:105] op_sel_hi:[0,1]
	v_pk_mul_f32 v[106:107], v[128:129], v[106:107] op_sel_hi:[0,1]
	v_pk_mul_f32 v[108:109], v[128:129], v[108:109] op_sel_hi:[0,1]
	v_pk_mul_f32 v[110:111], v[128:129], v[110:111] op_sel_hi:[0,1]
	v_pk_mul_f32 v[96:97], v[96:97], v[192:193]
	v_pk_mul_f32 v[98:99], v[98:99], v[194:195]
	v_pk_mul_f32 v[100:101], v[100:101], v[196:197]
	v_pk_mul_f32 v[102:103], v[102:103], v[198:199]
	v_pk_mul_f32 v[104:105], v[104:105], v[200:201]
	v_pk_mul_f32 v[106:107], v[106:107], v[202:203]
	v_pk_mul_f32 v[108:109], v[108:109], v[204:205]
	v_pk_mul_f32 v[110:111], v[110:111], v[206:207]
	v_lshlrev_b32_e32 v56, 16, v72
	v_and_b32_e32 v57, 0xffff0000, v72
	v_lshlrev_b32_e32 v58, 16, v73
	v_and_b32_e32 v59, 0xffff0000, v73
	v_lshlrev_b32_e32 v60, 16, v74
	v_and_b32_e32 v61, 0xffff0000, v74
	v_lshlrev_b32_e32 v62, 16, v75
	v_and_b32_e32 v63, 0xffff0000, v75
	v_pk_fma_f32 v[96:97], v[88:89], v[56:57], v[96:97] op_sel_hi:[0,1,1]
	v_pk_fma_f32 v[98:99], v[88:89], v[58:59], v[98:99] op_sel_hi:[0,1,1]
	v_pk_fma_f32 v[100:101], v[88:89], v[60:61], v[100:101] op_sel_hi:[0,1,1]
	v_pk_fma_f32 v[102:103], v[88:89], v[62:63], v[102:103] op_sel_hi:[0,1,1]
	v_lshlrev_b32_e32 v56, 16, v76
	v_and_b32_e32 v57, 0xffff0000, v76
	v_lshlrev_b32_e32 v58, 16, v77
	v_and_b32_e32 v59, 0xffff0000, v77
	v_lshlrev_b32_e32 v60, 16, v78
	v_and_b32_e32 v61, 0xffff0000, v78
	v_lshlrev_b32_e32 v62, 16, v79
	v_and_b32_e32 v63, 0xffff0000, v79
	v_pk_fma_f32 v[104:105], v[88:89], v[56:57], v[104:105] op_sel_hi:[0,1,1]
	v_pk_fma_f32 v[106:107], v[88:89], v[58:59], v[106:107] op_sel_hi:[0,1,1]
	v_pk_fma_f32 v[108:109], v[88:89], v[60:61], v[108:109] op_sel_hi:[0,1,1]
	v_pk_fma_f32 v[110:111], v[88:89], v[62:63], v[110:111] op_sel_hi:[0,1,1]
	v_pk_mul_f32 v[132:133], v[96:97], v[96:97]
	v_pk_fma_f32 v[132:133], v[98:99], v[98:99], v[132:133]
	v_pk_fma_f32 v[132:133], v[100:101], v[100:101], v[132:133]
	v_pk_fma_f32 v[132:133], v[102:103], v[102:103], v[132:133]
	v_pk_fma_f32 v[132:133], v[104:105], v[104:105], v[132:133]
	v_pk_fma_f32 v[132:133], v[106:107], v[106:107], v[132:133]
	v_pk_fma_f32 v[132:133], v[108:109], v[108:109], v[132:133]
	v_pk_fma_f32 v[132:133], v[110:111], v[110:111], v[132:133]
	s_nop 0
	v_add_f32_e32 v132, v132, v133
	v_pk_mul_f32 v[112:113], v[130:131], v[112:113] op_sel_hi:[0,1]
	v_pk_mul_f32 v[114:115], v[130:131], v[114:115] op_sel_hi:[0,1]
	v_pk_mul_f32 v[116:117], v[130:131], v[116:117] op_sel_hi:[0,1]
	v_pk_mul_f32 v[118:119], v[130:131], v[118:119] op_sel_hi:[0,1]
	v_pk_mul_f32 v[120:121], v[130:131], v[120:121] op_sel_hi:[0,1]
	v_pk_mul_f32 v[122:123], v[130:131], v[122:123] op_sel_hi:[0,1]
	v_pk_mul_f32 v[124:125], v[130:131], v[124:125] op_sel_hi:[0,1]
	v_pk_mul_f32 v[126:127], v[130:131], v[126:127] op_sel_hi:[0,1]
	v_pk_mul_f32 v[112:113], v[112:113], v[192:193]
	v_pk_mul_f32 v[114:115], v[114:115], v[194:195]
	v_pk_mul_f32 v[116:117], v[116:117], v[196:197]
	v_pk_mul_f32 v[118:119], v[118:119], v[198:199]
	v_pk_mul_f32 v[120:121], v[120:121], v[200:201]
	v_pk_mul_f32 v[122:123], v[122:123], v[202:203]
;     __device__ __forceinline__ float* out() const { return (float*)karg_in(33); }
; __device__ __forceinline__ void st4_bf16(bf16* p, v4f o) { v2u w; w.x = cvt_pk_nv(o.x, o.y); w.y = cvt_pk_nv(o.z, o.w); *(v2u*)p = w; }
; __device__ __forceinline__ float ssq4(v4f v) { return (v.x * v.x + v.y * v.y) + (v.z * v.z + v.w * v.w); }
; template <int R, bool BASE_F32, bool OUT_F32>
; __device__ __forceinline__ void rows_res(const Ctx& C, int m0, int stride, int mx, const float* gpost, float scale, int lane) {
;     ...
;     for (int j = 0; j < 4; ++j) { const v4f gp = ld4_f32(gpost + 4 * lane + 256 * j);
; #pragma unroll
;         for (int r = 0; r < R; ++r) d[r][j] = b[r][j] + d[r][j] * r1[r] * gp; }
;     if (OUT_F32) { float* Y = C.out();
; #pragma unroll
;         for (int r = 0; r < R; ++r)
; #pragma unroll
;             for (int j = 0; j < 4; ++j) if (ok[r]) *(v4f*)(Y + (size_t)mr[r] * DM + 4 * lane + 256 * j) = d[r][j];
;     } else { float* rs = C.RS(); float t[R];
; #pragma unroll
;         for (int r = 0; r < R; ++r) { float s = 0.f;
; #pragma unroll
;             for (int j = 0; j < 4; ++j) s += ssq4(d[r][j]);
;             t[r] = s; }
; #pragma unroll
;         for (int r = 0; r < R; ++r) t[r] = wave_sum(t[r]) * (1.f / DM) + EPS;
; #pragma unroll
;         for (int r = 0; r < R; ++r) { const float rstd = rsqrtf(t[r]);
; #pragma unroll
;             for (int j = 0; j < 4; ++j) if (ok[r]) st4_bf16(XN + (size_t)mr[r] * DM + 4 * lane + 256 * j, d[r][j] * rstd);
;             if (lane == 0 && ok[r]) rs[mr[r]] = sqrtf(t[r]); }
	v_pk_mul_f32 v[124:125], v[124:125], v[204:205]
	v_pk_mul_f32 v[126:127], v[126:127], v[206:207]
	v_lshlrev_b32_e32 v64, 16, v80
	v_and_b32_e32 v65, 0xffff0000, v80
	v_lshlrev_b32_e32 v66, 16, v81
	v_and_b32_e32 v67, 0xffff0000, v81
	v_lshlrev_b32_e32 v68, 16, v82
	v_and_b32_e32 v69, 0xffff0000, v82
	v_lshlrev_b32_e32 v70, 16, v83
	v_and_b32_e32 v71, 0xffff0000, v83
	v_pk_fma_f32 v[112:113], v[90:91], v[64:65], v[112:113] op_sel_hi:[0,1,1]
	v_pk_fma_f32 v[114:115], v[90:91], v[66:67], v[114:115] op_sel_hi:[0,1,1]
	v_pk_fma_f32 v[116:117], v[90:91], v[68:69], v[116:117] op_sel_hi:[0,1,1]
	v_pk_fma_f32 v[118:119], v[90:91], v[70:71], v[118:119] op_sel_hi:[0,1,1]
	v_lshlrev_b32_e32 v64, 16, v84
	v_and_b32_e32 v65, 0xffff0000, v84
	v_lshlrev_b32_e32 v66, 16, v85
	v_and_b32_e32 v67, 0xffff0000, v85
	v_lshlrev_b32_e32 v68, 16, v86
	v_and_b32_e32 v69, 0xffff0000, v86
	v_lshlrev_b32_e32 v70, 16, v87
	v_and_b32_e32 v71, 0xffff0000, v87
	v_pk_fma_f32 v[120:121], v[90:91], v[64:65], v[120:121] op_sel_hi:[0,1,1]
	v_pk_fma_f32 v[122:123], v[90:91], v[66:67], v[122:123] op_sel_hi:[0,1,1]
	v_pk_fma_f32 v[124:125], v[90:91], v[68:69], v[124:125] op_sel_hi:[0,1,1]
	v_pk_fma_f32 v[126:127], v[90:91], v[70:71], v[126:127] op_sel_hi:[0,1,1]
	v_pk_mul_f32 v[134:135], v[112:113], v[112:113]
	v_pk_fma_f32 v[134:135], v[114:115], v[114:115], v[134:135]
	v_pk_fma_f32 v[134:135], v[116:117], v[116:117], v[134:135]
	v_pk_fma_f32 v[134:135], v[118:119], v[118:119], v[134:135]
	v_pk_fma_f32 v[134:135], v[120:121], v[120:121], v[134:135]
	v_pk_fma_f32 v[134:135], v[122:123], v[122:123], v[134:135]
	v_pk_fma_f32 v[134:135], v[124:125], v[124:125], v[134:135]
	v_pk_fma_f32 v[134:135], v[126:127], v[126:127], v[134:135]
	s_nop 0
	v_add_f32_e32 v134, v134, v135
	s_nop 1
	v_add_f32_dpp v132, v132, v132 quad_perm:[1,0,3,2] row_mask:0xf bank_mask:0xf
	v_add_f32_dpp v134, v134, v134 quad_perm:[1,0,3,2] row_mask:0xf bank_mask:0xf
	s_nop 0
	v_add_f32_dpp v132, v132, v132 quad_perm:[2,3,0,1] row_mask:0xf bank_mask:0xf
	v_add_f32_dpp v134, v134, v134 quad_perm:[2,3,0,1] row_mask:0xf bank_mask:0xf
	s_nop 0
	v_add_f32_dpp v132, v132, v132 row_half_mirror row_mask:0xf bank_mask:0xf
	v_add_f32_dpp v134, v134, v134 row_half_mirror row_mask:0xf bank_mask:0xf
	s_nop 0
	v_add_f32_dpp v132, v132, v132 row_mirror row_mask:0xf bank_mask:0xf
	v_add_f32_dpp v134, v134, v134 row_mirror row_mask:0xf bank_mask:0xf
	s_nop 0
	ds_bpermute_b32 v136, v187, v132
	ds_bpermute_b32 v137, v187, v134
	s_waitcnt lgkmcnt(0)
	v_add_f32_e32 v132, v132, v136
	v_add_f32_e32 v134, v134, v137
	ds_bpermute_b32 v136, v188, v132
	ds_bpermute_b32 v137, v188, v134
	s_waitcnt lgkmcnt(0)
	v_add_f32_e32 v132, v132, v136
	v_add_f32_e32 v134, v134, v137
	v_fmamk_f32 v164, v132, 0x3a800000, v138
	v_fmamk_f32 v167, v134, 0x3a800000, v138
	s_nop 0
	v_rsq_f32_e32 v132, v164
	v_rsq_f32_e32 v134, v167
	v_sqrt_f32_e32 v165, v164
	v_sqrt_f32_e32 v168, v167
	s_nop 1
	v_pk_mul_f32 v[140:141], v[96:97], v[132:133] op_sel_hi:[1,0]
	v_cvt_pk_bf16_f32 v148, v140, v141
	v_pk_mul_f32 v[142:143], v[98:99], v[132:133] op_sel_hi:[1,0]
	v_cvt_pk_bf16_f32 v149, v142, v143
	v_pk_mul_f32 v[144:145], v[100:101], v[132:133] op_sel_hi:[1,0]
	v_cvt_pk_bf16_f32 v150, v144, v145
	v_pk_mul_f32 v[146:147], v[102:103], v[132:133] op_sel_hi:[1,0]
	v_cvt_pk_bf16_f32 v151, v146, v147
	v_pk_mul_f32 v[140:141], v[104:105], v[132:133] op_sel_hi:[1,0]
	v_cvt_pk_bf16_f32 v152, v140, v141
	v_pk_mul_f32 v[142:143], v[106:107], v[132:133] op_sel_hi:[1,0]
	v_cvt_pk_bf16_f32 v153, v142, v143
	v_pk_mul_f32 v[144:145], v[108:109], v[132:133] op_sel_hi:[1,0]
	v_cvt_pk_bf16_f32 v154, v144, v145
	v_pk_mul_f32 v[146:147], v[110:111], v[132:133] op_sel_hi:[1,0]
	v_cvt_pk_bf16_f32 v155, v146, v147
	global_store_dwordx4 v173, v[148:151], s[98:99]
	global_store_dwordx4 v173, v[152:155], s[98:99] offset:1024
	v_add_u32_e32 v173, 0x400000, v173
	v_pk_mul_f32 v[140:141], v[112:113], v[134:135] op_sel_hi:[1,0]
	v_cvt_pk_bf16_f32 v156, v140, v141
	v_pk_mul_f32 v[142:143], v[114:115], v[134:135] op_sel_hi:[1,0]
	v_cvt_pk_bf16_f32 v157, v142, v143
	v_pk_mul_f32 v[144:145], v[116:117], v[134:135] op_sel_hi:[1,0]
	v_cvt_pk_bf16_f32 v158, v144, v145
	v_pk_mul_f32 v[146:147], v[118:119], v[134:135] op_sel_hi:[1,0]
	v_cvt_pk_bf16_f32 v159, v146, v147
	v_pk_mul_f32 v[140:141], v[120:121], v[134:135] op_sel_hi:[1,0]
	v_cvt_pk_bf16_f32 v160, v140, v141
	v_pk_mul_f32 v[142:143], v[122:123], v[134:135] op_sel_hi:[1,0]
	v_cvt_pk_bf16_f32 v161, v142, v143
	v_pk_mul_f32 v[144:145], v[124:125], v[134:135] op_sel_hi:[1,0]
	v_cvt_pk_bf16_f32 v162, v144, v145
	v_pk_mul_f32 v[146:147], v[126:127], v[134:135] op_sel_hi:[1,0]
	v_cvt_pk_bf16_f32 v163, v146, v147
	global_store_dwordx4 v173, v[156:159], s[98:99]
	global_store_dwordx4 v173, v[160:163], s[98:99] offset:1024
	v_add_u32_e32 v173, 0x400000, v173
	v_add_u32_e32 v166, -1, v165
	v_fma_f32 v140, -v166, v165, v164
	v_cmp_ge_f32_e32 vcc, 0, v140
	v_add_u32_e32 v141, 1, v165
	v_cndmask_b32_e32 v166, v165, v166, vcc
	v_fma_f32 v140, -v141, v165, v164
	v_cmp_lt_f32_e32 vcc, 0, v140
	s_nop 1
	v_cndmask_b32_e32 v165, v166, v141, vcc
	v_add_u32_e32 v169, -1, v168
	v_fma_f32 v142, -v169, v168, v167
	v_cmp_ge_f32_e32 vcc, 0, v142
	v_add_u32_e32 v143, 1, v168
	v_cndmask_b32_e32 v169, v168, v169, vcc
	v_fma_f32 v142, -v143, v168, v167
	v_cmp_lt_f32_e32 vcc, 0, v142
	s_nop 1
	v_cndmask_b32_e32 v168, v169, v143, vcc
	s_mov_b64 exec, 1
	global_store_dword v174, v165, s[98:99]
	v_add_u32_e32 v174, 0x2000, v174
	global_store_dword v174, v168, s[98:99]
	v_add_u32_e32 v174, 0x2000, v174
	s_mov_b64 exec, -1
	global_load_dword v88, v172, s[98:99]
	global_load_dwordx4 v[56:59], v170, s[98:99]
	global_load_dwordx4 v[60:63], v170, s[98:99] offset:1024
	global_load_dwordx4 v[72:75], v171, s[98:99]
	global_load_dwordx4 v[76:79], v171, s[98:99] offset:1024
	v_add_u32_e32 v170, 0x400000, v170
	v_add_u32_e32 v171, 0x400000, v171
	v_add_u32_e32 v172, 0x2000, v172
	global_load_dword v90, v172, s[98:99]
	global_load_dwordx4 v[64:67], v170, s[98:99]
	global_load_dwordx4 v[68:71], v170, s[98:99] offset:1024
	global_load_dwordx4 v[80:83], v171, s[98:99]
	global_load_dwordx4 v[84:87], v171, s[98:99] offset:1024
	v_add_u32_e32 v170, 0x400000, v170
	v_add_u32_e32 v171, 0x400000, v171
	v_add_u32_e32 v172, 0x2000, v172
	s_waitcnt vmcnt(39)
; __device__ __forceinline__ const float* xrow_ptr(const Ctx& C, int row) { return row < MPROMPT ? C.in(0) + (size_t)row * DM : C.in(1) + (size_t)(row - MPROMPT) * DM; }
; __device__ __forceinline__ v4f ld4_bf16(const bf16* p) { const v2u w = *(const v2u*)p; return (v4f){bf_lo(w.x), bf_hi(w.x), bf_lo(w.y), bf_hi(w.y)}; }
; __device__ __forceinline__ float ssq4(v4f v) { return (v.x * v.x + v.y * v.y) + (v.z * v.z + v.w * v.w); }
; template <int R, bool BASE_F32, bool OUT_F32>
; __device__ __forceinline__ void rows_res(const Ctx& C, int m0, int stride, int mx, const float* gpost, float scale, int lane) {
;     ...
;     for (int r = 0; r < R; ++r) { mr[r] = (r == 4) ? mx : m0 + r * stride; ok[r] = (r == 4) ? (mx < M) : (mr[r] < MPROMPT); const int mm = ok[r] ? mr[r] : 0;
; #pragma unroll
;         for (int j = 0; j < 4; ++j) d[r][j] = ld4_bf16(D + (size_t)mm * DM + 4 * lane + 256 * j);
;         if (BASE_F32) { const float* x = xrow_ptr(C, mm);
; #pragma unroll
;             for (int j = 0; j < 4; ++j) b[r][j] = ld4_f32(x + 4 * lane + 256 * j);
;         } else { const float inv = C.RS()[mm];
; #pragma unroll
;             for (int j = 0; j < 4; ++j) b[r][j] = ld4_bf16(XN + (size_t)mm * DM + 4 * lane + 256 * j) * inv;
;         } }
; #pragma unroll
;     for (int r = 0; r < R; ++r) { float s = 0.f;
; #pragma unroll
;         for (int j = 0; j < 4; ++j) s += ssq4(d[r][j]);
;         r1[r] = s; }
; #pragma unroll
;     for (int r = 0; r < R; ++r) r1[r] = rsqrtf(wave_sum(r1[r]) * (1.f / DM) + EPS) * scale;
; #pragma unroll
;     for (int j = 0; j < 4; ++j) { const v4f gp = ld4_f32(gpost + 4 * lane + 256 * j);
; #pragma unroll
;         for (int r = 0; r < R; ++r) d[r][j] = b[r][j] + d[r][j] * r1[r] * gp; }
	v_lshlrev_b32_e32 v96, 16, v208
	v_and_b32_e32 v97, 0xffff0000, v208
	v_lshlrev_b32_e32 v98, 16, v209
	v_and_b32_e32 v99, 0xffff0000, v209
	v_lshlrev_b32_e32 v100, 16, v210
	v_and_b32_e32 v101, 0xffff0000, v210
	v_lshlrev_b32_e32 v102, 16, v211
	v_and_b32_e32 v103, 0xffff0000, v211
	v_lshlrev_b32_e32 v104, 16, v212
	v_and_b32_e32 v105, 0xffff0000, v212
	v_lshlrev_b32_e32 v106, 16, v213
	v_and_b32_e32 v107, 0xffff0000, v213
	v_lshlrev_b32_e32 v108, 16, v214
	v_and_b32_e32 v109, 0xffff0000, v214
	v_lshlrev_b32_e32 v110, 16, v215
	v_and_b32_e32 v111, 0xffff0000, v215
	v_pk_mul_f32 v[128:129], v[96:97], v[96:97]
	v_pk_fma_f32 v[128:129], v[98:99], v[98:99], v[128:129]
	v_pk_fma_f32 v[128:129], v[100:101], v[100:101], v[128:129]
	v_pk_fma_f32 v[128:129], v[102:103], v[102:103], v[128:129]
	v_pk_fma_f32 v[128:129], v[104:105], v[104:105], v[128:129]
	v_pk_fma_f32 v[128:129], v[106:107], v[106:107], v[128:129]
	v_pk_fma_f32 v[128:129], v[108:109], v[108:109], v[128:129]
	v_pk_fma_f32 v[128:129], v[110:111], v[110:111], v[128:129]
	s_nop 0
	v_add_f32_e32 v128, v128, v129
	s_waitcnt vmcnt(34)
	v_lshlrev_b32_e32 v112, 16, v216
	v_and_b32_e32 v113, 0xffff0000, v216
	v_lshlrev_b32_e32 v114, 16, v217
	v_and_b32_e32 v115, 0xffff0000, v217
	v_lshlrev_b32_e32 v116, 16, v218
	v_and_b32_e32 v117, 0xffff0000, v218
	v_lshlrev_b32_e32 v118, 16, v219
	v_and_b32_e32 v119, 0xffff0000, v219
	v_lshlrev_b32_e32 v120, 16, v220
	v_and_b32_e32 v121, 0xffff0000, v220
	v_lshlrev_b32_e32 v122, 16, v221
	v_and_b32_e32 v123, 0xffff0000, v221
	v_lshlrev_b32_e32 v124, 16, v222
	v_and_b32_e32 v125, 0xffff0000, v222
	v_lshlrev_b32_e32 v126, 16, v223
	v_and_b32_e32 v127, 0xffff0000, v223
	v_pk_mul_f32 v[130:131], v[112:113], v[112:113]
	v_pk_fma_f32 v[130:131], v[114:115], v[114:115], v[130:131]
	v_pk_fma_f32 v[130:131], v[116:117], v[116:117], v[130:131]
	v_pk_fma_f32 v[130:131], v[118:119], v[118:119], v[130:131]
	v_pk_fma_f32 v[130:131], v[120:121], v[120:121], v[130:131]
	v_pk_fma_f32 v[130:131], v[122:123], v[122:123], v[130:131]
	v_pk_fma_f32 v[130:131], v[124:125], v[124:125], v[130:131]
	v_pk_fma_f32 v[130:131], v[126:127], v[126:127], v[130:131]
	s_nop 0
	v_add_f32_e32 v130, v130, v131
	s_nop 1
	v_add_f32_dpp v128, v128, v128 quad_perm:[1,0,3,2] row_mask:0xf bank_mask:0xf
	v_add_f32_dpp v130, v130, v130 quad_perm:[1,0,3,2] row_mask:0xf bank_mask:0xf
	s_nop 0
	v_add_f32_dpp v128, v128, v128 quad_perm:[2,3,0,1] row_mask:0xf bank_mask:0xf
	v_add_f32_dpp v130, v130, v130 quad_perm:[2,3,0,1] row_mask:0xf bank_mask:0xf
	s_nop 0
	v_add_f32_dpp v128, v128, v128 row_half_mirror row_mask:0xf bank_mask:0xf
	v_add_f32_dpp v130, v130, v130 row_half_mirror row_mask:0xf bank_mask:0xf
	s_nop 0
	v_add_f32_dpp v128, v128, v128 row_mirror row_mask:0xf bank_mask:0xf
	v_add_f32_dpp v130, v130, v130 row_mirror row_mask:0xf bank_mask:0xf
	s_nop 0
	ds_bpermute_b32 v136, v187, v128
	ds_bpermute_b32 v137, v187, v130
	s_waitcnt lgkmcnt(0)
	v_add_f32_e32 v128, v128, v136
	v_add_f32_e32 v130, v130, v137
	ds_bpermute_b32 v136, v188, v128
	ds_bpermute_b32 v137, v188, v130
	s_waitcnt lgkmcnt(0)
	v_add_f32_e32 v128, v128, v136
	v_add_f32_e32 v130, v130, v137
	v_fmamk_f32 v128, v128, 0x3a800000, v138
	v_fmamk_f32 v130, v130, 0x3a800000, v138
	s_nop 0
	v_rsq_f32_e32 v128, v128
	v_rsq_f32_e32 v130, v130
	s_nop 1
	v_mul_f32_e32 v128, 0.5, v128
	v_mul_f32_e32 v130, 0.5, v130
	s_waitcnt vmcnt(32)
	v_pk_mul_f32 v[96:97], v[128:129], v[96:97] op_sel_hi:[0,1]
	v_pk_mul_f32 v[98:99], v[128:129], v[98:99] op_sel_hi:[0,1]
	v_pk_mul_f32 v[100:101], v[128:129], v[100:101] op_sel_hi:[0,1]
	v_pk_mul_f32 v[102:103], v[128:129], v[102:103] op_sel_hi:[0,1]
	v_pk_mul_f32 v[104:105], v[128:129], v[104:105] op_sel_hi:[0,1]
	v_pk_mul_f32 v[106:107], v[128:129], v[106:107] op_sel_hi:[0,1]
	v_pk_mul_f32 v[108:109], v[128:129], v[108:109] op_sel_hi:[0,1]
	v_pk_mul_f32 v[110:111], v[128:129], v[110:111] op_sel_hi:[0,1]
	v_pk_mul_f32 v[96:97], v[96:97], v[192:193]
	v_pk_mul_f32 v[98:99], v[98:99], v[194:195]
	v_pk_mul_f32 v[100:101], v[100:101], v[196:197]
	v_pk_mul_f32 v[102:103], v[102:103], v[198:199]
	v_pk_mul_f32 v[104:105], v[104:105], v[200:201]
	v_pk_mul_f32 v[106:107], v[106:107], v[202:203]
	v_pk_mul_f32 v[108:109], v[108:109], v[204:205]
	v_pk_mul_f32 v[110:111], v[110:111], v[206:207]
	v_lshlrev_b32_e32 v208, 16, v224
	v_and_b32_e32 v209, 0xffff0000, v224
	v_lshlrev_b32_e32 v210, 16, v225
	v_and_b32_e32 v211, 0xffff0000, v225
	v_lshlrev_b32_e32 v212, 16, v226
	v_and_b32_e32 v213, 0xffff0000, v226
	v_lshlrev_b32_e32 v214, 16, v227
	v_and_b32_e32 v215, 0xffff0000, v227
	v_pk_fma_f32 v[96:97], v[12:13], v[208:209], v[96:97] op_sel_hi:[0,1,1]
	v_pk_fma_f32 v[98:99], v[12:13], v[210:211], v[98:99] op_sel_hi:[0,1,1]
	v_pk_fma_f32 v[100:101], v[12:13], v[212:213], v[100:101] op_sel_hi:[0,1,1]
	v_pk_fma_f32 v[102:103], v[12:13], v[214:215], v[102:103] op_sel_hi:[0,1,1]
	v_lshlrev_b32_e32 v208, 16, v228
	v_and_b32_e32 v209, 0xffff0000, v228
	v_lshlrev_b32_e32 v210, 16, v229
	v_and_b32_e32 v211, 0xffff0000, v229
	v_lshlrev_b32_e32 v212, 16, v230
	v_and_b32_e32 v213, 0xffff0000, v230
	v_lshlrev_b32_e32 v214, 16, v231
	v_and_b32_e32 v215, 0xffff0000, v231
	v_pk_fma_f32 v[104:105], v[12:13], v[208:209], v[104:105] op_sel_hi:[0,1,1]
	v_pk_fma_f32 v[106:107], v[12:13], v[210:211], v[106:107] op_sel_hi:[0,1,1]
	v_pk_fma_f32 v[108:109], v[12:13], v[212:213], v[108:109] op_sel_hi:[0,1,1]
	v_pk_fma_f32 v[110:111], v[12:13], v[214:215], v[110:111] op_sel_hi:[0,1,1]
	v_pk_mul_f32 v[132:133], v[96:97], v[96:97]
	v_pk_fma_f32 v[132:133], v[98:99], v[98:99], v[132:133]
	v_pk_fma_f32 v[132:133], v[100:101], v[100:101], v[132:133]
;     __device__ __forceinline__ float* out() const { return (float*)karg_in(33); }
; __device__ __forceinline__ void st4_bf16(bf16* p, v4f o) { v2u w; w.x = cvt_pk_nv(o.x, o.y); w.y = cvt_pk_nv(o.z, o.w); *(v2u*)p = w; }
; __device__ __forceinline__ float ssq4(v4f v) { return (v.x * v.x + v.y * v.y) + (v.z * v.z + v.w * v.w); }
; template <int R, bool BASE_F32, bool OUT_F32>
; __device__ __forceinline__ void rows_res(const Ctx& C, int m0, int stride, int mx, const float* gpost, float scale, int lane) {
;     ...
;     for (int r = 0; r < R; ++r) r1[r] = rsqrtf(wave_sum(r1[r]) * (1.f / DM) + EPS) * scale;
; #pragma unroll
;     for (int j = 0; j < 4; ++j) { const v4f gp = ld4_f32(gpost + 4 * lane + 256 * j);
; #pragma unroll
;         for (int r = 0; r < R; ++r) d[r][j] = b[r][j] + d[r][j] * r1[r] * gp; }
;     if (OUT_F32) { float* Y = C.out();
; #pragma unroll
;         for (int r = 0; r < R; ++r)
; #pragma unroll
;             for (int j = 0; j < 4; ++j) if (ok[r]) *(v4f*)(Y + (size_t)mr[r] * DM + 4 * lane + 256 * j) = d[r][j];
;     } else { float* rs = C.RS(); float t[R];
; #pragma unroll
;         for (int r = 0; r < R; ++r) { float s = 0.f;
; #pragma unroll
;             for (int j = 0; j < 4; ++j) s += ssq4(d[r][j]);
;             t[r] = s; }
; #pragma unroll
;         for (int r = 0; r < R; ++r) t[r] = wave_sum(t[r]) * (1.f / DM) + EPS;
; #pragma unroll
;         for (int r = 0; r < R; ++r) { const float rstd = rsqrtf(t[r]);
; #pragma unroll
;             for (int j = 0; j < 4; ++j) if (ok[r]) st4_bf16(XN + (size_t)mr[r] * DM + 4 * lane + 256 * j, d[r][j] * rstd);
	v_pk_fma_f32 v[132:133], v[102:103], v[102:103], v[132:133]
	v_pk_fma_f32 v[132:133], v[104:105], v[104:105], v[132:133]
	v_pk_fma_f32 v[132:133], v[106:107], v[106:107], v[132:133]
	v_pk_fma_f32 v[132:133], v[108:109], v[108:109], v[132:133]
	v_pk_fma_f32 v[132:133], v[110:111], v[110:111], v[132:133]
	s_nop 0
	v_add_f32_e32 v132, v132, v133
	v_pk_mul_f32 v[112:113], v[130:131], v[112:113] op_sel_hi:[0,1]
	v_pk_mul_f32 v[114:115], v[130:131], v[114:115] op_sel_hi:[0,1]
	v_pk_mul_f32 v[116:117], v[130:131], v[116:117] op_sel_hi:[0,1]
	v_pk_mul_f32 v[118:119], v[130:131], v[118:119] op_sel_hi:[0,1]
	v_pk_mul_f32 v[120:121], v[130:131], v[120:121] op_sel_hi:[0,1]
	v_pk_mul_f32 v[122:123], v[130:131], v[122:123] op_sel_hi:[0,1]
	v_pk_mul_f32 v[124:125], v[130:131], v[124:125] op_sel_hi:[0,1]
	v_pk_mul_f32 v[126:127], v[130:131], v[126:127] op_sel_hi:[0,1]
	v_pk_mul_f32 v[112:113], v[112:113], v[192:193]
	v_pk_mul_f32 v[114:115], v[114:115], v[194:195]
	v_pk_mul_f32 v[116:117], v[116:117], v[196:197]
	v_pk_mul_f32 v[118:119], v[118:119], v[198:199]
	v_pk_mul_f32 v[120:121], v[120:121], v[200:201]
	v_pk_mul_f32 v[122:123], v[122:123], v[202:203]
	v_pk_mul_f32 v[124:125], v[124:125], v[204:205]
	v_pk_mul_f32 v[126:127], v[126:127], v[206:207]
	v_lshlrev_b32_e32 v216, 16, v4
	v_and_b32_e32 v217, 0xffff0000, v4
	v_lshlrev_b32_e32 v218, 16, v5
	v_and_b32_e32 v219, 0xffff0000, v5
	v_lshlrev_b32_e32 v220, 16, v6
	v_and_b32_e32 v221, 0xffff0000, v6
	v_lshlrev_b32_e32 v222, 16, v7
	v_and_b32_e32 v223, 0xffff0000, v7
	v_pk_fma_f32 v[112:113], v[14:15], v[216:217], v[112:113] op_sel_hi:[0,1,1]
	v_pk_fma_f32 v[114:115], v[14:15], v[218:219], v[114:115] op_sel_hi:[0,1,1]
	v_pk_fma_f32 v[116:117], v[14:15], v[220:221], v[116:117] op_sel_hi:[0,1,1]
	v_pk_fma_f32 v[118:119], v[14:15], v[222:223], v[118:119] op_sel_hi:[0,1,1]
	v_lshlrev_b32_e32 v216, 16, v8
	v_and_b32_e32 v217, 0xffff0000, v8
	v_lshlrev_b32_e32 v218, 16, v9
	v_and_b32_e32 v219, 0xffff0000, v9
	v_lshlrev_b32_e32 v220, 16, v10
	v_and_b32_e32 v221, 0xffff0000, v10
	v_lshlrev_b32_e32 v222, 16, v11
	v_and_b32_e32 v223, 0xffff0000, v11
	v_pk_fma_f32 v[120:121], v[14:15], v[216:217], v[120:121] op_sel_hi:[0,1,1]
	v_pk_fma_f32 v[122:123], v[14:15], v[218:219], v[122:123] op_sel_hi:[0,1,1]
	v_pk_fma_f32 v[124:125], v[14:15], v[220:221], v[124:125] op_sel_hi:[0,1,1]
	v_pk_fma_f32 v[126:127], v[14:15], v[222:223], v[126:127] op_sel_hi:[0,1,1]
	v_pk_mul_f32 v[134:135], v[112:113], v[112:113]
	v_pk_fma_f32 v[134:135], v[114:115], v[114:115], v[134:135]
	v_pk_fma_f32 v[134:135], v[116:117], v[116:117], v[134:135]
	v_pk_fma_f32 v[134:135], v[118:119], v[118:119], v[134:135]
	v_pk_fma_f32 v[134:135], v[120:121], v[120:121], v[134:135]
	v_pk_fma_f32 v[134:135], v[122:123], v[122:123], v[134:135]
	v_pk_fma_f32 v[134:135], v[124:125], v[124:125], v[134:135]
	v_pk_fma_f32 v[134:135], v[126:127], v[126:127], v[134:135]
	s_nop 0
	v_add_f32_e32 v134, v134, v135
	s_nop 1
	v_add_f32_dpp v132, v132, v132 quad_perm:[1,0,3,2] row_mask:0xf bank_mask:0xf
	v_add_f32_dpp v134, v134, v134 quad_perm:[1,0,3,2] row_mask:0xf bank_mask:0xf
	s_nop 0
	v_add_f32_dpp v132, v132, v132 quad_perm:[2,3,0,1] row_mask:0xf bank_mask:0xf
	v_add_f32_dpp v134, v134, v134 quad_perm:[2,3,0,1] row_mask:0xf bank_mask:0xf
	s_nop 0
	v_add_f32_dpp v132, v132, v132 row_half_mirror row_mask:0xf bank_mask:0xf
	v_add_f32_dpp v134, v134, v134 row_half_mirror row_mask:0xf bank_mask:0xf
	s_nop 0
	v_add_f32_dpp v132, v132, v132 row_mirror row_mask:0xf bank_mask:0xf
	v_add_f32_dpp v134, v134, v134 row_mirror row_mask:0xf bank_mask:0xf
	s_nop 0
	ds_bpermute_b32 v136, v187, v132
	ds_bpermute_b32 v137, v187, v134
	s_waitcnt lgkmcnt(0)
	v_add_f32_e32 v132, v132, v136
	v_add_f32_e32 v134, v134, v137
	ds_bpermute_b32 v136, v188, v132
	ds_bpermute_b32 v137, v188, v134
	s_waitcnt lgkmcnt(0)
	v_add_f32_e32 v132, v132, v136
	v_add_f32_e32 v134, v134, v137
	v_fmamk_f32 v164, v132, 0x3a800000, v138
	v_fmamk_f32 v167, v134, 0x3a800000, v138
	s_nop 0
	v_rsq_f32_e32 v132, v164
	v_rsq_f32_e32 v134, v167
	v_sqrt_f32_e32 v165, v164
	v_sqrt_f32_e32 v168, v167
	s_nop 1
	v_pk_mul_f32 v[140:141], v[96:97], v[132:133] op_sel_hi:[1,0]
	v_cvt_pk_bf16_f32 v148, v140, v141
	v_pk_mul_f32 v[142:143], v[98:99], v[132:133] op_sel_hi:[1,0]
	v_cvt_pk_bf16_f32 v149, v142, v143
	v_pk_mul_f32 v[144:145], v[100:101], v[132:133] op_sel_hi:[1,0]
	v_cvt_pk_bf16_f32 v150, v144, v145
	v_pk_mul_f32 v[146:147], v[102:103], v[132:133] op_sel_hi:[1,0]
	v_cvt_pk_bf16_f32 v151, v146, v147
	v_pk_mul_f32 v[140:141], v[104:105], v[132:133] op_sel_hi:[1,0]
	v_cvt_pk_bf16_f32 v152, v140, v141
	v_pk_mul_f32 v[142:143], v[106:107], v[132:133] op_sel_hi:[1,0]
	v_cvt_pk_bf16_f32 v153, v142, v143
	v_pk_mul_f32 v[144:145], v[108:109], v[132:133] op_sel_hi:[1,0]
	v_cvt_pk_bf16_f32 v154, v144, v145
	v_pk_mul_f32 v[146:147], v[110:111], v[132:133] op_sel_hi:[1,0]
	v_cvt_pk_bf16_f32 v155, v146, v147
	global_store_dwordx4 v173, v[148:151], s[98:99]
	global_store_dwordx4 v173, v[152:155], s[98:99] offset:1024
	v_add_u32_e32 v173, 0x400000, v173
	v_pk_mul_f32 v[140:141], v[112:113], v[134:135] op_sel_hi:[1,0]
	v_cvt_pk_bf16_f32 v156, v140, v141
	v_pk_mul_f32 v[142:143], v[114:115], v[134:135] op_sel_hi:[1,0]
	v_cvt_pk_bf16_f32 v157, v142, v143
	v_pk_mul_f32 v[144:145], v[116:117], v[134:135] op_sel_hi:[1,0]
	v_cvt_pk_bf16_f32 v158, v144, v145
	v_pk_mul_f32 v[146:147], v[118:119], v[134:135] op_sel_hi:[1,0]
	v_cvt_pk_bf16_f32 v159, v146, v147
	v_pk_mul_f32 v[140:141], v[120:121], v[134:135] op_sel_hi:[1,0]
	v_cvt_pk_bf16_f32 v160, v140, v141
	v_pk_mul_f32 v[142:143], v[122:123], v[134:135] op_sel_hi:[1,0]
; __device__ __forceinline__ const float* xrow_ptr(const Ctx& C, int row) { return row < MPROMPT ? C.in(0) + (size_t)row * DM : C.in(1) + (size_t)(row - MPROMPT) * DM; }
; __device__ __forceinline__ v4f ld4_bf16(const bf16* p) { const v2u w = *(const v2u*)p; return (v4f){bf_lo(w.x), bf_hi(w.x), bf_lo(w.y), bf_hi(w.y)}; }
; __device__ __forceinline__ void st4_bf16(bf16* p, v4f o) { v2u w; w.x = cvt_pk_nv(o.x, o.y); w.y = cvt_pk_nv(o.z, o.w); *(v2u*)p = w; }
; __device__ __forceinline__ float ssq4(v4f v) { return (v.x * v.x + v.y * v.y) + (v.z * v.z + v.w * v.w); }
; template <int R, bool BASE_F32, bool OUT_F32>
; __device__ __forceinline__ void rows_res(const Ctx& C, int m0, int stride, int mx, const float* gpost, float scale, int lane) {
;     ...
;     for (int r = 0; r < R; ++r) { mr[r] = (r == 4) ? mx : m0 + r * stride; ok[r] = (r == 4) ? (mx < M) : (mr[r] < MPROMPT); const int mm = ok[r] ? mr[r] : 0;
; #pragma unroll
;         for (int j = 0; j < 4; ++j) d[r][j] = ld4_bf16(D + (size_t)mm * DM + 4 * lane + 256 * j);
;         if (BASE_F32) { const float* x = xrow_ptr(C, mm);
; #pragma unroll
;             for (int j = 0; j < 4; ++j) b[r][j] = ld4_f32(x + 4 * lane + 256 * j);
;         } else { const float inv = C.RS()[mm];
; #pragma unroll
;             for (int j = 0; j < 4; ++j) b[r][j] = ld4_bf16(XN + (size_t)mm * DM + 4 * lane + 256 * j) * inv;
;         } }
; #pragma unroll
;     for (int r = 0; r < R; ++r) { float s = 0.f;
; #pragma unroll
;         for (int j = 0; j < 4; ++j) s += ssq4(d[r][j]);
;         r1[r] = s; }
;     ...
;         for (int r = 0; r < R; ++r) t[r] = wave_sum(t[r]) * (1.f / DM) + EPS;
; #pragma unroll
;         for (int r = 0; r < R; ++r) { const float rstd = rsqrtf(t[r]);
; #pragma unroll
;             for (int j = 0; j < 4; ++j) if (ok[r]) st4_bf16(XN + (size_t)mr[r] * DM + 4 * lane + 256 * j, d[r][j] * rstd);
;             if (lane == 0 && ok[r]) rs[mr[r]] = sqrtf(t[r]); }
	v_cvt_pk_bf16_f32 v161, v142, v143
	v_pk_mul_f32 v[144:145], v[124:125], v[134:135] op_sel_hi:[1,0]
	v_cvt_pk_bf16_f32 v162, v144, v145
	v_pk_mul_f32 v[146:147], v[126:127], v[134:135] op_sel_hi:[1,0]
	v_cvt_pk_bf16_f32 v163, v146, v147
	global_store_dwordx4 v173, v[156:159], s[98:99]
	global_store_dwordx4 v173, v[160:163], s[98:99] offset:1024
	v_add_u32_e32 v173, 0x400000, v173
	v_add_u32_e32 v166, -1, v165
	v_fma_f32 v140, -v166, v165, v164
	v_cmp_ge_f32_e32 vcc, 0, v140
	v_add_u32_e32 v141, 1, v165
	v_cndmask_b32_e32 v166, v165, v166, vcc
	v_fma_f32 v140, -v141, v165, v164
	v_cmp_lt_f32_e32 vcc, 0, v140
	s_nop 1
	v_cndmask_b32_e32 v165, v166, v141, vcc
	v_add_u32_e32 v169, -1, v168
	v_fma_f32 v142, -v169, v168, v167
	v_cmp_ge_f32_e32 vcc, 0, v142
	v_add_u32_e32 v143, 1, v168
	v_cndmask_b32_e32 v169, v168, v169, vcc
	v_fma_f32 v142, -v143, v168, v167
	v_cmp_lt_f32_e32 vcc, 0, v142
	s_nop 1
	v_cndmask_b32_e32 v168, v169, v143, vcc
	s_mov_b64 exec, 1
	global_store_dword v174, v165, s[98:99]
	v_add_u32_e32 v174, 0x2000, v174
	global_store_dword v174, v168, s[98:99]
	v_add_u32_e32 v174, 0x2000, v174
	s_mov_b64 exec, -1
	global_load_dword v12, v172, s[98:99]
	global_load_dwordx4 v[208:211], v170, s[98:99]
	global_load_dwordx4 v[212:215], v170, s[98:99] offset:1024
	global_load_dwordx4 v[224:227], v171, s[98:99]
	global_load_dwordx4 v[228:231], v171, s[98:99] offset:1024
	v_add_u32_e32 v170, 0x400000, v170
	v_add_u32_e32 v171, 0x400000, v171
	v_add_u32_e32 v172, 0x2000, v172
	global_load_dword v14, v172, s[98:99]
	global_load_dwordx4 v[216:219], v170, s[98:99]
	global_load_dwordx4 v[220:223], v170, s[98:99] offset:1024
	global_load_dwordx4 v[4:7], v171, s[98:99]
	global_load_dwordx4 v[8:11], v171, s[98:99] offset:1024
	v_add_u32_e32 v170, 0x400000, v170
	v_add_u32_e32 v171, 0x400000, v171
	v_add_u32_e32 v172, 0x2000, v172
	s_waitcnt vmcnt(39)
	v_lshlrev_b32_e32 v96, 16, v20
	v_and_b32_e32 v97, 0xffff0000, v20
	v_lshlrev_b32_e32 v98, 16, v21
	v_and_b32_e32 v99, 0xffff0000, v21
	v_lshlrev_b32_e32 v100, 16, v22
	v_and_b32_e32 v101, 0xffff0000, v22
	v_lshlrev_b32_e32 v102, 16, v23
	v_and_b32_e32 v103, 0xffff0000, v23
	v_lshlrev_b32_e32 v104, 16, v24
	v_and_b32_e32 v105, 0xffff0000, v24
	v_lshlrev_b32_e32 v106, 16, v25
	v_and_b32_e32 v107, 0xffff0000, v25
	v_lshlrev_b32_e32 v108, 16, v26
	v_and_b32_e32 v109, 0xffff0000, v26
	v_lshlrev_b32_e32 v110, 16, v27
	v_and_b32_e32 v111, 0xffff0000, v27
	v_pk_mul_f32 v[128:129], v[96:97], v[96:97]
	v_pk_fma_f32 v[128:129], v[98:99], v[98:99], v[128:129]
	v_pk_fma_f32 v[128:129], v[100:101], v[100:101], v[128:129]
	v_pk_fma_f32 v[128:129], v[102:103], v[102:103], v[128:129]
	v_pk_fma_f32 v[128:129], v[104:105], v[104:105], v[128:129]
	v_pk_fma_f32 v[128:129], v[106:107], v[106:107], v[128:129]
	v_pk_fma_f32 v[128:129], v[108:109], v[108:109], v[128:129]
	v_pk_fma_f32 v[128:129], v[110:111], v[110:111], v[128:129]
	s_nop 0
	v_add_f32_e32 v128, v128, v129
	s_waitcnt vmcnt(34)
	v_lshlrev_b32_e32 v112, 16, v28
	v_and_b32_e32 v113, 0xffff0000, v28
	v_lshlrev_b32_e32 v114, 16, v29
	v_and_b32_e32 v115, 0xffff0000, v29
	v_lshlrev_b32_e32 v116, 16, v30
	v_and_b32_e32 v117, 0xffff0000, v30
	v_lshlrev_b32_e32 v118, 16, v31
	v_and_b32_e32 v119, 0xffff0000, v31
	v_lshlrev_b32_e32 v120, 16, v32
	v_and_b32_e32 v121, 0xffff0000, v32
	v_lshlrev_b32_e32 v122, 16, v33
	v_and_b32_e32 v123, 0xffff0000, v33
	v_lshlrev_b32_e32 v124, 16, v34
	v_and_b32_e32 v125, 0xffff0000, v34
	v_lshlrev_b32_e32 v126, 16, v35
	v_and_b32_e32 v127, 0xffff0000, v35
	v_pk_mul_f32 v[130:131], v[112:113], v[112:113]
	v_pk_fma_f32 v[130:131], v[114:115], v[114:115], v[130:131]
	v_pk_fma_f32 v[130:131], v[116:117], v[116:117], v[130:131]
	v_pk_fma_f32 v[130:131], v[118:119], v[118:119], v[130:131]
	v_pk_fma_f32 v[130:131], v[120:121], v[120:121], v[130:131]
	v_pk_fma_f32 v[130:131], v[122:123], v[122:123], v[130:131]
	v_pk_fma_f32 v[130:131], v[124:125], v[124:125], v[130:131]
	v_pk_fma_f32 v[130:131], v[126:127], v[126:127], v[130:131]
	s_nop 0
	v_add_f32_e32 v130, v130, v131
	s_nop 1
	v_add_f32_dpp v128, v128, v128 quad_perm:[1,0,3,2] row_mask:0xf bank_mask:0xf
	v_add_f32_dpp v130, v130, v130 quad_perm:[1,0,3,2] row_mask:0xf bank_mask:0xf
	s_nop 0
	v_add_f32_dpp v128, v128, v128 quad_perm:[2,3,0,1] row_mask:0xf bank_mask:0xf
	v_add_f32_dpp v130, v130, v130 quad_perm:[2,3,0,1] row_mask:0xf bank_mask:0xf
	s_nop 0
	v_add_f32_dpp v128, v128, v128 row_half_mirror row_mask:0xf bank_mask:0xf
	v_add_f32_dpp v130, v130, v130 row_half_mirror row_mask:0xf bank_mask:0xf
	s_nop 0
	v_add_f32_dpp v128, v128, v128 row_mirror row_mask:0xf bank_mask:0xf
	v_add_f32_dpp v130, v130, v130 row_mirror row_mask:0xf bank_mask:0xf
	s_nop 0
	ds_bpermute_b32 v136, v187, v128
	ds_bpermute_b32 v137, v187, v130
	s_waitcnt lgkmcnt(0)
	v_add_f32_e32 v128, v128, v136
	v_add_f32_e32 v130, v130, v137
	ds_bpermute_b32 v136, v188, v128
	ds_bpermute_b32 v137, v188, v130
	s_waitcnt lgkmcnt(0)
	v_add_f32_e32 v128, v128, v136
	v_add_f32_e32 v130, v130, v137
	v_fmamk_f32 v128, v128, 0x3a800000, v138
	v_fmamk_f32 v130, v130, 0x3a800000, v138
	s_nop 0
	v_rsq_f32_e32 v128, v128
	v_rsq_f32_e32 v130, v130
	s_nop 1
	v_mul_f32_e32 v128, 0.5, v128
	v_mul_f32_e32 v130, 0.5, v130
	s_waitcnt vmcnt(32)
;     __device__ __forceinline__ float* out() const { return (float*)karg_in(33); }
; __device__ __forceinline__ float ssq4(v4f v) { return (v.x * v.x + v.y * v.y) + (v.z * v.z + v.w * v.w); }
; template <int R, bool BASE_F32, bool OUT_F32>
; __device__ __forceinline__ void rows_res(const Ctx& C, int m0, int stride, int mx, const float* gpost, float scale, int lane) {
;     ...
;     for (int r = 0; r < R; ++r) r1[r] = rsqrtf(wave_sum(r1[r]) * (1.f / DM) + EPS) * scale;
; #pragma unroll
;     for (int j = 0; j < 4; ++j) { const v4f gp = ld4_f32(gpost + 4 * lane + 256 * j);
; #pragma unroll
;         for (int r = 0; r < R; ++r) d[r][j] = b[r][j] + d[r][j] * r1[r] * gp; }
;     if (OUT_F32) { float* Y = C.out();
; #pragma unroll
;         for (int r = 0; r < R; ++r)
; #pragma unroll
;             for (int j = 0; j < 4; ++j) if (ok[r]) *(v4f*)(Y + (size_t)mr[r] * DM + 4 * lane + 256 * j) = d[r][j];
;     } else { float* rs = C.RS(); float t[R];
; #pragma unroll
;         for (int r = 0; r < R; ++r) { float s = 0.f;
; #pragma unroll
;             for (int j = 0; j < 4; ++j) s += ssq4(d[r][j]);
;             t[r] = s; }
	v_pk_mul_f32 v[96:97], v[128:129], v[96:97] op_sel_hi:[0,1]
	v_pk_mul_f32 v[98:99], v[128:129], v[98:99] op_sel_hi:[0,1]
	v_pk_mul_f32 v[100:101], v[128:129], v[100:101] op_sel_hi:[0,1]
	v_pk_mul_f32 v[102:103], v[128:129], v[102:103] op_sel_hi:[0,1]
	v_pk_mul_f32 v[104:105], v[128:129], v[104:105] op_sel_hi:[0,1]
	v_pk_mul_f32 v[106:107], v[128:129], v[106:107] op_sel_hi:[0,1]
	v_pk_mul_f32 v[108:109], v[128:129], v[108:109] op_sel_hi:[0,1]
	v_pk_mul_f32 v[110:111], v[128:129], v[110:111] op_sel_hi:[0,1]
	v_pk_mul_f32 v[96:97], v[96:97], v[192:193]
	v_pk_mul_f32 v[98:99], v[98:99], v[194:195]
	v_pk_mul_f32 v[100:101], v[100:101], v[196:197]
	v_pk_mul_f32 v[102:103], v[102:103], v[198:199]
	v_pk_mul_f32 v[104:105], v[104:105], v[200:201]
	v_pk_mul_f32 v[106:107], v[106:107], v[202:203]
	v_pk_mul_f32 v[108:109], v[108:109], v[204:205]
	v_pk_mul_f32 v[110:111], v[110:111], v[206:207]
	v_lshlrev_b32_e32 v20, 16, v36
	v_and_b32_e32 v21, 0xffff0000, v36
	v_lshlrev_b32_e32 v22, 16, v37
	v_and_b32_e32 v23, 0xffff0000, v37
	v_lshlrev_b32_e32 v24, 16, v38
	v_and_b32_e32 v25, 0xffff0000, v38
	v_lshlrev_b32_e32 v26, 16, v39
	v_and_b32_e32 v27, 0xffff0000, v39
	v_pk_fma_f32 v[96:97], v[52:53], v[20:21], v[96:97] op_sel_hi:[0,1,1]
	v_pk_fma_f32 v[98:99], v[52:53], v[22:23], v[98:99] op_sel_hi:[0,1,1]
	v_pk_fma_f32 v[100:101], v[52:53], v[24:25], v[100:101] op_sel_hi:[0,1,1]
	v_pk_fma_f32 v[102:103], v[52:53], v[26:27], v[102:103] op_sel_hi:[0,1,1]
	v_lshlrev_b32_e32 v20, 16, v40
	v_and_b32_e32 v21, 0xffff0000, v40
	v_lshlrev_b32_e32 v22, 16, v41
	v_and_b32_e32 v23, 0xffff0000, v41
	v_lshlrev_b32_e32 v24, 16, v42
	v_and_b32_e32 v25, 0xffff0000, v42
	v_lshlrev_b32_e32 v26, 16, v43
	v_and_b32_e32 v27, 0xffff0000, v43
	v_pk_fma_f32 v[104:105], v[52:53], v[20:21], v[104:105] op_sel_hi:[0,1,1]
	v_pk_fma_f32 v[106:107], v[52:53], v[22:23], v[106:107] op_sel_hi:[0,1,1]
	v_pk_fma_f32 v[108:109], v[52:53], v[24:25], v[108:109] op_sel_hi:[0,1,1]
	v_pk_fma_f32 v[110:111], v[52:53], v[26:27], v[110:111] op_sel_hi:[0,1,1]
	v_pk_mul_f32 v[132:133], v[96:97], v[96:97]
	v_pk_fma_f32 v[132:133], v[98:99], v[98:99], v[132:133]
	v_pk_fma_f32 v[132:133], v[100:101], v[100:101], v[132:133]
	v_pk_fma_f32 v[132:133], v[102:103], v[102:103], v[132:133]
	v_pk_fma_f32 v[132:133], v[104:105], v[104:105], v[132:133]
	v_pk_fma_f32 v[132:133], v[106:107], v[106:107], v[132:133]
	v_pk_fma_f32 v[132:133], v[108:109], v[108:109], v[132:133]
	v_pk_fma_f32 v[132:133], v[110:111], v[110:111], v[132:133]
	s_nop 0
	v_add_f32_e32 v132, v132, v133
	v_pk_mul_f32 v[112:113], v[130:131], v[112:113] op_sel_hi:[0,1]
	v_pk_mul_f32 v[114:115], v[130:131], v[114:115] op_sel_hi:[0,1]
	v_pk_mul_f32 v[116:117], v[130:131], v[116:117] op_sel_hi:[0,1]
	v_pk_mul_f32 v[118:119], v[130:131], v[118:119] op_sel_hi:[0,1]
	v_pk_mul_f32 v[120:121], v[130:131], v[120:121] op_sel_hi:[0,1]
	v_pk_mul_f32 v[122:123], v[130:131], v[122:123] op_sel_hi:[0,1]
	v_pk_mul_f32 v[124:125], v[130:131], v[124:125] op_sel_hi:[0,1]
	v_pk_mul_f32 v[126:127], v[130:131], v[126:127] op_sel_hi:[0,1]
	v_pk_mul_f32 v[112:113], v[112:113], v[192:193]
	v_pk_mul_f32 v[114:115], v[114:115], v[194:195]
	v_pk_mul_f32 v[116:117], v[116:117], v[196:197]
	v_pk_mul_f32 v[118:119], v[118:119], v[198:199]
	v_pk_mul_f32 v[120:121], v[120:121], v[200:201]
	v_pk_mul_f32 v[122:123], v[122:123], v[202:203]
	v_pk_mul_f32 v[124:125], v[124:125], v[204:205]
	v_pk_mul_f32 v[126:127], v[126:127], v[206:207]
	v_lshlrev_b32_e32 v28, 16, v44
	v_and_b32_e32 v29, 0xffff0000, v44
	v_lshlrev_b32_e32 v30, 16, v45
	v_and_b32_e32 v31, 0xffff0000, v45
	v_lshlrev_b32_e32 v32, 16, v46
	v_and_b32_e32 v33, 0xffff0000, v46
	v_lshlrev_b32_e32 v34, 16, v47
	v_and_b32_e32 v35, 0xffff0000, v47
	v_pk_fma_f32 v[112:113], v[54:55], v[28:29], v[112:113] op_sel_hi:[0,1,1]
	v_pk_fma_f32 v[114:115], v[54:55], v[30:31], v[114:115] op_sel_hi:[0,1,1]
	v_pk_fma_f32 v[116:117], v[54:55], v[32:33], v[116:117] op_sel_hi:[0,1,1]
	v_pk_fma_f32 v[118:119], v[54:55], v[34:35], v[118:119] op_sel_hi:[0,1,1]
	v_lshlrev_b32_e32 v28, 16, v48
	v_and_b32_e32 v29, 0xffff0000, v48
	v_lshlrev_b32_e32 v30, 16, v49
	v_and_b32_e32 v31, 0xffff0000, v49
	v_lshlrev_b32_e32 v32, 16, v50
	v_and_b32_e32 v33, 0xffff0000, v50
	v_lshlrev_b32_e32 v34, 16, v51
	v_and_b32_e32 v35, 0xffff0000, v51
	v_pk_fma_f32 v[120:121], v[54:55], v[28:29], v[120:121] op_sel_hi:[0,1,1]
	v_pk_fma_f32 v[122:123], v[54:55], v[30:31], v[122:123] op_sel_hi:[0,1,1]
	v_pk_fma_f32 v[124:125], v[54:55], v[32:33], v[124:125] op_sel_hi:[0,1,1]
	v_pk_fma_f32 v[126:127], v[54:55], v[34:35], v[126:127] op_sel_hi:[0,1,1]
	v_pk_mul_f32 v[134:135], v[112:113], v[112:113]
	v_pk_fma_f32 v[134:135], v[114:115], v[114:115], v[134:135]
	v_pk_fma_f32 v[134:135], v[116:117], v[116:117], v[134:135]
	v_pk_fma_f32 v[134:135], v[118:119], v[118:119], v[134:135]
	v_pk_fma_f32 v[134:135], v[120:121], v[120:121], v[134:135]
	v_pk_fma_f32 v[134:135], v[122:123], v[122:123], v[134:135]
	v_pk_fma_f32 v[134:135], v[124:125], v[124:125], v[134:135]
	v_pk_fma_f32 v[134:135], v[126:127], v[126:127], v[134:135]
	s_nop 0
	v_add_f32_e32 v134, v134, v135
	s_nop 1
	v_add_f32_dpp v132, v132, v132 quad_perm:[1,0,3,2] row_mask:0xf bank_mask:0xf
	v_add_f32_dpp v134, v134, v134 quad_perm:[1,0,3,2] row_mask:0xf bank_mask:0xf
	s_nop 0
	v_add_f32_dpp v132, v132, v132 quad_perm:[2,3,0,1] row_mask:0xf bank_mask:0xf
	v_add_f32_dpp v134, v134, v134 quad_perm:[2,3,0,1] row_mask:0xf bank_mask:0xf
	s_nop 0
	v_add_f32_dpp v132, v132, v132 row_half_mirror row_mask:0xf bank_mask:0xf
	v_add_f32_dpp v134, v134, v134 row_half_mirror row_mask:0xf bank_mask:0xf
	s_nop 0
	v_add_f32_dpp v132, v132, v132 row_mirror row_mask:0xf bank_mask:0xf
	v_add_f32_dpp v134, v134, v134 row_mirror row_mask:0xf bank_mask:0xf
	s_nop 0
	ds_bpermute_b32 v136, v187, v132
	ds_bpermute_b32 v137, v187, v134
	s_waitcnt lgkmcnt(0)
; __device__ __forceinline__ void st4_bf16(bf16* p, v4f o) { v2u w; w.x = cvt_pk_nv(o.x, o.y); w.y = cvt_pk_nv(o.z, o.w); *(v2u*)p = w; }
; __device__ __forceinline__ float ssq4(v4f v) { return (v.x * v.x + v.y * v.y) + (v.z * v.z + v.w * v.w); }
; template <int R, bool BASE_F32, bool OUT_F32>
; __device__ __forceinline__ void rows_res(const Ctx& C, int m0, int stride, int mx, const float* gpost, float scale, int lane) {
;     ...
; #pragma unroll
;     for (int r = 0; r < R; ++r) { float s = 0.f;
; #pragma unroll
;         for (int j = 0; j < 4; ++j) s += ssq4(d[r][j]);
;         r1[r] = s; }
; #pragma unroll
;     for (int r = 0; r < R; ++r) r1[r] = rsqrtf(wave_sum(r1[r]) * (1.f / DM) + EPS) * scale;
;     ...
;     } else { float* rs = C.RS(); float t[R];
; #pragma unroll
;         for (int r = 0; r < R; ++r) { float s = 0.f;
; #pragma unroll
;             for (int j = 0; j < 4; ++j) s += ssq4(d[r][j]);
;             t[r] = s; }
; #pragma unroll
;         for (int r = 0; r < R; ++r) t[r] = wave_sum(t[r]) * (1.f / DM) + EPS;
; #pragma unroll
;         for (int r = 0; r < R; ++r) { const float rstd = rsqrtf(t[r]);
; #pragma unroll
;             for (int j = 0; j < 4; ++j) if (ok[r]) st4_bf16(XN + (size_t)mr[r] * DM + 4 * lane + 256 * j, d[r][j] * rstd);
;             if (lane == 0 && ok[r]) rs[mr[r]] = sqrtf(t[r]); }
	v_add_f32_e32 v132, v132, v136
	v_add_f32_e32 v134, v134, v137
	ds_bpermute_b32 v136, v188, v132
	ds_bpermute_b32 v137, v188, v134
	s_waitcnt lgkmcnt(0)
	v_add_f32_e32 v132, v132, v136
	v_add_f32_e32 v134, v134, v137
	v_fmamk_f32 v164, v132, 0x3a800000, v138
	v_fmamk_f32 v167, v134, 0x3a800000, v138
	s_nop 0
	v_rsq_f32_e32 v132, v164
	v_rsq_f32_e32 v134, v167
	v_sqrt_f32_e32 v165, v164
	v_sqrt_f32_e32 v168, v167
	s_nop 1
	v_pk_mul_f32 v[140:141], v[96:97], v[132:133] op_sel_hi:[1,0]
	v_cvt_pk_bf16_f32 v148, v140, v141
	v_pk_mul_f32 v[142:143], v[98:99], v[132:133] op_sel_hi:[1,0]
	v_cvt_pk_bf16_f32 v149, v142, v143
	v_pk_mul_f32 v[144:145], v[100:101], v[132:133] op_sel_hi:[1,0]
	v_cvt_pk_bf16_f32 v150, v144, v145
	v_pk_mul_f32 v[146:147], v[102:103], v[132:133] op_sel_hi:[1,0]
	v_cvt_pk_bf16_f32 v151, v146, v147
	v_pk_mul_f32 v[140:141], v[104:105], v[132:133] op_sel_hi:[1,0]
	v_cvt_pk_bf16_f32 v152, v140, v141
	v_pk_mul_f32 v[142:143], v[106:107], v[132:133] op_sel_hi:[1,0]
	v_cvt_pk_bf16_f32 v153, v142, v143
	v_pk_mul_f32 v[144:145], v[108:109], v[132:133] op_sel_hi:[1,0]
	v_cvt_pk_bf16_f32 v154, v144, v145
	v_pk_mul_f32 v[146:147], v[110:111], v[132:133] op_sel_hi:[1,0]
	v_cvt_pk_bf16_f32 v155, v146, v147
	global_store_dwordx4 v173, v[148:151], s[98:99]
	global_store_dwordx4 v173, v[152:155], s[98:99] offset:1024
	v_add_u32_e32 v173, 0x400000, v173
	v_pk_mul_f32 v[140:141], v[112:113], v[134:135] op_sel_hi:[1,0]
	v_cvt_pk_bf16_f32 v156, v140, v141
	v_pk_mul_f32 v[142:143], v[114:115], v[134:135] op_sel_hi:[1,0]
	v_cvt_pk_bf16_f32 v157, v142, v143
	v_pk_mul_f32 v[144:145], v[116:117], v[134:135] op_sel_hi:[1,0]
	v_cvt_pk_bf16_f32 v158, v144, v145
	v_pk_mul_f32 v[146:147], v[118:119], v[134:135] op_sel_hi:[1,0]
	v_cvt_pk_bf16_f32 v159, v146, v147
	v_pk_mul_f32 v[140:141], v[120:121], v[134:135] op_sel_hi:[1,0]
	v_cvt_pk_bf16_f32 v160, v140, v141
	v_pk_mul_f32 v[142:143], v[122:123], v[134:135] op_sel_hi:[1,0]
	v_cvt_pk_bf16_f32 v161, v142, v143
	v_pk_mul_f32 v[144:145], v[124:125], v[134:135] op_sel_hi:[1,0]
	v_cvt_pk_bf16_f32 v162, v144, v145
	v_pk_mul_f32 v[146:147], v[126:127], v[134:135] op_sel_hi:[1,0]
	v_cvt_pk_bf16_f32 v163, v146, v147
	global_store_dwordx4 v173, v[156:159], s[98:99]
	global_store_dwordx4 v173, v[160:163], s[98:99] offset:1024
	v_add_u32_e32 v173, 0x400000, v173
	v_add_u32_e32 v166, -1, v165
	v_fma_f32 v140, -v166, v165, v164
	v_cmp_ge_f32_e32 vcc, 0, v140
	v_add_u32_e32 v141, 1, v165
	v_cndmask_b32_e32 v166, v165, v166, vcc
	v_fma_f32 v140, -v141, v165, v164
	v_cmp_lt_f32_e32 vcc, 0, v140
	s_nop 1
	v_cndmask_b32_e32 v165, v166, v141, vcc
	v_add_u32_e32 v169, -1, v168
	v_fma_f32 v142, -v169, v168, v167
	v_cmp_ge_f32_e32 vcc, 0, v142
	v_add_u32_e32 v143, 1, v168
	v_cndmask_b32_e32 v169, v168, v169, vcc
	v_fma_f32 v142, -v143, v168, v167
	v_cmp_lt_f32_e32 vcc, 0, v142
	s_nop 1
	v_cndmask_b32_e32 v168, v169, v143, vcc
	s_mov_b64 exec, 1
	global_store_dword v174, v165, s[98:99]
	v_add_u32_e32 v174, 0x2000, v174
	global_store_dword v174, v168, s[98:99]
	v_add_u32_e32 v174, 0x2000, v174
	s_mov_b64 exec, -1
	s_waitcnt vmcnt(29)
	v_lshlrev_b32_e32 v96, 16, v56
	v_and_b32_e32 v97, 0xffff0000, v56
	v_lshlrev_b32_e32 v98, 16, v57
	v_and_b32_e32 v99, 0xffff0000, v57
	v_lshlrev_b32_e32 v100, 16, v58
	v_and_b32_e32 v101, 0xffff0000, v58
	v_lshlrev_b32_e32 v102, 16, v59
	v_and_b32_e32 v103, 0xffff0000, v59
	v_lshlrev_b32_e32 v104, 16, v60
	v_and_b32_e32 v105, 0xffff0000, v60
	v_lshlrev_b32_e32 v106, 16, v61
	v_and_b32_e32 v107, 0xffff0000, v61
	v_lshlrev_b32_e32 v108, 16, v62
	v_and_b32_e32 v109, 0xffff0000, v62
	v_lshlrev_b32_e32 v110, 16, v63
	v_and_b32_e32 v111, 0xffff0000, v63
	v_pk_mul_f32 v[128:129], v[96:97], v[96:97]
	v_pk_fma_f32 v[128:129], v[98:99], v[98:99], v[128:129]
	v_pk_fma_f32 v[128:129], v[100:101], v[100:101], v[128:129]
	v_pk_fma_f32 v[128:129], v[102:103], v[102:103], v[128:129]
	v_pk_fma_f32 v[128:129], v[104:105], v[104:105], v[128:129]
	v_pk_fma_f32 v[128:129], v[106:107], v[106:107], v[128:129]
	v_pk_fma_f32 v[128:129], v[108:109], v[108:109], v[128:129]
	v_pk_fma_f32 v[128:129], v[110:111], v[110:111], v[128:129]
	s_nop 0
	v_add_f32_e32 v128, v128, v129
	s_waitcnt vmcnt(24)
	v_lshlrev_b32_e32 v112, 16, v64
	v_and_b32_e32 v113, 0xffff0000, v64
	v_lshlrev_b32_e32 v114, 16, v65
	v_and_b32_e32 v115, 0xffff0000, v65
	v_lshlrev_b32_e32 v116, 16, v66
	v_and_b32_e32 v117, 0xffff0000, v66
	v_lshlrev_b32_e32 v118, 16, v67
	v_and_b32_e32 v119, 0xffff0000, v67
	v_lshlrev_b32_e32 v120, 16, v68
	v_and_b32_e32 v121, 0xffff0000, v68
	v_lshlrev_b32_e32 v122, 16, v69
	v_and_b32_e32 v123, 0xffff0000, v69
	v_lshlrev_b32_e32 v124, 16, v70
	v_and_b32_e32 v125, 0xffff0000, v70
	v_lshlrev_b32_e32 v126, 16, v71
	v_and_b32_e32 v127, 0xffff0000, v71
	v_pk_mul_f32 v[130:131], v[112:113], v[112:113]
	v_pk_fma_f32 v[130:131], v[114:115], v[114:115], v[130:131]
	v_pk_fma_f32 v[130:131], v[116:117], v[116:117], v[130:131]
	v_pk_fma_f32 v[130:131], v[118:119], v[118:119], v[130:131]
	v_pk_fma_f32 v[130:131], v[120:121], v[120:121], v[130:131]
	v_pk_fma_f32 v[130:131], v[122:123], v[122:123], v[130:131]
	v_pk_fma_f32 v[130:131], v[124:125], v[124:125], v[130:131]
	v_pk_fma_f32 v[130:131], v[126:127], v[126:127], v[130:131]
	s_nop 0
	v_add_f32_e32 v130, v130, v131
	s_nop 1
	v_add_f32_dpp v128, v128, v128 quad_perm:[1,0,3,2] row_mask:0xf bank_mask:0xf
	v_add_f32_dpp v130, v130, v130 quad_perm:[1,0,3,2] row_mask:0xf bank_mask:0xf
	s_nop 0
	v_add_f32_dpp v128, v128, v128 quad_perm:[2,3,0,1] row_mask:0xf bank_mask:0xf
	v_add_f32_dpp v130, v130, v130 quad_perm:[2,3,0,1] row_mask:0xf bank_mask:0xf
	s_nop 0
	v_add_f32_dpp v128, v128, v128 row_half_mirror row_mask:0xf bank_mask:0xf
	v_add_f32_dpp v130, v130, v130 row_half_mirror row_mask:0xf bank_mask:0xf
	s_nop 0
	v_add_f32_dpp v128, v128, v128 row_mirror row_mask:0xf bank_mask:0xf
	v_add_f32_dpp v130, v130, v130 row_mirror row_mask:0xf bank_mask:0xf
	s_nop 0
	ds_bpermute_b32 v136, v187, v128
	ds_bpermute_b32 v137, v187, v130
	s_waitcnt lgkmcnt(0)
;     __device__ __forceinline__ float* out() const { return (float*)karg_in(33); }
; __device__ __forceinline__ float ssq4(v4f v) { return (v.x * v.x + v.y * v.y) + (v.z * v.z + v.w * v.w); }
; template <int R, bool BASE_F32, bool OUT_F32>
; __device__ __forceinline__ void rows_res(const Ctx& C, int m0, int stride, int mx, const float* gpost, float scale, int lane) {
;     ...
;     for (int r = 0; r < R; ++r) r1[r] = rsqrtf(wave_sum(r1[r]) * (1.f / DM) + EPS) * scale;
; #pragma unroll
;     for (int j = 0; j < 4; ++j) { const v4f gp = ld4_f32(gpost + 4 * lane + 256 * j);
; #pragma unroll
;         for (int r = 0; r < R; ++r) d[r][j] = b[r][j] + d[r][j] * r1[r] * gp; }
;     if (OUT_F32) { float* Y = C.out();
; #pragma unroll
;         for (int r = 0; r < R; ++r)
; #pragma unroll
;             for (int j = 0; j < 4; ++j) if (ok[r]) *(v4f*)(Y + (size_t)mr[r] * DM + 4 * lane + 256 * j) = d[r][j];
;     } else { float* rs = C.RS(); float t[R];
; #pragma unroll
;         for (int r = 0; r < R; ++r) { float s = 0.f;
; #pragma unroll
;             for (int j = 0; j < 4; ++j) s += ssq4(d[r][j]);
;             t[r] = s; }
	v_add_f32_e32 v128, v128, v136
	v_add_f32_e32 v130, v130, v137
	ds_bpermute_b32 v136, v188, v128
	ds_bpermute_b32 v137, v188, v130
	s_waitcnt lgkmcnt(0)
	v_add_f32_e32 v128, v128, v136
	v_add_f32_e32 v130, v130, v137
	v_fmamk_f32 v128, v128, 0x3a800000, v138
	v_fmamk_f32 v130, v130, 0x3a800000, v138
	s_nop 0
	v_rsq_f32_e32 v128, v128
	v_rsq_f32_e32 v130, v130
	s_nop 1
	v_mul_f32_e32 v128, 0.5, v128
	v_mul_f32_e32 v130, 0.5, v130
	s_waitcnt vmcnt(22)
	v_pk_mul_f32 v[96:97], v[128:129], v[96:97] op_sel_hi:[0,1]
	v_pk_mul_f32 v[98:99], v[128:129], v[98:99] op_sel_hi:[0,1]
	v_pk_mul_f32 v[100:101], v[128:129], v[100:101] op_sel_hi:[0,1]
	v_pk_mul_f32 v[102:103], v[128:129], v[102:103] op_sel_hi:[0,1]
	v_pk_mul_f32 v[104:105], v[128:129], v[104:105] op_sel_hi:[0,1]
	v_pk_mul_f32 v[106:107], v[128:129], v[106:107] op_sel_hi:[0,1]
	v_pk_mul_f32 v[108:109], v[128:129], v[108:109] op_sel_hi:[0,1]
	v_pk_mul_f32 v[110:111], v[128:129], v[110:111] op_sel_hi:[0,1]
	v_pk_mul_f32 v[96:97], v[96:97], v[192:193]
	v_pk_mul_f32 v[98:99], v[98:99], v[194:195]
	v_pk_mul_f32 v[100:101], v[100:101], v[196:197]
	v_pk_mul_f32 v[102:103], v[102:103], v[198:199]
	v_pk_mul_f32 v[104:105], v[104:105], v[200:201]
	v_pk_mul_f32 v[106:107], v[106:107], v[202:203]
	v_pk_mul_f32 v[108:109], v[108:109], v[204:205]
	v_pk_mul_f32 v[110:111], v[110:111], v[206:207]
	v_lshlrev_b32_e32 v56, 16, v72
	v_and_b32_e32 v57, 0xffff0000, v72
	v_lshlrev_b32_e32 v58, 16, v73
	v_and_b32_e32 v59, 0xffff0000, v73
	v_lshlrev_b32_e32 v60, 16, v74
	v_and_b32_e32 v61, 0xffff0000, v74
	v_lshlrev_b32_e32 v62, 16, v75
	v_and_b32_e32 v63, 0xffff0000, v75
	v_pk_fma_f32 v[96:97], v[88:89], v[56:57], v[96:97] op_sel_hi:[0,1,1]
	v_pk_fma_f32 v[98:99], v[88:89], v[58:59], v[98:99] op_sel_hi:[0,1,1]
	v_pk_fma_f32 v[100:101], v[88:89], v[60:61], v[100:101] op_sel_hi:[0,1,1]
	v_pk_fma_f32 v[102:103], v[88:89], v[62:63], v[102:103] op_sel_hi:[0,1,1]
	v_lshlrev_b32_e32 v56, 16, v76
	v_and_b32_e32 v57, 0xffff0000, v76
	v_lshlrev_b32_e32 v58, 16, v77
	v_and_b32_e32 v59, 0xffff0000, v77
	v_lshlrev_b32_e32 v60, 16, v78
	v_and_b32_e32 v61, 0xffff0000, v78
	v_lshlrev_b32_e32 v62, 16, v79
	v_and_b32_e32 v63, 0xffff0000, v79
	v_pk_fma_f32 v[104:105], v[88:89], v[56:57], v[104:105] op_sel_hi:[0,1,1]
	v_pk_fma_f32 v[106:107], v[88:89], v[58:59], v[106:107] op_sel_hi:[0,1,1]
	v_pk_fma_f32 v[108:109], v[88:89], v[60:61], v[108:109] op_sel_hi:[0,1,1]
	v_pk_fma_f32 v[110:111], v[88:89], v[62:63], v[110:111] op_sel_hi:[0,1,1]
	v_pk_mul_f32 v[132:133], v[96:97], v[96:97]
	v_pk_fma_f32 v[132:133], v[98:99], v[98:99], v[132:133]
	v_pk_fma_f32 v[132:133], v[100:101], v[100:101], v[132:133]
	v_pk_fma_f32 v[132:133], v[102:103], v[102:103], v[132:133]
	v_pk_fma_f32 v[132:133], v[104:105], v[104:105], v[132:133]
	v_pk_fma_f32 v[132:133], v[106:107], v[106:107], v[132:133]
	v_pk_fma_f32 v[132:133], v[108:109], v[108:109], v[132:133]
	v_pk_fma_f32 v[132:133], v[110:111], v[110:111], v[132:133]
	s_nop 0
	v_add_f32_e32 v132, v132, v133
	v_pk_mul_f32 v[112:113], v[130:131], v[112:113] op_sel_hi:[0,1]
	v_pk_mul_f32 v[114:115], v[130:131], v[114:115] op_sel_hi:[0,1]
	v_pk_mul_f32 v[116:117], v[130:131], v[116:117] op_sel_hi:[0,1]
	v_pk_mul_f32 v[118:119], v[130:131], v[118:119] op_sel_hi:[0,1]
	v_pk_mul_f32 v[120:121], v[130:131], v[120:121] op_sel_hi:[0,1]
	v_pk_mul_f32 v[122:123], v[130:131], v[122:123] op_sel_hi:[0,1]
	v_pk_mul_f32 v[124:125], v[130:131], v[124:125] op_sel_hi:[0,1]
	v_pk_mul_f32 v[126:127], v[130:131], v[126:127] op_sel_hi:[0,1]
	v_pk_mul_f32 v[112:113], v[112:113], v[192:193]
	v_pk_mul_f32 v[114:115], v[114:115], v[194:195]
	v_pk_mul_f32 v[116:117], v[116:117], v[196:197]
	v_pk_mul_f32 v[118:119], v[118:119], v[198:199]
	v_pk_mul_f32 v[120:121], v[120:121], v[200:201]
	v_pk_mul_f32 v[122:123], v[122:123], v[202:203]
	v_pk_mul_f32 v[124:125], v[124:125], v[204:205]
	v_pk_mul_f32 v[126:127], v[126:127], v[206:207]
	v_lshlrev_b32_e32 v64, 16, v80
	v_and_b32_e32 v65, 0xffff0000, v80
	v_lshlrev_b32_e32 v66, 16, v81
	v_and_b32_e32 v67, 0xffff0000, v81
	v_lshlrev_b32_e32 v68, 16, v82
	v_and_b32_e32 v69, 0xffff0000, v82
	v_lshlrev_b32_e32 v70, 16, v83
	v_and_b32_e32 v71, 0xffff0000, v83
	v_pk_fma_f32 v[112:113], v[90:91], v[64:65], v[112:113] op_sel_hi:[0,1,1]
	v_pk_fma_f32 v[114:115], v[90:91], v[66:67], v[114:115] op_sel_hi:[0,1,1]
	v_pk_fma_f32 v[116:117], v[90:91], v[68:69], v[116:117] op_sel_hi:[0,1,1]
	v_pk_fma_f32 v[118:119], v[90:91], v[70:71], v[118:119] op_sel_hi:[0,1,1]
	v_lshlrev_b32_e32 v64, 16, v84
	v_and_b32_e32 v65, 0xffff0000, v84
	v_lshlrev_b32_e32 v66, 16, v85
	v_and_b32_e32 v67, 0xffff0000, v85
	v_lshlrev_b32_e32 v68, 16, v86
	v_and_b32_e32 v69, 0xffff0000, v86
	v_lshlrev_b32_e32 v70, 16, v87
	v_and_b32_e32 v71, 0xffff0000, v87
	v_pk_fma_f32 v[120:121], v[90:91], v[64:65], v[120:121] op_sel_hi:[0,1,1]
	v_pk_fma_f32 v[122:123], v[90:91], v[66:67], v[122:123] op_sel_hi:[0,1,1]
	v_pk_fma_f32 v[124:125], v[90:91], v[68:69], v[124:125] op_sel_hi:[0,1,1]
	v_pk_fma_f32 v[126:127], v[90:91], v[70:71], v[126:127] op_sel_hi:[0,1,1]
	v_pk_mul_f32 v[134:135], v[112:113], v[112:113]
	v_pk_fma_f32 v[134:135], v[114:115], v[114:115], v[134:135]
	v_pk_fma_f32 v[134:135], v[116:117], v[116:117], v[134:135]
	v_pk_fma_f32 v[134:135], v[118:119], v[118:119], v[134:135]
	v_pk_fma_f32 v[134:135], v[120:121], v[120:121], v[134:135]
	v_pk_fma_f32 v[134:135], v[122:123], v[122:123], v[134:135]
	v_pk_fma_f32 v[134:135], v[124:125], v[124:125], v[134:135]
	v_pk_fma_f32 v[134:135], v[126:127], v[126:127], v[134:135]
	s_nop 0
	v_add_f32_e32 v134, v134, v135
	s_nop 1
	v_add_f32_dpp v132, v132, v132 quad_perm:[1,0,3,2] row_mask:0xf bank_mask:0xf
	v_add_f32_dpp v134, v134, v134 quad_perm:[1,0,3,2] row_mask:0xf bank_mask:0xf
	s_nop 0
	v_add_f32_dpp v132, v132, v132 quad_perm:[2,3,0,1] row_mask:0xf bank_mask:0xf
	v_add_f32_dpp v134, v134, v134 quad_perm:[2,3,0,1] row_mask:0xf bank_mask:0xf
	s_nop 0
	v_add_f32_dpp v132, v132, v132 row_half_mirror row_mask:0xf bank_mask:0xf
	v_add_f32_dpp v134, v134, v134 row_half_mirror row_mask:0xf bank_mask:0xf
	s_nop 0
	v_add_f32_dpp v132, v132, v132 row_mirror row_mask:0xf bank_mask:0xf
	v_add_f32_dpp v134, v134, v134 row_mirror row_mask:0xf bank_mask:0xf
	s_nop 0
	ds_bpermute_b32 v136, v187, v132
	ds_bpermute_b32 v137, v187, v134
	s_waitcnt lgkmcnt(0)
; __device__ __forceinline__ void st4_bf16(bf16* p, v4f o) { v2u w; w.x = cvt_pk_nv(o.x, o.y); w.y = cvt_pk_nv(o.z, o.w); *(v2u*)p = w; }
; __device__ __forceinline__ float ssq4(v4f v) { return (v.x * v.x + v.y * v.y) + (v.z * v.z + v.w * v.w); }
; template <int R, bool BASE_F32, bool OUT_F32>
; __device__ __forceinline__ void rows_res(const Ctx& C, int m0, int stride, int mx, const float* gpost, float scale, int lane) {
;     ...
; #pragma unroll
;     for (int r = 0; r < R; ++r) { float s = 0.f;
; #pragma unroll
;         for (int j = 0; j < 4; ++j) s += ssq4(d[r][j]);
;         r1[r] = s; }
; #pragma unroll
;     for (int r = 0; r < R; ++r) r1[r] = rsqrtf(wave_sum(r1[r]) * (1.f / DM) + EPS) * scale;
;     ...
;         for (int r = 0; r < R; ++r) t[r] = wave_sum(t[r]) * (1.f / DM) + EPS;
; #pragma unroll
;         for (int r = 0; r < R; ++r) { const float rstd = rsqrtf(t[r]);
; #pragma unroll
;             for (int j = 0; j < 4; ++j) if (ok[r]) st4_bf16(XN + (size_t)mr[r] * DM + 4 * lane + 256 * j, d[r][j] * rstd);
;             if (lane == 0 && ok[r]) rs[mr[r]] = sqrtf(t[r]); }
	v_add_f32_e32 v132, v132, v136
	v_add_f32_e32 v134, v134, v137
	ds_bpermute_b32 v136, v188, v132
	ds_bpermute_b32 v137, v188, v134
	s_waitcnt lgkmcnt(0)
	v_add_f32_e32 v132, v132, v136
	v_add_f32_e32 v134, v134, v137
	v_fmamk_f32 v164, v132, 0x3a800000, v138
	v_fmamk_f32 v167, v134, 0x3a800000, v138
	s_nop 0
	v_rsq_f32_e32 v132, v164
	v_rsq_f32_e32 v134, v167
	v_sqrt_f32_e32 v165, v164
	v_sqrt_f32_e32 v168, v167
	s_nop 1
	v_pk_mul_f32 v[140:141], v[96:97], v[132:133] op_sel_hi:[1,0]
	v_cvt_pk_bf16_f32 v148, v140, v141
	v_pk_mul_f32 v[142:143], v[98:99], v[132:133] op_sel_hi:[1,0]
	v_cvt_pk_bf16_f32 v149, v142, v143
	v_pk_mul_f32 v[144:145], v[100:101], v[132:133] op_sel_hi:[1,0]
	v_cvt_pk_bf16_f32 v150, v144, v145
	v_pk_mul_f32 v[146:147], v[102:103], v[132:133] op_sel_hi:[1,0]
	v_cvt_pk_bf16_f32 v151, v146, v147
	v_pk_mul_f32 v[140:141], v[104:105], v[132:133] op_sel_hi:[1,0]
	v_cvt_pk_bf16_f32 v152, v140, v141
	v_pk_mul_f32 v[142:143], v[106:107], v[132:133] op_sel_hi:[1,0]
	v_cvt_pk_bf16_f32 v153, v142, v143
	v_pk_mul_f32 v[144:145], v[108:109], v[132:133] op_sel_hi:[1,0]
	v_cvt_pk_bf16_f32 v154, v144, v145
	v_pk_mul_f32 v[146:147], v[110:111], v[132:133] op_sel_hi:[1,0]
	v_cvt_pk_bf16_f32 v155, v146, v147
	global_store_dwordx4 v173, v[148:151], s[98:99]
	global_store_dwordx4 v173, v[152:155], s[98:99] offset:1024
	v_add_u32_e32 v173, 0x400000, v173
	v_pk_mul_f32 v[140:141], v[112:113], v[134:135] op_sel_hi:[1,0]
	v_cvt_pk_bf16_f32 v156, v140, v141
	v_pk_mul_f32 v[142:143], v[114:115], v[134:135] op_sel_hi:[1,0]
	v_cvt_pk_bf16_f32 v157, v142, v143
	v_pk_mul_f32 v[144:145], v[116:117], v[134:135] op_sel_hi:[1,0]
	v_cvt_pk_bf16_f32 v158, v144, v145
	v_pk_mul_f32 v[146:147], v[118:119], v[134:135] op_sel_hi:[1,0]
	v_cvt_pk_bf16_f32 v159, v146, v147
	v_pk_mul_f32 v[140:141], v[120:121], v[134:135] op_sel_hi:[1,0]
	v_cvt_pk_bf16_f32 v160, v140, v141
	v_pk_mul_f32 v[142:143], v[122:123], v[134:135] op_sel_hi:[1,0]
	v_cvt_pk_bf16_f32 v161, v142, v143
	v_pk_mul_f32 v[144:145], v[124:125], v[134:135] op_sel_hi:[1,0]
	v_cvt_pk_bf16_f32 v162, v144, v145
	v_pk_mul_f32 v[146:147], v[126:127], v[134:135] op_sel_hi:[1,0]
	v_cvt_pk_bf16_f32 v163, v146, v147
	global_store_dwordx4 v173, v[156:159], s[98:99]
	global_store_dwordx4 v173, v[160:163], s[98:99] offset:1024
	v_add_u32_e32 v173, 0x400000, v173
	v_add_u32_e32 v166, -1, v165
	v_fma_f32 v140, -v166, v165, v164
	v_cmp_ge_f32_e32 vcc, 0, v140
	v_add_u32_e32 v141, 1, v165
	v_cndmask_b32_e32 v166, v165, v166, vcc
	v_fma_f32 v140, -v141, v165, v164
	v_cmp_lt_f32_e32 vcc, 0, v140
	s_nop 1
	v_cndmask_b32_e32 v165, v166, v141, vcc
	v_add_u32_e32 v169, -1, v168
	v_fma_f32 v142, -v169, v168, v167
	v_cmp_ge_f32_e32 vcc, 0, v142
	v_add_u32_e32 v143, 1, v168
	v_cndmask_b32_e32 v169, v168, v169, vcc
	v_fma_f32 v142, -v143, v168, v167
	v_cmp_lt_f32_e32 vcc, 0, v142
	s_nop 1
	v_cndmask_b32_e32 v168, v169, v143, vcc
	s_mov_b64 exec, 1
	global_store_dword v174, v165, s[98:99]
	v_add_u32_e32 v174, 0x2000, v174
	global_store_dword v174, v168, s[98:99]
	v_add_u32_e32 v174, 0x2000, v174
	s_mov_b64 exec, -1
	s_waitcnt vmcnt(19)
	v_lshlrev_b32_e32 v96, 16, v208
	v_and_b32_e32 v97, 0xffff0000, v208
	v_lshlrev_b32_e32 v98, 16, v209
	v_and_b32_e32 v99, 0xffff0000, v209
	v_lshlrev_b32_e32 v100, 16, v210
	v_and_b32_e32 v101, 0xffff0000, v210
	v_lshlrev_b32_e32 v102, 16, v211
	v_and_b32_e32 v103, 0xffff0000, v211
	v_lshlrev_b32_e32 v104, 16, v212
	v_and_b32_e32 v105, 0xffff0000, v212
	v_lshlrev_b32_e32 v106, 16, v213
	v_and_b32_e32 v107, 0xffff0000, v213
	v_lshlrev_b32_e32 v108, 16, v214
	v_and_b32_e32 v109, 0xffff0000, v214
	v_lshlrev_b32_e32 v110, 16, v215
	v_and_b32_e32 v111, 0xffff0000, v215
	v_pk_mul_f32 v[128:129], v[96:97], v[96:97]
	v_pk_fma_f32 v[128:129], v[98:99], v[98:99], v[128:129]
	v_pk_fma_f32 v[128:129], v[100:101], v[100:101], v[128:129]
	v_pk_fma_f32 v[128:129], v[102:103], v[102:103], v[128:129]
	v_pk_fma_f32 v[128:129], v[104:105], v[104:105], v[128:129]
	v_pk_fma_f32 v[128:129], v[106:107], v[106:107], v[128:129]
	v_pk_fma_f32 v[128:129], v[108:109], v[108:109], v[128:129]
	v_pk_fma_f32 v[128:129], v[110:111], v[110:111], v[128:129]
	s_nop 0
	v_add_f32_e32 v128, v128, v129
	s_waitcnt vmcnt(14)
	v_lshlrev_b32_e32 v112, 16, v216
	v_and_b32_e32 v113, 0xffff0000, v216
	v_lshlrev_b32_e32 v114, 16, v217
	v_and_b32_e32 v115, 0xffff0000, v217
	v_lshlrev_b32_e32 v116, 16, v218
	v_and_b32_e32 v117, 0xffff0000, v218
	v_lshlrev_b32_e32 v118, 16, v219
	v_and_b32_e32 v119, 0xffff0000, v219
	v_lshlrev_b32_e32 v120, 16, v220
	v_and_b32_e32 v121, 0xffff0000, v220
	v_lshlrev_b32_e32 v122, 16, v221
	v_and_b32_e32 v123, 0xffff0000, v221
	v_lshlrev_b32_e32 v124, 16, v222
	v_and_b32_e32 v125, 0xffff0000, v222
	v_lshlrev_b32_e32 v126, 16, v223
	v_and_b32_e32 v127, 0xffff0000, v223
	v_pk_mul_f32 v[130:131], v[112:113], v[112:113]
	v_pk_fma_f32 v[130:131], v[114:115], v[114:115], v[130:131]
	v_pk_fma_f32 v[130:131], v[116:117], v[116:117], v[130:131]
	v_pk_fma_f32 v[130:131], v[118:119], v[118:119], v[130:131]
	v_pk_fma_f32 v[130:131], v[120:121], v[120:121], v[130:131]
	v_pk_fma_f32 v[130:131], v[122:123], v[122:123], v[130:131]
	v_pk_fma_f32 v[130:131], v[124:125], v[124:125], v[130:131]
	v_pk_fma_f32 v[130:131], v[126:127], v[126:127], v[130:131]
	s_nop 0
	v_add_f32_e32 v130, v130, v131
	s_nop 1
	v_add_f32_dpp v128, v128, v128 quad_perm:[1,0,3,2] row_mask:0xf bank_mask:0xf
	v_add_f32_dpp v130, v130, v130 quad_perm:[1,0,3,2] row_mask:0xf bank_mask:0xf
	s_nop 0
	v_add_f32_dpp v128, v128, v128 quad_perm:[2,3,0,1] row_mask:0xf bank_mask:0xf
	v_add_f32_dpp v130, v130, v130 quad_perm:[2,3,0,1] row_mask:0xf bank_mask:0xf
	s_nop 0
	v_add_f32_dpp v128, v128, v128 row_half_mirror row_mask:0xf bank_mask:0xf
	v_add_f32_dpp v130, v130, v130 row_half_mirror row_mask:0xf bank_mask:0xf
	s_nop 0
	v_add_f32_dpp v128, v128, v128 row_mirror row_mask:0xf bank_mask:0xf
	v_add_f32_dpp v130, v130, v130 row_mirror row_mask:0xf bank_mask:0xf
	s_nop 0
	ds_bpermute_b32 v136, v187, v128
	ds_bpermute_b32 v137, v187, v130
	s_waitcnt lgkmcnt(0)
;     __device__ __forceinline__ float* out() const { return (float*)karg_in(33); }
; __device__ __forceinline__ float ssq4(v4f v) { return (v.x * v.x + v.y * v.y) + (v.z * v.z + v.w * v.w); }
; template <int R, bool BASE_F32, bool OUT_F32>
; __device__ __forceinline__ void rows_res(const Ctx& C, int m0, int stride, int mx, const float* gpost, float scale, int lane) {
;     ...
;     for (int r = 0; r < R; ++r) r1[r] = rsqrtf(wave_sum(r1[r]) * (1.f / DM) + EPS) * scale;
; #pragma unroll
;     for (int j = 0; j < 4; ++j) { const v4f gp = ld4_f32(gpost + 4 * lane + 256 * j);
; #pragma unroll
;         for (int r = 0; r < R; ++r) d[r][j] = b[r][j] + d[r][j] * r1[r] * gp; }
;     if (OUT_F32) { float* Y = C.out();
; #pragma unroll
;         for (int r = 0; r < R; ++r)
; #pragma unroll
;             for (int j = 0; j < 4; ++j) if (ok[r]) *(v4f*)(Y + (size_t)mr[r] * DM + 4 * lane + 256 * j) = d[r][j];
;     } else { float* rs = C.RS(); float t[R];
; #pragma unroll
;         for (int r = 0; r < R; ++r) { float s = 0.f;
; #pragma unroll
;             for (int j = 0; j < 4; ++j) s += ssq4(d[r][j]);
;             t[r] = s; }
	v_add_f32_e32 v128, v128, v136
	v_add_f32_e32 v130, v130, v137
	ds_bpermute_b32 v136, v188, v128
	ds_bpermute_b32 v137, v188, v130
	s_waitcnt lgkmcnt(0)
	v_add_f32_e32 v128, v128, v136
	v_add_f32_e32 v130, v130, v137
	v_fmamk_f32 v128, v128, 0x3a800000, v138
	v_fmamk_f32 v130, v130, 0x3a800000, v138
	s_nop 0
	v_rsq_f32_e32 v128, v128
	v_rsq_f32_e32 v130, v130
	s_nop 1
	v_mul_f32_e32 v128, 0.5, v128
	v_mul_f32_e32 v130, 0.5, v130
	s_waitcnt vmcnt(12)
	v_pk_mul_f32 v[96:97], v[128:129], v[96:97] op_sel_hi:[0,1]
	v_pk_mul_f32 v[98:99], v[128:129], v[98:99] op_sel_hi:[0,1]
	v_pk_mul_f32 v[100:101], v[128:129], v[100:101] op_sel_hi:[0,1]
	v_pk_mul_f32 v[102:103], v[128:129], v[102:103] op_sel_hi:[0,1]
	v_pk_mul_f32 v[104:105], v[128:129], v[104:105] op_sel_hi:[0,1]
	v_pk_mul_f32 v[106:107], v[128:129], v[106:107] op_sel_hi:[0,1]
	v_pk_mul_f32 v[108:109], v[128:129], v[108:109] op_sel_hi:[0,1]
	v_pk_mul_f32 v[110:111], v[128:129], v[110:111] op_sel_hi:[0,1]
	v_pk_mul_f32 v[96:97], v[96:97], v[192:193]
	v_pk_mul_f32 v[98:99], v[98:99], v[194:195]
	v_pk_mul_f32 v[100:101], v[100:101], v[196:197]
	v_pk_mul_f32 v[102:103], v[102:103], v[198:199]
	v_pk_mul_f32 v[104:105], v[104:105], v[200:201]
	v_pk_mul_f32 v[106:107], v[106:107], v[202:203]
	v_pk_mul_f32 v[108:109], v[108:109], v[204:205]
	v_pk_mul_f32 v[110:111], v[110:111], v[206:207]
	v_lshlrev_b32_e32 v208, 16, v224
	v_and_b32_e32 v209, 0xffff0000, v224
	v_lshlrev_b32_e32 v210, 16, v225
	v_and_b32_e32 v211, 0xffff0000, v225
	v_lshlrev_b32_e32 v212, 16, v226
	v_and_b32_e32 v213, 0xffff0000, v226
	v_lshlrev_b32_e32 v214, 16, v227
	v_and_b32_e32 v215, 0xffff0000, v227
	v_pk_fma_f32 v[96:97], v[12:13], v[208:209], v[96:97] op_sel_hi:[0,1,1]
	v_pk_fma_f32 v[98:99], v[12:13], v[210:211], v[98:99] op_sel_hi:[0,1,1]
	v_pk_fma_f32 v[100:101], v[12:13], v[212:213], v[100:101] op_sel_hi:[0,1,1]
	v_pk_fma_f32 v[102:103], v[12:13], v[214:215], v[102:103] op_sel_hi:[0,1,1]
	v_lshlrev_b32_e32 v208, 16, v228
	v_and_b32_e32 v209, 0xffff0000, v228
	v_lshlrev_b32_e32 v210, 16, v229
	v_and_b32_e32 v211, 0xffff0000, v229
	v_lshlrev_b32_e32 v212, 16, v230
	v_and_b32_e32 v213, 0xffff0000, v230
	v_lshlrev_b32_e32 v214, 16, v231
	v_and_b32_e32 v215, 0xffff0000, v231
	v_pk_fma_f32 v[104:105], v[12:13], v[208:209], v[104:105] op_sel_hi:[0,1,1]
	v_pk_fma_f32 v[106:107], v[12:13], v[210:211], v[106:107] op_sel_hi:[0,1,1]
	v_pk_fma_f32 v[108:109], v[12:13], v[212:213], v[108:109] op_sel_hi:[0,1,1]
	v_pk_fma_f32 v[110:111], v[12:13], v[214:215], v[110:111] op_sel_hi:[0,1,1]
	v_pk_mul_f32 v[132:133], v[96:97], v[96:97]
	v_pk_fma_f32 v[132:133], v[98:99], v[98:99], v[132:133]
	v_pk_fma_f32 v[132:133], v[100:101], v[100:101], v[132:133]
	v_pk_fma_f32 v[132:133], v[102:103], v[102:103], v[132:133]
	v_pk_fma_f32 v[132:133], v[104:105], v[104:105], v[132:133]
	v_pk_fma_f32 v[132:133], v[106:107], v[106:107], v[132:133]
	v_pk_fma_f32 v[132:133], v[108:109], v[108:109], v[132:133]
	v_pk_fma_f32 v[132:133], v[110:111], v[110:111], v[132:133]
	s_nop 0
	v_add_f32_e32 v132, v132, v133
	v_pk_mul_f32 v[112:113], v[130:131], v[112:113] op_sel_hi:[0,1]
	v_pk_mul_f32 v[114:115], v[130:131], v[114:115] op_sel_hi:[0,1]
	v_pk_mul_f32 v[116:117], v[130:131], v[116:117] op_sel_hi:[0,1]
	v_pk_mul_f32 v[118:119], v[130:131], v[118:119] op_sel_hi:[0,1]
	v_pk_mul_f32 v[120:121], v[130:131], v[120:121] op_sel_hi:[0,1]
	v_pk_mul_f32 v[122:123], v[130:131], v[122:123] op_sel_hi:[0,1]
	v_pk_mul_f32 v[124:125], v[130:131], v[124:125] op_sel_hi:[0,1]
	v_pk_mul_f32 v[126:127], v[130:131], v[126:127] op_sel_hi:[0,1]
	v_pk_mul_f32 v[112:113], v[112:113], v[192:193]
	v_pk_mul_f32 v[114:115], v[114:115], v[194:195]
	v_pk_mul_f32 v[116:117], v[116:117], v[196:197]
	v_pk_mul_f32 v[118:119], v[118:119], v[198:199]
	v_pk_mul_f32 v[120:121], v[120:121], v[200:201]
	v_pk_mul_f32 v[122:123], v[122:123], v[202:203]
	v_pk_mul_f32 v[124:125], v[124:125], v[204:205]
	v_pk_mul_f32 v[126:127], v[126:127], v[206:207]
	v_lshlrev_b32_e32 v216, 16, v4
	v_and_b32_e32 v217, 0xffff0000, v4
	v_lshlrev_b32_e32 v218, 16, v5
	v_and_b32_e32 v219, 0xffff0000, v5
	v_lshlrev_b32_e32 v220, 16, v6
	v_and_b32_e32 v221, 0xffff0000, v6
	v_lshlrev_b32_e32 v222, 16, v7
	v_and_b32_e32 v223, 0xffff0000, v7
	v_pk_fma_f32 v[112:113], v[14:15], v[216:217], v[112:113] op_sel_hi:[0,1,1]
	v_pk_fma_f32 v[114:115], v[14:15], v[218:219], v[114:115] op_sel_hi:[0,1,1]
	v_pk_fma_f32 v[116:117], v[14:15], v[220:221], v[116:117] op_sel_hi:[0,1,1]
	v_pk_fma_f32 v[118:119], v[14:15], v[222:223], v[118:119] op_sel_hi:[0,1,1]
	v_lshlrev_b32_e32 v216, 16, v8
	v_and_b32_e32 v217, 0xffff0000, v8
	v_lshlrev_b32_e32 v218, 16, v9
	v_and_b32_e32 v219, 0xffff0000, v9
	v_lshlrev_b32_e32 v220, 16, v10
	v_and_b32_e32 v221, 0xffff0000, v10
	v_lshlrev_b32_e32 v222, 16, v11
	v_and_b32_e32 v223, 0xffff0000, v11
	v_pk_fma_f32 v[120:121], v[14:15], v[216:217], v[120:121] op_sel_hi:[0,1,1]
	v_pk_fma_f32 v[122:123], v[14:15], v[218:219], v[122:123] op_sel_hi:[0,1,1]
	v_pk_fma_f32 v[124:125], v[14:15], v[220:221], v[124:125] op_sel_hi:[0,1,1]
	v_pk_fma_f32 v[126:127], v[14:15], v[222:223], v[126:127] op_sel_hi:[0,1,1]
	v_pk_mul_f32 v[134:135], v[112:113], v[112:113]
	v_pk_fma_f32 v[134:135], v[114:115], v[114:115], v[134:135]
	v_pk_fma_f32 v[134:135], v[116:117], v[116:117], v[134:135]
	v_pk_fma_f32 v[134:135], v[118:119], v[118:119], v[134:135]
	v_pk_fma_f32 v[134:135], v[120:121], v[120:121], v[134:135]
	v_pk_fma_f32 v[134:135], v[122:123], v[122:123], v[134:135]
	v_pk_fma_f32 v[134:135], v[124:125], v[124:125], v[134:135]
	v_pk_fma_f32 v[134:135], v[126:127], v[126:127], v[134:135]
	s_nop 0
	v_add_f32_e32 v134, v134, v135
	s_nop 1
	v_add_f32_dpp v132, v132, v132 quad_perm:[1,0,3,2] row_mask:0xf bank_mask:0xf
	v_add_f32_dpp v134, v134, v134 quad_perm:[1,0,3,2] row_mask:0xf bank_mask:0xf
	s_nop 0
	v_add_f32_dpp v132, v132, v132 quad_perm:[2,3,0,1] row_mask:0xf bank_mask:0xf
	v_add_f32_dpp v134, v134, v134 quad_perm:[2,3,0,1] row_mask:0xf bank_mask:0xf
	s_nop 0
	v_add_f32_dpp v132, v132, v132 row_half_mirror row_mask:0xf bank_mask:0xf
	v_add_f32_dpp v134, v134, v134 row_half_mirror row_mask:0xf bank_mask:0xf
	s_nop 0
	v_add_f32_dpp v132, v132, v132 row_mirror row_mask:0xf bank_mask:0xf
	v_add_f32_dpp v134, v134, v134 row_mirror row_mask:0xf bank_mask:0xf
	s_nop 0
	ds_bpermute_b32 v136, v187, v132
	ds_bpermute_b32 v137, v187, v134
	s_waitcnt lgkmcnt(0)
; __device__ __forceinline__ void st4_bf16(bf16* p, v4f o) { v2u w; w.x = cvt_pk_nv(o.x, o.y); w.y = cvt_pk_nv(o.z, o.w); *(v2u*)p = w; }
; template <int R, bool BASE_F32, bool OUT_F32>
; __device__ __forceinline__ void rows_res(const Ctx& C, int m0, int stride, int mx, const float* gpost, float scale, int lane) {
;     ...
;         for (int r = 0; r < R; ++r) t[r] = wave_sum(t[r]) * (1.f / DM) + EPS;
; #pragma unroll
;         for (int r = 0; r < R; ++r) { const float rstd = rsqrtf(t[r]);
; #pragma unroll
;             for (int j = 0; j < 4; ++j) if (ok[r]) st4_bf16(XN + (size_t)mr[r] * DM + 4 * lane + 256 * j, d[r][j] * rstd);
;             if (lane == 0 && ok[r]) rs[mr[r]] = sqrtf(t[r]); }
	v_add_f32_e32 v132, v132, v136
	v_add_f32_e32 v134, v134, v137
	ds_bpermute_b32 v136, v188, v132
	ds_bpermute_b32 v137, v188, v134
	s_waitcnt lgkmcnt(0)
	v_add_f32_e32 v132, v132, v136
	v_add_f32_e32 v134, v134, v137
	v_fmamk_f32 v164, v132, 0x3a800000, v138
	v_fmamk_f32 v167, v134, 0x3a800000, v138
	s_nop 0
	v_rsq_f32_e32 v132, v164
	v_rsq_f32_e32 v134, v167
	v_sqrt_f32_e32 v165, v164
	v_sqrt_f32_e32 v168, v167
	s_nop 1
	v_pk_mul_f32 v[140:141], v[96:97], v[132:133] op_sel_hi:[1,0]
	v_cvt_pk_bf16_f32 v148, v140, v141
	v_pk_mul_f32 v[142:143], v[98:99], v[132:133] op_sel_hi:[1,0]
	v_cvt_pk_bf16_f32 v149, v142, v143
	v_pk_mul_f32 v[144:145], v[100:101], v[132:133] op_sel_hi:[1,0]
	v_cvt_pk_bf16_f32 v150, v144, v145
	v_pk_mul_f32 v[146:147], v[102:103], v[132:133] op_sel_hi:[1,0]
	v_cvt_pk_bf16_f32 v151, v146, v147
	v_pk_mul_f32 v[140:141], v[104:105], v[132:133] op_sel_hi:[1,0]
	v_cvt_pk_bf16_f32 v152, v140, v141
	v_pk_mul_f32 v[142:143], v[106:107], v[132:133] op_sel_hi:[1,0]
	v_cvt_pk_bf16_f32 v153, v142, v143
	v_pk_mul_f32 v[144:145], v[108:109], v[132:133] op_sel_hi:[1,0]
	v_cvt_pk_bf16_f32 v154, v144, v145
	v_pk_mul_f32 v[146:147], v[110:111], v[132:133] op_sel_hi:[1,0]
	v_cvt_pk_bf16_f32 v155, v146, v147
	global_store_dwordx4 v173, v[148:151], s[98:99]
	global_store_dwordx4 v173, v[152:155], s[98:99] offset:1024
	v_add_u32_e32 v173, 0x400000, v173
	v_pk_mul_f32 v[140:141], v[112:113], v[134:135] op_sel_hi:[1,0]
	v_cvt_pk_bf16_f32 v156, v140, v141
	v_pk_mul_f32 v[142:143], v[114:115], v[134:135] op_sel_hi:[1,0]
	v_cvt_pk_bf16_f32 v157, v142, v143
	v_pk_mul_f32 v[144:145], v[116:117], v[134:135] op_sel_hi:[1,0]
	v_cvt_pk_bf16_f32 v158, v144, v145
	v_pk_mul_f32 v[146:147], v[118:119], v[134:135] op_sel_hi:[1,0]
	v_cvt_pk_bf16_f32 v159, v146, v147
	v_pk_mul_f32 v[140:141], v[120:121], v[134:135] op_sel_hi:[1,0]
	v_cvt_pk_bf16_f32 v160, v140, v141
	v_pk_mul_f32 v[142:143], v[122:123], v[134:135] op_sel_hi:[1,0]
	v_cvt_pk_bf16_f32 v161, v142, v143
	v_pk_mul_f32 v[144:145], v[124:125], v[134:135] op_sel_hi:[1,0]
	v_cvt_pk_bf16_f32 v162, v144, v145
	v_pk_mul_f32 v[146:147], v[126:127], v[134:135] op_sel_hi:[1,0]
	v_cvt_pk_bf16_f32 v163, v146, v147
	global_store_dwordx4 v173, v[156:159], s[98:99]
	global_store_dwordx4 v173, v[160:163], s[98:99] offset:1024
	v_add_u32_e32 v173, 0x400000, v173
	v_add_u32_e32 v166, -1, v165
	v_fma_f32 v140, -v166, v165, v164
	v_cmp_ge_f32_e32 vcc, 0, v140
	v_add_u32_e32 v141, 1, v165
	v_cndmask_b32_e32 v166, v165, v166, vcc
	v_fma_f32 v140, -v141, v165, v164
	v_cmp_lt_f32_e32 vcc, 0, v140
	s_nop 1
	v_cndmask_b32_e32 v165, v166, v141, vcc
	v_add_u32_e32 v169, -1, v168
	v_fma_f32 v142, -v169, v168, v167
	v_cmp_ge_f32_e32 vcc, 0, v142
	v_add_u32_e32 v143, 1, v168
	v_cndmask_b32_e32 v169, v168, v169, vcc
	v_fma_f32 v142, -v143, v168, v167
	v_cmp_lt_f32_e32 vcc, 0, v142
	s_nop 1
	v_cndmask_b32_e32 v168, v169, v143, vcc
	s_mov_b64 exec, 1
	global_store_dword v174, v165, s[98:99]
	v_add_u32_e32 v174, 0x2000, v174
	global_store_dword v174, v168, s[98:99]
	v_add_u32_e32 v174, 0x2000, v174
	s_mov_b64 exec, -1
	s_branch .LBB0_385
	v_mov_b32_e32 v3, v1
	s_mov_b32 s0, 0x358637bd
	s_waitcnt lgkmcnt(0)
	v_lshl_add_u64 v[4:5], s[14:15], 0, v[2:3]
	s_mov_b64 s[12:13], 0x7100000
	s_mov_b64 s[16:17], 0x3000000
	v_mov_b32_e32 v3, 0x2a80000
	s_mov_b32 s18, 0x3a800000
	v_mov_b64_e32 v[6:7], s[0:1]
	s_mov_b32 s19, 0x800000
	v_mov_b32_e32 v37, 0x358637bd
	s_mov_b32 s43, 0xf800000
	v_mov_b32_e32 v148, 0x260
	s_mov_b32 s20, s42
	v_readlane_b32 s54, v232, 5
	s_branch .LBB0_369

;     __device__ __forceinline__ const float* in(int i) const { return karg_in(i); }
; __device__ __forceinline__ const float* xrow_ptr(const Ctx& C, int row) { return row < MPROMPT ? C.in(0) + (size_t)row * DM : C.in(1) + (size_t)(row - MPROMPT) * DM; }
; __device__ __forceinline__ v4f ld4_bf16(const bf16* p) { const v2u w = *(const v2u*)p; return (v4f){bf_lo(w.x), bf_hi(w.x), bf_lo(w.y), bf_hi(w.y)}; }
; __device__ __forceinline__ float ssq4(v4f v) { return (v.x * v.x + v.y * v.y) + (v.z * v.z + v.w * v.w); }
; #define FTID const int ftid_ = fresh_tid()
; template <int R, bool BASE_F32, bool OUT_F32>
; __device__ __forceinline__ void rows_res(const Ctx& C, int m0, int stride, int mx, const float* gpost, float scale, int lane) {
;     ...
;     const bf16* D = C.D(); bf16* XN = C.XN();
; #pragma unroll
;     for (int r = 0; r < R; ++r) { mr[r] = (r == 4) ? mx : m0 + r * stride; ok[r] = (r == 4) ? (mx < M) : (mr[r] < MPROMPT); const int mm = ok[r] ? mr[r] : 0;
; #pragma unroll
;         for (int j = 0; j < 4; ++j) d[r][j] = ld4_bf16(D + (size_t)mm * DM + 4 * lane + 256 * j);
;         if (BASE_F32) { const float* x = xrow_ptr(C, mm);
; #pragma unroll
;             for (int j = 0; j < 4; ++j) b[r][j] = ld4_f32(x + 4 * lane + 256 * j);
;         } else { const float inv = C.RS()[mm];
; #pragma unroll
;             for (int j = 0; j < 4; ++j) b[r][j] = ld4_bf16(XN + (size_t)mm * DM + 4 * lane + 256 * j) * inv;
;         } }
; #pragma unroll
;     for (int r = 0; r < R; ++r) { float s = 0.f;
; #pragma unroll
;         for (int j = 0; j < 4; ++j) s += ssq4(d[r][j]);
;         r1[r] = s; }
; #pragma unroll
;     for (int r = 0; r < R; ++r) r1[r] = rsqrtf(wave_sum(r1[r]) * (1.f / DM) + EPS) * scale;
; __global__ void __launch_bounds__(NTHREADS, 2) fwd_kernel(Args args) {
;     ...
;     { FTID; const float* gp = C.in(27); { const int gw_ = GWV, ngw_ = NGWV, nit = (MPROMPT + 4 * ngw_ - 1) / (4 * ngw_);
;       for (int it = 0; it < nit - 1; ++it) rows_res<4, false, false>(C, gw_ + 4 * it * ngw_, ngw_, M, gp, 1.0f, LANE);
.LBB0_994:
	s_or_b64 exec, exec, s[10:11]
	s_waitcnt lgkmcnt(0)
	v_mov_b32_e32 v0, v182
	s_mov_b64 s[0:1], s[80:81]
	s_barrier
	s_load_dwordx2 s[16:17], s[0:1], 0xd8
	v_readfirstlane_b32 s0, v0
	v_and_b32_e32 v189, 63, v0
	s_ashr_i32 s47, s0, 6
	v_readlane_b32 s0, v232, 0
	v_lshlrev_b32_e32 v0, 2, v189
	s_add_i32 s23, s47, s0
	v_mov_b32_e32 v1, 0
	s_and_b64 vcc, exec, s[6:7]
	v_lshlrev_b32_e32 v2, 2, v0
	v_cmp_ne_u32_e64 s[10:11], 0, v189
	v_lshlrev_b32_e32 v0, 1, v0
	s_load_dwordx2 s[98:99], s[80:81], 0x110
	s_load_dwordx2 s[100:101], s[80:81], 0xd8
	v_and_b32_e32 v176, 63, v182
	v_lshlrev_b32_e32 v170, 4, v176
	s_lshl_b32 vcc_lo, s23, 11
	v_add_u32_e32 v170, vcc_lo, v170
	v_add_u32_e32 v171, 0x3000000, v170
	v_add_u32_e32 v170, 0x7100000, v170
	v_mov_b32_e32 v173, v171
	s_lshl_b32 vcc_lo, s23, 2
	v_mov_b32_e32 v172, 0x2a80000
	v_add_u32_e32 v172, vcc_lo, v172
	v_mov_b32_e32 v174, v172
	v_lshlrev_b32_e32 v176, 5, v176
	v_mov_b32_e32 v138, 0x358637bd
	s_waitcnt lgkmcnt(0)
	global_load_dwordx4 v[192:195], v176, s[100:101]
	global_load_dwordx4 v[196:199], v176, s[100:101] offset:16
	global_load_dwordx4 v[200:203], v176, s[100:101] offset:2048
	global_load_dwordx4 v[204:207], v176, s[100:101] offset:2064
	global_load_dword v52, v172, s[98:99]
	global_load_dwordx4 v[20:23], v170, s[98:99]
	global_load_dwordx4 v[24:27], v170, s[98:99] offset:1024
	global_load_dwordx4 v[36:39], v171, s[98:99]
	global_load_dwordx4 v[40:43], v171, s[98:99] offset:1024
	v_add_u32_e32 v170, 0x400000, v170
	v_add_u32_e32 v171, 0x400000, v171
	v_add_u32_e32 v172, 0x2000, v172
	global_load_dword v54, v172, s[98:99]
	global_load_dwordx4 v[28:31], v170, s[98:99]
	global_load_dwordx4 v[32:35], v170, s[98:99] offset:1024
	global_load_dwordx4 v[44:47], v171, s[98:99]
	global_load_dwordx4 v[48:51], v171, s[98:99] offset:1024
	v_add_u32_e32 v170, 0x400000, v170
	v_add_u32_e32 v171, 0x400000, v171
	v_add_u32_e32 v172, 0x2000, v172
	global_load_dword v88, v172, s[98:99]
	global_load_dwordx4 v[56:59], v170, s[98:99]
	global_load_dwordx4 v[60:63], v170, s[98:99] offset:1024
	global_load_dwordx4 v[72:75], v171, s[98:99]
	global_load_dwordx4 v[76:79], v171, s[98:99] offset:1024
	v_add_u32_e32 v170, 0x400000, v170
	v_add_u32_e32 v171, 0x400000, v171
	v_add_u32_e32 v172, 0x2000, v172
	global_load_dword v90, v172, s[98:99]
	global_load_dwordx4 v[64:67], v170, s[98:99]
	global_load_dwordx4 v[68:71], v170, s[98:99] offset:1024
	global_load_dwordx4 v[80:83], v171, s[98:99]
	global_load_dwordx4 v[84:87], v171, s[98:99] offset:1024
	v_add_u32_e32 v170, 0x400000, v170
	v_add_u32_e32 v171, 0x400000, v171
	v_add_u32_e32 v172, 0x2000, v172
	global_load_dword v12, v172, s[98:99]
	global_load_dwordx4 v[208:211], v170, s[98:99]
	global_load_dwordx4 v[212:215], v170, s[98:99] offset:1024
	global_load_dwordx4 v[224:227], v171, s[98:99]
	global_load_dwordx4 v[228:231], v171, s[98:99] offset:1024
	v_add_u32_e32 v170, 0x400000, v170
	v_add_u32_e32 v171, 0x400000, v171
	v_add_u32_e32 v172, 0x2000, v172
	global_load_dword v14, v172, s[98:99]
	global_load_dwordx4 v[216:219], v170, s[98:99]
	global_load_dwordx4 v[220:223], v170, s[98:99] offset:1024
	global_load_dwordx4 v[4:7], v171, s[98:99]
	global_load_dwordx4 v[8:11], v171, s[98:99] offset:1024
	v_add_u32_e32 v170, 0x400000, v170
	v_add_u32_e32 v171, 0x400000, v171
	v_add_u32_e32 v172, 0x2000, v172
	s_waitcnt vmcnt(27)
	v_lshlrev_b32_e32 v96, 16, v20
	v_and_b32_e32 v97, 0xffff0000, v20
	v_lshlrev_b32_e32 v98, 16, v21
	v_and_b32_e32 v99, 0xffff0000, v21
	v_lshlrev_b32_e32 v100, 16, v22
	v_and_b32_e32 v101, 0xffff0000, v22
	v_lshlrev_b32_e32 v102, 16, v23
	v_and_b32_e32 v103, 0xffff0000, v23
	v_lshlrev_b32_e32 v104, 16, v24
	v_and_b32_e32 v105, 0xffff0000, v24
	v_lshlrev_b32_e32 v106, 16, v25
	v_and_b32_e32 v107, 0xffff0000, v25
	v_lshlrev_b32_e32 v108, 16, v26
	v_and_b32_e32 v109, 0xffff0000, v26
	v_lshlrev_b32_e32 v110, 16, v27
	v_and_b32_e32 v111, 0xffff0000, v27
	v_pk_mul_f32 v[128:129], v[96:97], v[96:97]
	v_pk_fma_f32 v[128:129], v[98:99], v[98:99], v[128:129]
	v_pk_fma_f32 v[128:129], v[100:101], v[100:101], v[128:129]
	v_pk_fma_f32 v[128:129], v[102:103], v[102:103], v[128:129]
	v_pk_fma_f32 v[128:129], v[104:105], v[104:105], v[128:129]
	v_pk_fma_f32 v[128:129], v[106:107], v[106:107], v[128:129]
	v_pk_fma_f32 v[128:129], v[108:109], v[108:109], v[128:129]
	v_pk_fma_f32 v[128:129], v[110:111], v[110:111], v[128:129]
	s_nop 0
	v_add_f32_e32 v128, v128, v129
	s_waitcnt vmcnt(22)
	v_lshlrev_b32_e32 v112, 16, v28
	v_and_b32_e32 v113, 0xffff0000, v28
	v_lshlrev_b32_e32 v114, 16, v29
	v_and_b32_e32 v115, 0xffff0000, v29
	v_lshlrev_b32_e32 v116, 16, v30
	v_and_b32_e32 v117, 0xffff0000, v30
	v_lshlrev_b32_e32 v118, 16, v31
	v_and_b32_e32 v119, 0xffff0000, v31
	v_lshlrev_b32_e32 v120, 16, v32
	v_and_b32_e32 v121, 0xffff0000, v32
	v_lshlrev_b32_e32 v122, 16, v33
	v_and_b32_e32 v123, 0xffff0000, v33
	v_lshlrev_b32_e32 v124, 16, v34
	v_and_b32_e32 v125, 0xffff0000, v34
	v_lshlrev_b32_e32 v126, 16, v35
	v_and_b32_e32 v127, 0xffff0000, v35
	v_pk_mul_f32 v[130:131], v[112:113], v[112:113]
	v_pk_fma_f32 v[130:131], v[114:115], v[114:115], v[130:131]
	v_pk_fma_f32 v[130:131], v[116:117], v[116:117], v[130:131]
	v_pk_fma_f32 v[130:131], v[118:119], v[118:119], v[130:131]
	v_pk_fma_f32 v[130:131], v[120:121], v[120:121], v[130:131]
	v_pk_fma_f32 v[130:131], v[122:123], v[122:123], v[130:131]
	v_pk_fma_f32 v[130:131], v[124:125], v[124:125], v[130:131]
	v_pk_fma_f32 v[130:131], v[126:127], v[126:127], v[130:131]
	s_nop 0
	v_add_f32_e32 v130, v130, v131
	s_nop 1
	v_add_f32_dpp v128, v128, v128 quad_perm:[1,0,3,2] row_mask:0xf bank_mask:0xf
	v_add_f32_dpp v130, v130, v130 quad_perm:[1,0,3,2] row_mask:0xf bank_mask:0xf
	s_nop 0
	v_add_f32_dpp v128, v128, v128 quad_perm:[2,3,0,1] row_mask:0xf bank_mask:0xf
	v_add_f32_dpp v130, v130, v130 quad_perm:[2,3,0,1] row_mask:0xf bank_mask:0xf
	s_nop 0
	v_add_f32_dpp v128, v128, v128 row_half_mirror row_mask:0xf bank_mask:0xf
	v_add_f32_dpp v130, v130, v130 row_half_mirror row_mask:0xf bank_mask:0xf
	s_nop 0
	v_add_f32_dpp v128, v128, v128 row_mirror row_mask:0xf bank_mask:0xf
	v_add_f32_dpp v130, v130, v130 row_mirror row_mask:0xf bank_mask:0xf
	s_nop 0
	ds_bpermute_b32 v136, v187, v128
	ds_bpermute_b32 v137, v187, v130
	s_waitcnt lgkmcnt(0)
;     __device__ __forceinline__ float* out() const { return (float*)karg_in(33); }
; __device__ __forceinline__ float ssq4(v4f v) { return (v.x * v.x + v.y * v.y) + (v.z * v.z + v.w * v.w); }
; template <int R, bool BASE_F32, bool OUT_F32>
; __device__ __forceinline__ void rows_res(const Ctx& C, int m0, int stride, int mx, const float* gpost, float scale, int lane) {
;     ...
;     for (int r = 0; r < R; ++r) r1[r] = rsqrtf(wave_sum(r1[r]) * (1.f / DM) + EPS) * scale;
; #pragma unroll
;     for (int j = 0; j < 4; ++j) { const v4f gp = ld4_f32(gpost + 4 * lane + 256 * j);
; #pragma unroll
;         for (int r = 0; r < R; ++r) d[r][j] = b[r][j] + d[r][j] * r1[r] * gp; }
;     if (OUT_F32) { float* Y = C.out();
; #pragma unroll
;         for (int r = 0; r < R; ++r)
; #pragma unroll
;             for (int j = 0; j < 4; ++j) if (ok[r]) *(v4f*)(Y + (size_t)mr[r] * DM + 4 * lane + 256 * j) = d[r][j];
;     } else { float* rs = C.RS(); float t[R];
; #pragma unroll
;         for (int r = 0; r < R; ++r) { float s = 0.f;
; #pragma unroll
;             for (int j = 0; j < 4; ++j) s += ssq4(d[r][j]);
;             t[r] = s; }
	v_add_f32_e32 v128, v128, v136
	v_add_f32_e32 v130, v130, v137
	ds_bpermute_b32 v136, v188, v128
	ds_bpermute_b32 v137, v188, v130
	s_waitcnt lgkmcnt(0)
	v_add_f32_e32 v128, v128, v136
	v_add_f32_e32 v130, v130, v137
	v_fmamk_f32 v128, v128, 0x3a800000, v138
	v_fmamk_f32 v130, v130, 0x3a800000, v138
	s_nop 0
	v_rsq_f32_e32 v128, v128
	v_rsq_f32_e32 v130, v130
	s_nop 1
	s_waitcnt vmcnt(20)
	v_pk_mul_f32 v[96:97], v[128:129], v[96:97] op_sel_hi:[0,1]
	v_pk_mul_f32 v[98:99], v[128:129], v[98:99] op_sel_hi:[0,1]
	v_pk_mul_f32 v[100:101], v[128:129], v[100:101] op_sel_hi:[0,1]
	v_pk_mul_f32 v[102:103], v[128:129], v[102:103] op_sel_hi:[0,1]
	v_pk_mul_f32 v[104:105], v[128:129], v[104:105] op_sel_hi:[0,1]
	v_pk_mul_f32 v[106:107], v[128:129], v[106:107] op_sel_hi:[0,1]
	v_pk_mul_f32 v[108:109], v[128:129], v[108:109] op_sel_hi:[0,1]
	v_pk_mul_f32 v[110:111], v[128:129], v[110:111] op_sel_hi:[0,1]
	v_pk_mul_f32 v[96:97], v[96:97], v[192:193]
	v_pk_mul_f32 v[98:99], v[98:99], v[194:195]
	v_pk_mul_f32 v[100:101], v[100:101], v[196:197]
	v_pk_mul_f32 v[102:103], v[102:103], v[198:199]
	v_pk_mul_f32 v[104:105], v[104:105], v[200:201]
	v_pk_mul_f32 v[106:107], v[106:107], v[202:203]
	v_pk_mul_f32 v[108:109], v[108:109], v[204:205]
	v_pk_mul_f32 v[110:111], v[110:111], v[206:207]
	v_lshlrev_b32_e32 v20, 16, v36
	v_and_b32_e32 v21, 0xffff0000, v36
	v_lshlrev_b32_e32 v22, 16, v37
	v_and_b32_e32 v23, 0xffff0000, v37
	v_lshlrev_b32_e32 v24, 16, v38
	v_and_b32_e32 v25, 0xffff0000, v38
	v_lshlrev_b32_e32 v26, 16, v39
	v_and_b32_e32 v27, 0xffff0000, v39
	v_pk_fma_f32 v[96:97], v[52:53], v[20:21], v[96:97] op_sel_hi:[0,1,1]
	v_pk_fma_f32 v[98:99], v[52:53], v[22:23], v[98:99] op_sel_hi:[0,1,1]
	v_pk_fma_f32 v[100:101], v[52:53], v[24:25], v[100:101] op_sel_hi:[0,1,1]
	v_pk_fma_f32 v[102:103], v[52:53], v[26:27], v[102:103] op_sel_hi:[0,1,1]
	v_lshlrev_b32_e32 v20, 16, v40
	v_and_b32_e32 v21, 0xffff0000, v40
	v_lshlrev_b32_e32 v22, 16, v41
	v_and_b32_e32 v23, 0xffff0000, v41
	v_lshlrev_b32_e32 v24, 16, v42
	v_and_b32_e32 v25, 0xffff0000, v42
	v_lshlrev_b32_e32 v26, 16, v43
	v_and_b32_e32 v27, 0xffff0000, v43
	v_pk_fma_f32 v[104:105], v[52:53], v[20:21], v[104:105] op_sel_hi:[0,1,1]
	v_pk_fma_f32 v[106:107], v[52:53], v[22:23], v[106:107] op_sel_hi:[0,1,1]
	v_pk_fma_f32 v[108:109], v[52:53], v[24:25], v[108:109] op_sel_hi:[0,1,1]
	v_pk_fma_f32 v[110:111], v[52:53], v[26:27], v[110:111] op_sel_hi:[0,1,1]
	v_pk_mul_f32 v[132:133], v[96:97], v[96:97]
	v_pk_fma_f32 v[132:133], v[98:99], v[98:99], v[132:133]
	v_pk_fma_f32 v[132:133], v[100:101], v[100:101], v[132:133]
	v_pk_fma_f32 v[132:133], v[102:103], v[102:103], v[132:133]
	v_pk_fma_f32 v[132:133], v[104:105], v[104:105], v[132:133]
	v_pk_fma_f32 v[132:133], v[106:107], v[106:107], v[132:133]
	v_pk_fma_f32 v[132:133], v[108:109], v[108:109], v[132:133]
	v_pk_fma_f32 v[132:133], v[110:111], v[110:111], v[132:133]
	s_nop 0
	v_add_f32_e32 v132, v132, v133
	v_pk_mul_f32 v[112:113], v[130:131], v[112:113] op_sel_hi:[0,1]
	v_pk_mul_f32 v[114:115], v[130:131], v[114:115] op_sel_hi:[0,1]
	v_pk_mul_f32 v[116:117], v[130:131], v[116:117] op_sel_hi:[0,1]
	v_pk_mul_f32 v[118:119], v[130:131], v[118:119] op_sel_hi:[0,1]
	v_pk_mul_f32 v[120:121], v[130:131], v[120:121] op_sel_hi:[0,1]
	v_pk_mul_f32 v[122:123], v[130:131], v[122:123] op_sel_hi:[0,1]
	v_pk_mul_f32 v[124:125], v[130:131], v[124:125] op_sel_hi:[0,1]
	v_pk_mul_f32 v[126:127], v[130:131], v[126:127] op_sel_hi:[0,1]
	v_pk_mul_f32 v[112:113], v[112:113], v[192:193]
	v_pk_mul_f32 v[114:115], v[114:115], v[194:195]
	v_pk_mul_f32 v[116:117], v[116:117], v[196:197]
	v_pk_mul_f32 v[118:119], v[118:119], v[198:199]
	v_pk_mul_f32 v[120:121], v[120:121], v[200:201]
	v_pk_mul_f32 v[122:123], v[122:123], v[202:203]
	v_pk_mul_f32 v[124:125], v[124:125], v[204:205]
	v_pk_mul_f32 v[126:127], v[126:127], v[206:207]
	v_lshlrev_b32_e32 v28, 16, v44
	v_and_b32_e32 v29, 0xffff0000, v44
	v_lshlrev_b32_e32 v30, 16, v45
	v_and_b32_e32 v31, 0xffff0000, v45
	v_lshlrev_b32_e32 v32, 16, v46
	v_and_b32_e32 v33, 0xffff0000, v46
	v_lshlrev_b32_e32 v34, 16, v47
	v_and_b32_e32 v35, 0xffff0000, v47
	v_pk_fma_f32 v[112:113], v[54:55], v[28:29], v[112:113] op_sel_hi:[0,1,1]
	v_pk_fma_f32 v[114:115], v[54:55], v[30:31], v[114:115] op_sel_hi:[0,1,1]
	v_pk_fma_f32 v[116:117], v[54:55], v[32:33], v[116:117] op_sel_hi:[0,1,1]
	v_pk_fma_f32 v[118:119], v[54:55], v[34:35], v[118:119] op_sel_hi:[0,1,1]
	v_lshlrev_b32_e32 v28, 16, v48
	v_and_b32_e32 v29, 0xffff0000, v48
	v_lshlrev_b32_e32 v30, 16, v49
	v_and_b32_e32 v31, 0xffff0000, v49
	v_lshlrev_b32_e32 v32, 16, v50
	v_and_b32_e32 v33, 0xffff0000, v50
	v_lshlrev_b32_e32 v34, 16, v51
	v_and_b32_e32 v35, 0xffff0000, v51
	v_pk_fma_f32 v[120:121], v[54:55], v[28:29], v[120:121] op_sel_hi:[0,1,1]
	v_pk_fma_f32 v[122:123], v[54:55], v[30:31], v[122:123] op_sel_hi:[0,1,1]
	v_pk_fma_f32 v[124:125], v[54:55], v[32:33], v[124:125] op_sel_hi:[0,1,1]
	v_pk_fma_f32 v[126:127], v[54:55], v[34:35], v[126:127] op_sel_hi:[0,1,1]
	v_pk_mul_f32 v[134:135], v[112:113], v[112:113]
	v_pk_fma_f32 v[134:135], v[114:115], v[114:115], v[134:135]
	v_pk_fma_f32 v[134:135], v[116:117], v[116:117], v[134:135]
	v_pk_fma_f32 v[134:135], v[118:119], v[118:119], v[134:135]
	v_pk_fma_f32 v[134:135], v[120:121], v[120:121], v[134:135]
	v_pk_fma_f32 v[134:135], v[122:123], v[122:123], v[134:135]
	v_pk_fma_f32 v[134:135], v[124:125], v[124:125], v[134:135]
	v_pk_fma_f32 v[134:135], v[126:127], v[126:127], v[134:135]
	s_nop 0
	v_add_f32_e32 v134, v134, v135
	s_nop 1
	v_add_f32_dpp v132, v132, v132 quad_perm:[1,0,3,2] row_mask:0xf bank_mask:0xf
	v_add_f32_dpp v134, v134, v134 quad_perm:[1,0,3,2] row_mask:0xf bank_mask:0xf
	s_nop 0
	v_add_f32_dpp v132, v132, v132 quad_perm:[2,3,0,1] row_mask:0xf bank_mask:0xf
	v_add_f32_dpp v134, v134, v134 quad_perm:[2,3,0,1] row_mask:0xf bank_mask:0xf
	s_nop 0
	v_add_f32_dpp v132, v132, v132 row_half_mirror row_mask:0xf bank_mask:0xf
	v_add_f32_dpp v134, v134, v134 row_half_mirror row_mask:0xf bank_mask:0xf
	s_nop 0
	v_add_f32_dpp v132, v132, v132 row_mirror row_mask:0xf bank_mask:0xf
	v_add_f32_dpp v134, v134, v134 row_mirror row_mask:0xf bank_mask:0xf
	s_nop 0
	ds_bpermute_b32 v136, v187, v132
	ds_bpermute_b32 v137, v187, v134
	s_waitcnt lgkmcnt(0)
; __device__ __forceinline__ const float* xrow_ptr(const Ctx& C, int row) { return row < MPROMPT ? C.in(0) + (size_t)row * DM : C.in(1) + (size_t)(row - MPROMPT) * DM; }
; __device__ __forceinline__ v4f ld4_bf16(const bf16* p) { const v2u w = *(const v2u*)p; return (v4f){bf_lo(w.x), bf_hi(w.x), bf_lo(w.y), bf_hi(w.y)}; }
; __device__ __forceinline__ void st4_bf16(bf16* p, v4f o) { v2u w; w.x = cvt_pk_nv(o.x, o.y); w.y = cvt_pk_nv(o.z, o.w); *(v2u*)p = w; }
; __device__ __forceinline__ float ssq4(v4f v) { return (v.x * v.x + v.y * v.y) + (v.z * v.z + v.w * v.w); }
; template <int R, bool BASE_F32, bool OUT_F32>
; __device__ __forceinline__ void rows_res(const Ctx& C, int m0, int stride, int mx, const float* gpost, float scale, int lane) {
;     ...
;     for (int r = 0; r < R; ++r) { mr[r] = (r == 4) ? mx : m0 + r * stride; ok[r] = (r == 4) ? (mx < M) : (mr[r] < MPROMPT); const int mm = ok[r] ? mr[r] : 0;
; #pragma unroll
;         for (int j = 0; j < 4; ++j) d[r][j] = ld4_bf16(D + (size_t)mm * DM + 4 * lane + 256 * j);
;         if (BASE_F32) { const float* x = xrow_ptr(C, mm);
; #pragma unroll
;             for (int j = 0; j < 4; ++j) b[r][j] = ld4_f32(x + 4 * lane + 256 * j);
;         } else { const float inv = C.RS()[mm];
; #pragma unroll
;             for (int j = 0; j < 4; ++j) b[r][j] = ld4_bf16(XN + (size_t)mm * DM + 4 * lane + 256 * j) * inv;
;         } }
;     ...
;     } else { float* rs = C.RS(); float t[R];
; #pragma unroll
;         for (int r = 0; r < R; ++r) { float s = 0.f;
; #pragma unroll
;             for (int j = 0; j < 4; ++j) s += ssq4(d[r][j]);
;             t[r] = s; }
; #pragma unroll
;         for (int r = 0; r < R; ++r) t[r] = wave_sum(t[r]) * (1.f / DM) + EPS;
; #pragma unroll
;         for (int r = 0; r < R; ++r) { const float rstd = rsqrtf(t[r]);
; #pragma unroll
;             for (int j = 0; j < 4; ++j) if (ok[r]) st4_bf16(XN + (size_t)mr[r] * DM + 4 * lane + 256 * j, d[r][j] * rstd);
;             if (lane == 0 && ok[r]) rs[mr[r]] = sqrtf(t[r]); }
	v_add_f32_e32 v132, v132, v136
	v_add_f32_e32 v134, v134, v137
	ds_bpermute_b32 v136, v188, v132
	ds_bpermute_b32 v137, v188, v134
	s_waitcnt lgkmcnt(0)
	v_add_f32_e32 v132, v132, v136
	v_add_f32_e32 v134, v134, v137
	v_fmamk_f32 v164, v132, 0x3a800000, v138
	v_fmamk_f32 v167, v134, 0x3a800000, v138
	s_nop 0
	v_rsq_f32_e32 v132, v164
	v_rsq_f32_e32 v134, v167
	v_sqrt_f32_e32 v165, v164
	v_sqrt_f32_e32 v168, v167
	s_nop 1
	v_pk_mul_f32 v[140:141], v[96:97], v[132:133] op_sel_hi:[1,0]
	v_cvt_pk_bf16_f32 v148, v140, v141
	v_pk_mul_f32 v[142:143], v[98:99], v[132:133] op_sel_hi:[1,0]
	v_cvt_pk_bf16_f32 v149, v142, v143
	v_pk_mul_f32 v[144:145], v[100:101], v[132:133] op_sel_hi:[1,0]
	v_cvt_pk_bf16_f32 v150, v144, v145
	v_pk_mul_f32 v[146:147], v[102:103], v[132:133] op_sel_hi:[1,0]
	v_cvt_pk_bf16_f32 v151, v146, v147
	v_pk_mul_f32 v[140:141], v[104:105], v[132:133] op_sel_hi:[1,0]
	v_cvt_pk_bf16_f32 v152, v140, v141
	v_pk_mul_f32 v[142:143], v[106:107], v[132:133] op_sel_hi:[1,0]
	v_cvt_pk_bf16_f32 v153, v142, v143
	v_pk_mul_f32 v[144:145], v[108:109], v[132:133] op_sel_hi:[1,0]
	v_cvt_pk_bf16_f32 v154, v144, v145
	v_pk_mul_f32 v[146:147], v[110:111], v[132:133] op_sel_hi:[1,0]
	v_cvt_pk_bf16_f32 v155, v146, v147
	global_store_dwordx4 v173, v[148:151], s[98:99]
	global_store_dwordx4 v173, v[152:155], s[98:99] offset:1024
	v_add_u32_e32 v173, 0x400000, v173
	v_pk_mul_f32 v[140:141], v[112:113], v[134:135] op_sel_hi:[1,0]
	v_cvt_pk_bf16_f32 v156, v140, v141
	v_pk_mul_f32 v[142:143], v[114:115], v[134:135] op_sel_hi:[1,0]
	v_cvt_pk_bf16_f32 v157, v142, v143
	v_pk_mul_f32 v[144:145], v[116:117], v[134:135] op_sel_hi:[1,0]
	v_cvt_pk_bf16_f32 v158, v144, v145
	v_pk_mul_f32 v[146:147], v[118:119], v[134:135] op_sel_hi:[1,0]
	v_cvt_pk_bf16_f32 v159, v146, v147
	v_pk_mul_f32 v[140:141], v[120:121], v[134:135] op_sel_hi:[1,0]
	v_cvt_pk_bf16_f32 v160, v140, v141
	v_pk_mul_f32 v[142:143], v[122:123], v[134:135] op_sel_hi:[1,0]
	v_cvt_pk_bf16_f32 v161, v142, v143
	v_pk_mul_f32 v[144:145], v[124:125], v[134:135] op_sel_hi:[1,0]
	v_cvt_pk_bf16_f32 v162, v144, v145
	v_pk_mul_f32 v[146:147], v[126:127], v[134:135] op_sel_hi:[1,0]
	v_cvt_pk_bf16_f32 v163, v146, v147
	global_store_dwordx4 v173, v[156:159], s[98:99]
	global_store_dwordx4 v173, v[160:163], s[98:99] offset:1024
	v_add_u32_e32 v173, 0x400000, v173
	v_add_u32_e32 v166, -1, v165
	v_fma_f32 v140, -v166, v165, v164
	v_cmp_ge_f32_e32 vcc, 0, v140
	v_add_u32_e32 v141, 1, v165
	v_cndmask_b32_e32 v166, v165, v166, vcc
	v_fma_f32 v140, -v141, v165, v164
	v_cmp_lt_f32_e32 vcc, 0, v140
	s_nop 1
	v_cndmask_b32_e32 v165, v166, v141, vcc
	v_add_u32_e32 v169, -1, v168
	v_fma_f32 v142, -v169, v168, v167
	v_cmp_ge_f32_e32 vcc, 0, v142
	v_add_u32_e32 v143, 1, v168
	v_cndmask_b32_e32 v169, v168, v169, vcc
	v_fma_f32 v142, -v143, v168, v167
	v_cmp_lt_f32_e32 vcc, 0, v142
	s_nop 1
	v_cndmask_b32_e32 v168, v169, v143, vcc
	s_mov_b64 exec, 1
	global_store_dword v174, v165, s[98:99]
	v_add_u32_e32 v174, 0x2000, v174
	global_store_dword v174, v168, s[98:99]
	v_add_u32_e32 v174, 0x2000, v174
	s_mov_b64 exec, -1
	global_load_dword v52, v172, s[98:99]
	global_load_dwordx4 v[20:23], v170, s[98:99]
	global_load_dwordx4 v[24:27], v170, s[98:99] offset:1024
	global_load_dwordx4 v[36:39], v171, s[98:99]
	global_load_dwordx4 v[40:43], v171, s[98:99] offset:1024
	v_add_u32_e32 v170, 0x400000, v170
	v_add_u32_e32 v171, 0x400000, v171
	v_add_u32_e32 v172, 0x2000, v172
	global_load_dword v54, v172, s[98:99]
	global_load_dwordx4 v[28:31], v170, s[98:99]
	global_load_dwordx4 v[32:35], v170, s[98:99] offset:1024
	global_load_dwordx4 v[44:47], v171, s[98:99]
	global_load_dwordx4 v[48:51], v171, s[98:99] offset:1024
	v_add_u32_e32 v170, 0x400000, v170
	v_add_u32_e32 v171, 0x400000, v171
	v_add_u32_e32 v172, 0x2000, v172
	s_waitcnt vmcnt(33)
	v_lshlrev_b32_e32 v96, 16, v56
	v_and_b32_e32 v97, 0xffff0000, v56
	v_lshlrev_b32_e32 v98, 16, v57
	v_and_b32_e32 v99, 0xffff0000, v57
	v_lshlrev_b32_e32 v100, 16, v58
	v_and_b32_e32 v101, 0xffff0000, v58
	v_lshlrev_b32_e32 v102, 16, v59
	v_and_b32_e32 v103, 0xffff0000, v59
	v_lshlrev_b32_e32 v104, 16, v60
	v_and_b32_e32 v105, 0xffff0000, v60
	v_lshlrev_b32_e32 v106, 16, v61
	v_and_b32_e32 v107, 0xffff0000, v61
	v_lshlrev_b32_e32 v108, 16, v62
	v_and_b32_e32 v109, 0xffff0000, v62
	v_lshlrev_b32_e32 v110, 16, v63
	v_and_b32_e32 v111, 0xffff0000, v63
	v_pk_mul_f32 v[128:129], v[96:97], v[96:97]
	v_pk_fma_f32 v[128:129], v[98:99], v[98:99], v[128:129]
	v_pk_fma_f32 v[128:129], v[100:101], v[100:101], v[128:129]
	v_pk_fma_f32 v[128:129], v[102:103], v[102:103], v[128:129]
	v_pk_fma_f32 v[128:129], v[104:105], v[104:105], v[128:129]
	v_pk_fma_f32 v[128:129], v[106:107], v[106:107], v[128:129]
	v_pk_fma_f32 v[128:129], v[108:109], v[108:109], v[128:129]
	v_pk_fma_f32 v[128:129], v[110:111], v[110:111], v[128:129]
	s_nop 0
	v_add_f32_e32 v128, v128, v129
	s_waitcnt vmcnt(28)
; __device__ __forceinline__ float ssq4(v4f v) { return (v.x * v.x + v.y * v.y) + (v.z * v.z + v.w * v.w); }
; template <int R, bool BASE_F32, bool OUT_F32>
; __device__ __forceinline__ void rows_res(const Ctx& C, int m0, int stride, int mx, const float* gpost, float scale, int lane) {
;     ...
;     for (int r = 0; r < R; ++r) { float s = 0.f;
; #pragma unroll
;         for (int j = 0; j < 4; ++j) s += ssq4(d[r][j]);
;         r1[r] = s; }
; #pragma unroll
;     for (int r = 0; r < R; ++r) r1[r] = rsqrtf(wave_sum(r1[r]) * (1.f / DM) + EPS) * scale;
; #pragma unroll
;     for (int j = 0; j < 4; ++j) { const v4f gp = ld4_f32(gpost + 4 * lane + 256 * j);
; #pragma unroll
;         for (int r = 0; r < R; ++r) d[r][j] = b[r][j] + d[r][j] * r1[r] * gp; }
	v_lshlrev_b32_e32 v112, 16, v64
	v_and_b32_e32 v113, 0xffff0000, v64
	v_lshlrev_b32_e32 v114, 16, v65
	v_and_b32_e32 v115, 0xffff0000, v65
	v_lshlrev_b32_e32 v116, 16, v66
	v_and_b32_e32 v117, 0xffff0000, v66
	v_lshlrev_b32_e32 v118, 16, v67
	v_and_b32_e32 v119, 0xffff0000, v67
	v_lshlrev_b32_e32 v120, 16, v68
	v_and_b32_e32 v121, 0xffff0000, v68
	v_lshlrev_b32_e32 v122, 16, v69
	v_and_b32_e32 v123, 0xffff0000, v69
	v_lshlrev_b32_e32 v124, 16, v70
	v_and_b32_e32 v125, 0xffff0000, v70
	v_lshlrev_b32_e32 v126, 16, v71
	v_and_b32_e32 v127, 0xffff0000, v71
	v_pk_mul_f32 v[130:131], v[112:113], v[112:113]
	v_pk_fma_f32 v[130:131], v[114:115], v[114:115], v[130:131]
	v_pk_fma_f32 v[130:131], v[116:117], v[116:117], v[130:131]
	v_pk_fma_f32 v[130:131], v[118:119], v[118:119], v[130:131]
	v_pk_fma_f32 v[130:131], v[120:121], v[120:121], v[130:131]
	v_pk_fma_f32 v[130:131], v[122:123], v[122:123], v[130:131]
	v_pk_fma_f32 v[130:131], v[124:125], v[124:125], v[130:131]
	v_pk_fma_f32 v[130:131], v[126:127], v[126:127], v[130:131]
	s_nop 0
	v_add_f32_e32 v130, v130, v131
	s_nop 1
	v_add_f32_dpp v128, v128, v128 quad_perm:[1,0,3,2] row_mask:0xf bank_mask:0xf
	v_add_f32_dpp v130, v130, v130 quad_perm:[1,0,3,2] row_mask:0xf bank_mask:0xf
	s_nop 0
	v_add_f32_dpp v128, v128, v128 quad_perm:[2,3,0,1] row_mask:0xf bank_mask:0xf
	v_add_f32_dpp v130, v130, v130 quad_perm:[2,3,0,1] row_mask:0xf bank_mask:0xf
	s_nop 0
	v_add_f32_dpp v128, v128, v128 row_half_mirror row_mask:0xf bank_mask:0xf
	v_add_f32_dpp v130, v130, v130 row_half_mirror row_mask:0xf bank_mask:0xf
	s_nop 0
	v_add_f32_dpp v128, v128, v128 row_mirror row_mask:0xf bank_mask:0xf
	v_add_f32_dpp v130, v130, v130 row_mirror row_mask:0xf bank_mask:0xf
	s_nop 0
	ds_bpermute_b32 v136, v187, v128
	ds_bpermute_b32 v137, v187, v130
	s_waitcnt lgkmcnt(0)
	v_add_f32_e32 v128, v128, v136
	v_add_f32_e32 v130, v130, v137
	ds_bpermute_b32 v136, v188, v128
	ds_bpermute_b32 v137, v188, v130
	s_waitcnt lgkmcnt(0)
	v_add_f32_e32 v128, v128, v136
	v_add_f32_e32 v130, v130, v137
	v_fmamk_f32 v128, v128, 0x3a800000, v138
	v_fmamk_f32 v130, v130, 0x3a800000, v138
	s_nop 0
	v_rsq_f32_e32 v128, v128
	v_rsq_f32_e32 v130, v130
	s_nop 1
	s_waitcnt vmcnt(26)
	v_pk_mul_f32 v[96:97], v[128:129], v[96:97] op_sel_hi:[0,1]
	v_pk_mul_f32 v[98:99], v[128:129], v[98:99] op_sel_hi:[0,1]
	v_pk_mul_f32 v[100:101], v[128:129], v[100:101] op_sel_hi:[0,1]
	v_pk_mul_f32 v[102:103], v[128:129], v[102:103] op_sel_hi:[0,1]
	v_pk_mul_f32 v[104:105], v[128:129], v[104:105] op_sel_hi:[0,1]
	v_pk_mul_f32 v[106:107], v[128:129], v[106:107] op_sel_hi:[0,1]
	v_pk_mul_f32 v[108:109], v[128:129], v[108:109] op_sel_hi:[0,1]
	v_pk_mul_f32 v[110:111], v[128:129], v[110:111] op_sel_hi:[0,1]
	v_pk_mul_f32 v[96:97], v[96:97], v[192:193]
	v_pk_mul_f32 v[98:99], v[98:99], v[194:195]
	v_pk_mul_f32 v[100:101], v[100:101], v[196:197]
	v_pk_mul_f32 v[102:103], v[102:103], v[198:199]
	v_pk_mul_f32 v[104:105], v[104:105], v[200:201]
	v_pk_mul_f32 v[106:107], v[106:107], v[202:203]
	v_pk_mul_f32 v[108:109], v[108:109], v[204:205]
	v_pk_mul_f32 v[110:111], v[110:111], v[206:207]
	v_lshlrev_b32_e32 v56, 16, v72
	v_and_b32_e32 v57, 0xffff0000, v72
	v_lshlrev_b32_e32 v58, 16, v73
	v_and_b32_e32 v59, 0xffff0000, v73
	v_lshlrev_b32_e32 v60, 16, v74
	v_and_b32_e32 v61, 0xffff0000, v74
	v_lshlrev_b32_e32 v62, 16, v75
	v_and_b32_e32 v63, 0xffff0000, v75
	v_pk_fma_f32 v[96:97], v[88:89], v[56:57], v[96:97] op_sel_hi:[0,1,1]
	v_pk_fma_f32 v[98:99], v[88:89], v[58:59], v[98:99] op_sel_hi:[0,1,1]
	v_pk_fma_f32 v[100:101], v[88:89], v[60:61], v[100:101] op_sel_hi:[0,1,1]
	v_pk_fma_f32 v[102:103], v[88:89], v[62:63], v[102:103] op_sel_hi:[0,1,1]
	v_lshlrev_b32_e32 v56, 16, v76
	v_and_b32_e32 v57, 0xffff0000, v76
	v_lshlrev_b32_e32 v58, 16, v77
	v_and_b32_e32 v59, 0xffff0000, v77
	v_lshlrev_b32_e32 v60, 16, v78
	v_and_b32_e32 v61, 0xffff0000, v78
	v_lshlrev_b32_e32 v62, 16, v79
	v_and_b32_e32 v63, 0xffff0000, v79
	v_pk_fma_f32 v[104:105], v[88:89], v[56:57], v[104:105] op_sel_hi:[0,1,1]
	v_pk_fma_f32 v[106:107], v[88:89], v[58:59], v[106:107] op_sel_hi:[0,1,1]
	v_pk_fma_f32 v[108:109], v[88:89], v[60:61], v[108:109] op_sel_hi:[0,1,1]
	v_pk_fma_f32 v[110:111], v[88:89], v[62:63], v[110:111] op_sel_hi:[0,1,1]
	v_pk_mul_f32 v[132:133], v[96:97], v[96:97]
	v_pk_fma_f32 v[132:133], v[98:99], v[98:99], v[132:133]
	v_pk_fma_f32 v[132:133], v[100:101], v[100:101], v[132:133]
	v_pk_fma_f32 v[132:133], v[102:103], v[102:103], v[132:133]
	v_pk_fma_f32 v[132:133], v[104:105], v[104:105], v[132:133]
	v_pk_fma_f32 v[132:133], v[106:107], v[106:107], v[132:133]
	v_pk_fma_f32 v[132:133], v[108:109], v[108:109], v[132:133]
	v_pk_fma_f32 v[132:133], v[110:111], v[110:111], v[132:133]
	s_nop 0
	v_add_f32_e32 v132, v132, v133
	v_pk_mul_f32 v[112:113], v[130:131], v[112:113] op_sel_hi:[0,1]
	v_pk_mul_f32 v[114:115], v[130:131], v[114:115] op_sel_hi:[0,1]
	v_pk_mul_f32 v[116:117], v[130:131], v[116:117] op_sel_hi:[0,1]
	v_pk_mul_f32 v[118:119], v[130:131], v[118:119] op_sel_hi:[0,1]
	v_pk_mul_f32 v[120:121], v[130:131], v[120:121] op_sel_hi:[0,1]
	v_pk_mul_f32 v[122:123], v[130:131], v[122:123] op_sel_hi:[0,1]
	v_pk_mul_f32 v[124:125], v[130:131], v[124:125] op_sel_hi:[0,1]
	v_pk_mul_f32 v[126:127], v[130:131], v[126:127] op_sel_hi:[0,1]
	v_pk_mul_f32 v[112:113], v[112:113], v[192:193]
	v_pk_mul_f32 v[114:115], v[114:115], v[194:195]
	v_pk_mul_f32 v[116:117], v[116:117], v[196:197]
	v_pk_mul_f32 v[118:119], v[118:119], v[198:199]
	v_pk_mul_f32 v[120:121], v[120:121], v[200:201]
	v_pk_mul_f32 v[122:123], v[122:123], v[202:203]
	v_pk_mul_f32 v[124:125], v[124:125], v[204:205]
	v_pk_mul_f32 v[126:127], v[126:127], v[206:207]
;     __device__ __forceinline__ float* out() const { return (float*)karg_in(33); }
; __device__ __forceinline__ const float* xrow_ptr(const Ctx& C, int row) { return row < MPROMPT ? C.in(0) + (size_t)row * DM : C.in(1) + (size_t)(row - MPROMPT) * DM; }
; __device__ __forceinline__ v4f ld4_bf16(const bf16* p) { const v2u w = *(const v2u*)p; return (v4f){bf_lo(w.x), bf_hi(w.x), bf_lo(w.y), bf_hi(w.y)}; }
; __device__ __forceinline__ void st4_bf16(bf16* p, v4f o) { v2u w; w.x = cvt_pk_nv(o.x, o.y); w.y = cvt_pk_nv(o.z, o.w); *(v2u*)p = w; }
; __device__ __forceinline__ float ssq4(v4f v) { return (v.x * v.x + v.y * v.y) + (v.z * v.z + v.w * v.w); }
; template <int R, bool BASE_F32, bool OUT_F32>
; __device__ __forceinline__ void rows_res(const Ctx& C, int m0, int stride, int mx, const float* gpost, float scale, int lane) {
;     ...
;     for (int r = 0; r < R; ++r) { mr[r] = (r == 4) ? mx : m0 + r * stride; ok[r] = (r == 4) ? (mx < M) : (mr[r] < MPROMPT); const int mm = ok[r] ? mr[r] : 0;
; #pragma unroll
;         for (int j = 0; j < 4; ++j) d[r][j] = ld4_bf16(D + (size_t)mm * DM + 4 * lane + 256 * j);
;         if (BASE_F32) { const float* x = xrow_ptr(C, mm);
; #pragma unroll
;             for (int j = 0; j < 4; ++j) b[r][j] = ld4_f32(x + 4 * lane + 256 * j);
;         } else { const float inv = C.RS()[mm];
; #pragma unroll
;             for (int j = 0; j < 4; ++j) b[r][j] = ld4_bf16(XN + (size_t)mm * DM + 4 * lane + 256 * j) * inv;
;         } }
;     ...
;         for (int r = 0; r < R; ++r) d[r][j] = b[r][j] + d[r][j] * r1[r] * gp; }
;     if (OUT_F32) { float* Y = C.out();
; #pragma unroll
;         for (int r = 0; r < R; ++r)
; #pragma unroll
;             for (int j = 0; j < 4; ++j) if (ok[r]) *(v4f*)(Y + (size_t)mr[r] * DM + 4 * lane + 256 * j) = d[r][j];
;     } else { float* rs = C.RS(); float t[R];
; #pragma unroll
;         for (int r = 0; r < R; ++r) { float s = 0.f;
; #pragma unroll
;             for (int j = 0; j < 4; ++j) s += ssq4(d[r][j]);
;             t[r] = s; }
; #pragma unroll
;         for (int r = 0; r < R; ++r) t[r] = wave_sum(t[r]) * (1.f / DM) + EPS;
; #pragma unroll
;         for (int r = 0; r < R; ++r) { const float rstd = rsqrtf(t[r]);
; #pragma unroll
;             for (int j = 0; j < 4; ++j) if (ok[r]) st4_bf16(XN + (size_t)mr[r] * DM + 4 * lane + 256 * j, d[r][j] * rstd);
;             if (lane == 0 && ok[r]) rs[mr[r]] = sqrtf(t[r]); }
	v_lshlrev_b32_e32 v64, 16, v80
	v_and_b32_e32 v65, 0xffff0000, v80
	v_lshlrev_b32_e32 v66, 16, v81
	v_and_b32_e32 v67, 0xffff0000, v81
	v_lshlrev_b32_e32 v68, 16, v82
	v_and_b32_e32 v69, 0xffff0000, v82
	v_lshlrev_b32_e32 v70, 16, v83
	v_and_b32_e32 v71, 0xffff0000, v83
	v_pk_fma_f32 v[112:113], v[90:91], v[64:65], v[112:113] op_sel_hi:[0,1,1]
	v_pk_fma_f32 v[114:115], v[90:91], v[66:67], v[114:115] op_sel_hi:[0,1,1]
	v_pk_fma_f32 v[116:117], v[90:91], v[68:69], v[116:117] op_sel_hi:[0,1,1]
	v_pk_fma_f32 v[118:119], v[90:91], v[70:71], v[118:119] op_sel_hi:[0,1,1]
	v_lshlrev_b32_e32 v64, 16, v84
	v_and_b32_e32 v65, 0xffff0000, v84
	v_lshlrev_b32_e32 v66, 16, v85
	v_and_b32_e32 v67, 0xffff0000, v85
	v_lshlrev_b32_e32 v68, 16, v86
	v_and_b32_e32 v69, 0xffff0000, v86
	v_lshlrev_b32_e32 v70, 16, v87
	v_and_b32_e32 v71, 0xffff0000, v87
	v_pk_fma_f32 v[120:121], v[90:91], v[64:65], v[120:121] op_sel_hi:[0,1,1]
	v_pk_fma_f32 v[122:123], v[90:91], v[66:67], v[122:123] op_sel_hi:[0,1,1]
	v_pk_fma_f32 v[124:125], v[90:91], v[68:69], v[124:125] op_sel_hi:[0,1,1]
	v_pk_fma_f32 v[126:127], v[90:91], v[70:71], v[126:127] op_sel_hi:[0,1,1]
	v_pk_mul_f32 v[134:135], v[112:113], v[112:113]
	v_pk_fma_f32 v[134:135], v[114:115], v[114:115], v[134:135]
	v_pk_fma_f32 v[134:135], v[116:117], v[116:117], v[134:135]
	v_pk_fma_f32 v[134:135], v[118:119], v[118:119], v[134:135]
	v_pk_fma_f32 v[134:135], v[120:121], v[120:121], v[134:135]
	v_pk_fma_f32 v[134:135], v[122:123], v[122:123], v[134:135]
	v_pk_fma_f32 v[134:135], v[124:125], v[124:125], v[134:135]
	v_pk_fma_f32 v[134:135], v[126:127], v[126:127], v[134:135]
	s_nop 0
	v_add_f32_e32 v134, v134, v135
	s_nop 1
	v_add_f32_dpp v132, v132, v132 quad_perm:[1,0,3,2] row_mask:0xf bank_mask:0xf
	v_add_f32_dpp v134, v134, v134 quad_perm:[1,0,3,2] row_mask:0xf bank_mask:0xf
	s_nop 0
	v_add_f32_dpp v132, v132, v132 quad_perm:[2,3,0,1] row_mask:0xf bank_mask:0xf
	v_add_f32_dpp v134, v134, v134 quad_perm:[2,3,0,1] row_mask:0xf bank_mask:0xf
	s_nop 0
	v_add_f32_dpp v132, v132, v132 row_half_mirror row_mask:0xf bank_mask:0xf
	v_add_f32_dpp v134, v134, v134 row_half_mirror row_mask:0xf bank_mask:0xf
	s_nop 0
	v_add_f32_dpp v132, v132, v132 row_mirror row_mask:0xf bank_mask:0xf
	v_add_f32_dpp v134, v134, v134 row_mirror row_mask:0xf bank_mask:0xf
	s_nop 0
	ds_bpermute_b32 v136, v187, v132
	ds_bpermute_b32 v137, v187, v134
	s_waitcnt lgkmcnt(0)
	v_add_f32_e32 v132, v132, v136
	v_add_f32_e32 v134, v134, v137
	ds_bpermute_b32 v136, v188, v132
	ds_bpermute_b32 v137, v188, v134
	s_waitcnt lgkmcnt(0)
	v_add_f32_e32 v132, v132, v136
	v_add_f32_e32 v134, v134, v137
	v_fmamk_f32 v164, v132, 0x3a800000, v138
	v_fmamk_f32 v167, v134, 0x3a800000, v138
	s_nop 0
	v_rsq_f32_e32 v132, v164
	v_rsq_f32_e32 v134, v167
	v_sqrt_f32_e32 v165, v164
	v_sqrt_f32_e32 v168, v167
	s_nop 1
	v_pk_mul_f32 v[140:141], v[96:97], v[132:133] op_sel_hi:[1,0]
	v_cvt_pk_bf16_f32 v148, v140, v141
	v_pk_mul_f32 v[142:143], v[98:99], v[132:133] op_sel_hi:[1,0]
	v_cvt_pk_bf16_f32 v149, v142, v143
	v_pk_mul_f32 v[144:145], v[100:101], v[132:133] op_sel_hi:[1,0]
	v_cvt_pk_bf16_f32 v150, v144, v145
	v_pk_mul_f32 v[146:147], v[102:103], v[132:133] op_sel_hi:[1,0]
	v_cvt_pk_bf16_f32 v151, v146, v147
	v_pk_mul_f32 v[140:141], v[104:105], v[132:133] op_sel_hi:[1,0]
	v_cvt_pk_bf16_f32 v152, v140, v141
	v_pk_mul_f32 v[142:143], v[106:107], v[132:133] op_sel_hi:[1,0]
	v_cvt_pk_bf16_f32 v153, v142, v143
	v_pk_mul_f32 v[144:145], v[108:109], v[132:133] op_sel_hi:[1,0]
	v_cvt_pk_bf16_f32 v154, v144, v145
	v_pk_mul_f32 v[146:147], v[110:111], v[132:133] op_sel_hi:[1,0]
	v_cvt_pk_bf16_f32 v155, v146, v147
	global_store_dwordx4 v173, v[148:151], s[98:99]
	global_store_dwordx4 v173, v[152:155], s[98:99] offset:1024
	v_add_u32_e32 v173, 0x400000, v173
	v_pk_mul_f32 v[140:141], v[112:113], v[134:135] op_sel_hi:[1,0]
	v_cvt_pk_bf16_f32 v156, v140, v141
	v_pk_mul_f32 v[142:143], v[114:115], v[134:135] op_sel_hi:[1,0]
	v_cvt_pk_bf16_f32 v157, v142, v143
	v_pk_mul_f32 v[144:145], v[116:117], v[134:135] op_sel_hi:[1,0]
	v_cvt_pk_bf16_f32 v158, v144, v145
	v_pk_mul_f32 v[146:147], v[118:119], v[134:135] op_sel_hi:[1,0]
	v_cvt_pk_bf16_f32 v159, v146, v147
	v_pk_mul_f32 v[140:141], v[120:121], v[134:135] op_sel_hi:[1,0]
	v_cvt_pk_bf16_f32 v160, v140, v141
	v_pk_mul_f32 v[142:143], v[122:123], v[134:135] op_sel_hi:[1,0]
	v_cvt_pk_bf16_f32 v161, v142, v143
	v_pk_mul_f32 v[144:145], v[124:125], v[134:135] op_sel_hi:[1,0]
	v_cvt_pk_bf16_f32 v162, v144, v145
	v_pk_mul_f32 v[146:147], v[126:127], v[134:135] op_sel_hi:[1,0]
	v_cvt_pk_bf16_f32 v163, v146, v147
	global_store_dwordx4 v173, v[156:159], s[98:99]
	global_store_dwordx4 v173, v[160:163], s[98:99] offset:1024
	v_add_u32_e32 v173, 0x400000, v173
	v_add_u32_e32 v166, -1, v165
	v_fma_f32 v140, -v166, v165, v164
	v_cmp_ge_f32_e32 vcc, 0, v140
	v_add_u32_e32 v141, 1, v165
	v_cndmask_b32_e32 v166, v165, v166, vcc
	v_fma_f32 v140, -v141, v165, v164
	v_cmp_lt_f32_e32 vcc, 0, v140
	s_nop 1
	v_cndmask_b32_e32 v165, v166, v141, vcc
	v_add_u32_e32 v169, -1, v168
	v_fma_f32 v142, -v169, v168, v167
	v_cmp_ge_f32_e32 vcc, 0, v142
	v_add_u32_e32 v143, 1, v168
	v_cndmask_b32_e32 v169, v168, v169, vcc
	v_fma_f32 v142, -v143, v168, v167
	v_cmp_lt_f32_e32 vcc, 0, v142
	s_nop 1
	v_cndmask_b32_e32 v168, v169, v143, vcc
	s_mov_b64 exec, 1
	global_store_dword v174, v165, s[98:99]
	v_add_u32_e32 v174, 0x2000, v174
	global_store_dword v174, v168, s[98:99]
	v_add_u32_e32 v174, 0x2000, v174
	s_mov_b64 exec, -1
	global_load_dword v88, v172, s[98:99]
	global_load_dwordx4 v[56:59], v170, s[98:99]
	global_load_dwordx4 v[60:63], v170, s[98:99] offset:1024
	global_load_dwordx4 v[72:75], v171, s[98:99]
	global_load_dwordx4 v[76:79], v171, s[98:99] offset:1024
	v_add_u32_e32 v170, 0x400000, v170
	v_add_u32_e32 v171, 0x400000, v171
	v_add_u32_e32 v172, 0x2000, v172
	global_load_dword v90, v172, s[98:99]
	global_load_dwordx4 v[64:67], v170, s[98:99]
	global_load_dwordx4 v[68:71], v170, s[98:99] offset:1024
	global_load_dwordx4 v[80:83], v171, s[98:99]
	global_load_dwordx4 v[84:87], v171, s[98:99] offset:1024
	v_add_u32_e32 v170, 0x400000, v170
	v_add_u32_e32 v171, 0x400000, v171
	v_add_u32_e32 v172, 0x2000, v172
	s_waitcnt vmcnt(39)
;     __device__ __forceinline__ float* out() const { return (float*)karg_in(33); }
; __device__ __forceinline__ float ssq4(v4f v) { return (v.x * v.x + v.y * v.y) + (v.z * v.z + v.w * v.w); }
; template <int R, bool BASE_F32, bool OUT_F32>
; __device__ __forceinline__ void rows_res(const Ctx& C, int m0, int stride, int mx, const float* gpost, float scale, int lane) {
;     ...
;     for (int r = 0; r < R; ++r) { float s = 0.f;
; #pragma unroll
;         for (int j = 0; j < 4; ++j) s += ssq4(d[r][j]);
;         r1[r] = s; }
; #pragma unroll
;     for (int r = 0; r < R; ++r) r1[r] = rsqrtf(wave_sum(r1[r]) * (1.f / DM) + EPS) * scale;
; #pragma unroll
;     for (int j = 0; j < 4; ++j) { const v4f gp = ld4_f32(gpost + 4 * lane + 256 * j);
; #pragma unroll
;         for (int r = 0; r < R; ++r) d[r][j] = b[r][j] + d[r][j] * r1[r] * gp; }
;     if (OUT_F32) { float* Y = C.out();
; #pragma unroll
;         for (int r = 0; r < R; ++r)
; #pragma unroll
;             for (int j = 0; j < 4; ++j) if (ok[r]) *(v4f*)(Y + (size_t)mr[r] * DM + 4 * lane + 256 * j) = d[r][j];
;     } else { float* rs = C.RS(); float t[R];
; #pragma unroll
;         for (int r = 0; r < R; ++r) { float s = 0.f;
; #pragma unroll
;             for (int j = 0; j < 4; ++j) s += ssq4(d[r][j]);
;             t[r] = s; }
	v_lshlrev_b32_e32 v96, 16, v208
	v_and_b32_e32 v97, 0xffff0000, v208
	v_lshlrev_b32_e32 v98, 16, v209
	v_and_b32_e32 v99, 0xffff0000, v209
	v_lshlrev_b32_e32 v100, 16, v210
	v_and_b32_e32 v101, 0xffff0000, v210
	v_lshlrev_b32_e32 v102, 16, v211
	v_and_b32_e32 v103, 0xffff0000, v211
	v_lshlrev_b32_e32 v104, 16, v212
	v_and_b32_e32 v105, 0xffff0000, v212
	v_lshlrev_b32_e32 v106, 16, v213
	v_and_b32_e32 v107, 0xffff0000, v213
	v_lshlrev_b32_e32 v108, 16, v214
	v_and_b32_e32 v109, 0xffff0000, v214
	v_lshlrev_b32_e32 v110, 16, v215
	v_and_b32_e32 v111, 0xffff0000, v215
	v_pk_mul_f32 v[128:129], v[96:97], v[96:97]
	v_pk_fma_f32 v[128:129], v[98:99], v[98:99], v[128:129]
	v_pk_fma_f32 v[128:129], v[100:101], v[100:101], v[128:129]
	v_pk_fma_f32 v[128:129], v[102:103], v[102:103], v[128:129]
	v_pk_fma_f32 v[128:129], v[104:105], v[104:105], v[128:129]
	v_pk_fma_f32 v[128:129], v[106:107], v[106:107], v[128:129]
	v_pk_fma_f32 v[128:129], v[108:109], v[108:109], v[128:129]
	v_pk_fma_f32 v[128:129], v[110:111], v[110:111], v[128:129]
	s_nop 0
	v_add_f32_e32 v128, v128, v129
	s_waitcnt vmcnt(34)
	v_lshlrev_b32_e32 v112, 16, v216
	v_and_b32_e32 v113, 0xffff0000, v216
	v_lshlrev_b32_e32 v114, 16, v217
	v_and_b32_e32 v115, 0xffff0000, v217
	v_lshlrev_b32_e32 v116, 16, v218
	v_and_b32_e32 v117, 0xffff0000, v218
	v_lshlrev_b32_e32 v118, 16, v219
	v_and_b32_e32 v119, 0xffff0000, v219
	v_lshlrev_b32_e32 v120, 16, v220
	v_and_b32_e32 v121, 0xffff0000, v220
	v_lshlrev_b32_e32 v122, 16, v221
	v_and_b32_e32 v123, 0xffff0000, v221
	v_lshlrev_b32_e32 v124, 16, v222
	v_and_b32_e32 v125, 0xffff0000, v222
	v_lshlrev_b32_e32 v126, 16, v223
	v_and_b32_e32 v127, 0xffff0000, v223
	v_pk_mul_f32 v[130:131], v[112:113], v[112:113]
	v_pk_fma_f32 v[130:131], v[114:115], v[114:115], v[130:131]
	v_pk_fma_f32 v[130:131], v[116:117], v[116:117], v[130:131]
	v_pk_fma_f32 v[130:131], v[118:119], v[118:119], v[130:131]
	v_pk_fma_f32 v[130:131], v[120:121], v[120:121], v[130:131]
	v_pk_fma_f32 v[130:131], v[122:123], v[122:123], v[130:131]
	v_pk_fma_f32 v[130:131], v[124:125], v[124:125], v[130:131]
	v_pk_fma_f32 v[130:131], v[126:127], v[126:127], v[130:131]
	s_nop 0
	v_add_f32_e32 v130, v130, v131
	s_nop 1
	v_add_f32_dpp v128, v128, v128 quad_perm:[1,0,3,2] row_mask:0xf bank_mask:0xf
	v_add_f32_dpp v130, v130, v130 quad_perm:[1,0,3,2] row_mask:0xf bank_mask:0xf
	s_nop 0
	v_add_f32_dpp v128, v128, v128 quad_perm:[2,3,0,1] row_mask:0xf bank_mask:0xf
	v_add_f32_dpp v130, v130, v130 quad_perm:[2,3,0,1] row_mask:0xf bank_mask:0xf
	s_nop 0
	v_add_f32_dpp v128, v128, v128 row_half_mirror row_mask:0xf bank_mask:0xf
	v_add_f32_dpp v130, v130, v130 row_half_mirror row_mask:0xf bank_mask:0xf
	s_nop 0
	v_add_f32_dpp v128, v128, v128 row_mirror row_mask:0xf bank_mask:0xf
	v_add_f32_dpp v130, v130, v130 row_mirror row_mask:0xf bank_mask:0xf
	s_nop 0
	ds_bpermute_b32 v136, v187, v128
	ds_bpermute_b32 v137, v187, v130
	s_waitcnt lgkmcnt(0)
	v_add_f32_e32 v128, v128, v136
	v_add_f32_e32 v130, v130, v137
	ds_bpermute_b32 v136, v188, v128
	ds_bpermute_b32 v137, v188, v130
	s_waitcnt lgkmcnt(0)
	v_add_f32_e32 v128, v128, v136
	v_add_f32_e32 v130, v130, v137
	v_fmamk_f32 v128, v128, 0x3a800000, v138
	v_fmamk_f32 v130, v130, 0x3a800000, v138
	s_nop 0
	v_rsq_f32_e32 v128, v128
	v_rsq_f32_e32 v130, v130
	s_nop 1
	s_waitcnt vmcnt(32)
	v_pk_mul_f32 v[96:97], v[128:129], v[96:97] op_sel_hi:[0,1]
	v_pk_mul_f32 v[98:99], v[128:129], v[98:99] op_sel_hi:[0,1]
	v_pk_mul_f32 v[100:101], v[128:129], v[100:101] op_sel_hi:[0,1]
	v_pk_mul_f32 v[102:103], v[128:129], v[102:103] op_sel_hi:[0,1]
	v_pk_mul_f32 v[104:105], v[128:129], v[104:105] op_sel_hi:[0,1]
	v_pk_mul_f32 v[106:107], v[128:129], v[106:107] op_sel_hi:[0,1]
	v_pk_mul_f32 v[108:109], v[128:129], v[108:109] op_sel_hi:[0,1]
	v_pk_mul_f32 v[110:111], v[128:129], v[110:111] op_sel_hi:[0,1]
	v_pk_mul_f32 v[96:97], v[96:97], v[192:193]
	v_pk_mul_f32 v[98:99], v[98:99], v[194:195]
	v_pk_mul_f32 v[100:101], v[100:101], v[196:197]
	v_pk_mul_f32 v[102:103], v[102:103], v[198:199]
	v_pk_mul_f32 v[104:105], v[104:105], v[200:201]
	v_pk_mul_f32 v[106:107], v[106:107], v[202:203]
	v_pk_mul_f32 v[108:109], v[108:109], v[204:205]
	v_pk_mul_f32 v[110:111], v[110:111], v[206:207]
	v_lshlrev_b32_e32 v208, 16, v224
	v_and_b32_e32 v209, 0xffff0000, v224
	v_lshlrev_b32_e32 v210, 16, v225
	v_and_b32_e32 v211, 0xffff0000, v225
	v_lshlrev_b32_e32 v212, 16, v226
	v_and_b32_e32 v213, 0xffff0000, v226
	v_lshlrev_b32_e32 v214, 16, v227
	v_and_b32_e32 v215, 0xffff0000, v227
	v_pk_fma_f32 v[96:97], v[12:13], v[208:209], v[96:97] op_sel_hi:[0,1,1]
	v_pk_fma_f32 v[98:99], v[12:13], v[210:211], v[98:99] op_sel_hi:[0,1,1]
	v_pk_fma_f32 v[100:101], v[12:13], v[212:213], v[100:101] op_sel_hi:[0,1,1]
	v_pk_fma_f32 v[102:103], v[12:13], v[214:215], v[102:103] op_sel_hi:[0,1,1]
	v_lshlrev_b32_e32 v208, 16, v228
	v_and_b32_e32 v209, 0xffff0000, v228
	v_lshlrev_b32_e32 v210, 16, v229
	v_and_b32_e32 v211, 0xffff0000, v229
	v_lshlrev_b32_e32 v212, 16, v230
	v_and_b32_e32 v213, 0xffff0000, v230
	v_lshlrev_b32_e32 v214, 16, v231
	v_and_b32_e32 v215, 0xffff0000, v231
	v_pk_fma_f32 v[104:105], v[12:13], v[208:209], v[104:105] op_sel_hi:[0,1,1]
	v_pk_fma_f32 v[106:107], v[12:13], v[210:211], v[106:107] op_sel_hi:[0,1,1]
	v_pk_fma_f32 v[108:109], v[12:13], v[212:213], v[108:109] op_sel_hi:[0,1,1]
	v_pk_fma_f32 v[110:111], v[12:13], v[214:215], v[110:111] op_sel_hi:[0,1,1]
	v_pk_mul_f32 v[132:133], v[96:97], v[96:97]
	v_pk_fma_f32 v[132:133], v[98:99], v[98:99], v[132:133]
	v_pk_fma_f32 v[132:133], v[100:101], v[100:101], v[132:133]
	v_pk_fma_f32 v[132:133], v[102:103], v[102:103], v[132:133]
;     __device__ __forceinline__ float* out() const { return (float*)karg_in(33); }
; __device__ __forceinline__ void st4_bf16(bf16* p, v4f o) { v2u w; w.x = cvt_pk_nv(o.x, o.y); w.y = cvt_pk_nv(o.z, o.w); *(v2u*)p = w; }
; __device__ __forceinline__ float ssq4(v4f v) { return (v.x * v.x + v.y * v.y) + (v.z * v.z + v.w * v.w); }
; template <int R, bool BASE_F32, bool OUT_F32>
; __device__ __forceinline__ void rows_res(const Ctx& C, int m0, int stride, int mx, const float* gpost, float scale, int lane) {
;     ...
;     for (int j = 0; j < 4; ++j) { const v4f gp = ld4_f32(gpost + 4 * lane + 256 * j);
; #pragma unroll
;         for (int r = 0; r < R; ++r) d[r][j] = b[r][j] + d[r][j] * r1[r] * gp; }
;     if (OUT_F32) { float* Y = C.out();
; #pragma unroll
;         for (int r = 0; r < R; ++r)
; #pragma unroll
;             for (int j = 0; j < 4; ++j) if (ok[r]) *(v4f*)(Y + (size_t)mr[r] * DM + 4 * lane + 256 * j) = d[r][j];
;     } else { float* rs = C.RS(); float t[R];
; #pragma unroll
;         for (int r = 0; r < R; ++r) { float s = 0.f;
; #pragma unroll
;             for (int j = 0; j < 4; ++j) s += ssq4(d[r][j]);
;             t[r] = s; }
; #pragma unroll
;         for (int r = 0; r < R; ++r) t[r] = wave_sum(t[r]) * (1.f / DM) + EPS;
; #pragma unroll
;         for (int r = 0; r < R; ++r) { const float rstd = rsqrtf(t[r]);
; #pragma unroll
;             for (int j = 0; j < 4; ++j) if (ok[r]) st4_bf16(XN + (size_t)mr[r] * DM + 4 * lane + 256 * j, d[r][j] * rstd);
;             if (lane == 0 && ok[r]) rs[mr[r]] = sqrtf(t[r]); }
	v_pk_fma_f32 v[132:133], v[104:105], v[104:105], v[132:133]
	v_pk_fma_f32 v[132:133], v[106:107], v[106:107], v[132:133]
	v_pk_fma_f32 v[132:133], v[108:109], v[108:109], v[132:133]
	v_pk_fma_f32 v[132:133], v[110:111], v[110:111], v[132:133]
	s_nop 0
	v_add_f32_e32 v132, v132, v133
	v_pk_mul_f32 v[112:113], v[130:131], v[112:113] op_sel_hi:[0,1]
	v_pk_mul_f32 v[114:115], v[130:131], v[114:115] op_sel_hi:[0,1]
	v_pk_mul_f32 v[116:117], v[130:131], v[116:117] op_sel_hi:[0,1]
	v_pk_mul_f32 v[118:119], v[130:131], v[118:119] op_sel_hi:[0,1]
	v_pk_mul_f32 v[120:121], v[130:131], v[120:121] op_sel_hi:[0,1]
	v_pk_mul_f32 v[122:123], v[130:131], v[122:123] op_sel_hi:[0,1]
	v_pk_mul_f32 v[124:125], v[130:131], v[124:125] op_sel_hi:[0,1]
	v_pk_mul_f32 v[126:127], v[130:131], v[126:127] op_sel_hi:[0,1]
	v_pk_mul_f32 v[112:113], v[112:113], v[192:193]
	v_pk_mul_f32 v[114:115], v[114:115], v[194:195]
	v_pk_mul_f32 v[116:117], v[116:117], v[196:197]
	v_pk_mul_f32 v[118:119], v[118:119], v[198:199]
	v_pk_mul_f32 v[120:121], v[120:121], v[200:201]
	v_pk_mul_f32 v[122:123], v[122:123], v[202:203]
	v_pk_mul_f32 v[124:125], v[124:125], v[204:205]
	v_pk_mul_f32 v[126:127], v[126:127], v[206:207]
	v_lshlrev_b32_e32 v216, 16, v4
	v_and_b32_e32 v217, 0xffff0000, v4
	v_lshlrev_b32_e32 v218, 16, v5
	v_and_b32_e32 v219, 0xffff0000, v5
	v_lshlrev_b32_e32 v220, 16, v6
	v_and_b32_e32 v221, 0xffff0000, v6
	v_lshlrev_b32_e32 v222, 16, v7
	v_and_b32_e32 v223, 0xffff0000, v7
	v_pk_fma_f32 v[112:113], v[14:15], v[216:217], v[112:113] op_sel_hi:[0,1,1]
	v_pk_fma_f32 v[114:115], v[14:15], v[218:219], v[114:115] op_sel_hi:[0,1,1]
	v_pk_fma_f32 v[116:117], v[14:15], v[220:221], v[116:117] op_sel_hi:[0,1,1]
	v_pk_fma_f32 v[118:119], v[14:15], v[222:223], v[118:119] op_sel_hi:[0,1,1]
	v_lshlrev_b32_e32 v216, 16, v8
	v_and_b32_e32 v217, 0xffff0000, v8
	v_lshlrev_b32_e32 v218, 16, v9
	v_and_b32_e32 v219, 0xffff0000, v9
	v_lshlrev_b32_e32 v220, 16, v10
	v_and_b32_e32 v221, 0xffff0000, v10
	v_lshlrev_b32_e32 v222, 16, v11
	v_and_b32_e32 v223, 0xffff0000, v11
	v_pk_fma_f32 v[120:121], v[14:15], v[216:217], v[120:121] op_sel_hi:[0,1,1]
	v_pk_fma_f32 v[122:123], v[14:15], v[218:219], v[122:123] op_sel_hi:[0,1,1]
	v_pk_fma_f32 v[124:125], v[14:15], v[220:221], v[124:125] op_sel_hi:[0,1,1]
	v_pk_fma_f32 v[126:127], v[14:15], v[222:223], v[126:127] op_sel_hi:[0,1,1]
	v_pk_mul_f32 v[134:135], v[112:113], v[112:113]
	v_pk_fma_f32 v[134:135], v[114:115], v[114:115], v[134:135]
	v_pk_fma_f32 v[134:135], v[116:117], v[116:117], v[134:135]
	v_pk_fma_f32 v[134:135], v[118:119], v[118:119], v[134:135]
	v_pk_fma_f32 v[134:135], v[120:121], v[120:121], v[134:135]
	v_pk_fma_f32 v[134:135], v[122:123], v[122:123], v[134:135]
	v_pk_fma_f32 v[134:135], v[124:125], v[124:125], v[134:135]
	v_pk_fma_f32 v[134:135], v[126:127], v[126:127], v[134:135]
	s_nop 0
	v_add_f32_e32 v134, v134, v135
	s_nop 1
	v_add_f32_dpp v132, v132, v132 quad_perm:[1,0,3,2] row_mask:0xf bank_mask:0xf
	v_add_f32_dpp v134, v134, v134 quad_perm:[1,0,3,2] row_mask:0xf bank_mask:0xf
	s_nop 0
	v_add_f32_dpp v132, v132, v132 quad_perm:[2,3,0,1] row_mask:0xf bank_mask:0xf
	v_add_f32_dpp v134, v134, v134 quad_perm:[2,3,0,1] row_mask:0xf bank_mask:0xf
	s_nop 0
	v_add_f32_dpp v132, v132, v132 row_half_mirror row_mask:0xf bank_mask:0xf
	v_add_f32_dpp v134, v134, v134 row_half_mirror row_mask:0xf bank_mask:0xf
	s_nop 0
	v_add_f32_dpp v132, v132, v132 row_mirror row_mask:0xf bank_mask:0xf
	v_add_f32_dpp v134, v134, v134 row_mirror row_mask:0xf bank_mask:0xf
	s_nop 0
	ds_bpermute_b32 v136, v187, v132
	ds_bpermute_b32 v137, v187, v134
	s_waitcnt lgkmcnt(0)
	v_add_f32_e32 v132, v132, v136
	v_add_f32_e32 v134, v134, v137
	ds_bpermute_b32 v136, v188, v132
	ds_bpermute_b32 v137, v188, v134
	s_waitcnt lgkmcnt(0)
	v_add_f32_e32 v132, v132, v136
	v_add_f32_e32 v134, v134, v137
	v_fmamk_f32 v164, v132, 0x3a800000, v138
	v_fmamk_f32 v167, v134, 0x3a800000, v138
	s_nop 0
	v_rsq_f32_e32 v132, v164
	v_rsq_f32_e32 v134, v167
	v_sqrt_f32_e32 v165, v164
	v_sqrt_f32_e32 v168, v167
	s_nop 1
	v_pk_mul_f32 v[140:141], v[96:97], v[132:133] op_sel_hi:[1,0]
	v_cvt_pk_bf16_f32 v148, v140, v141
	v_pk_mul_f32 v[142:143], v[98:99], v[132:133] op_sel_hi:[1,0]
	v_cvt_pk_bf16_f32 v149, v142, v143
	v_pk_mul_f32 v[144:145], v[100:101], v[132:133] op_sel_hi:[1,0]
	v_cvt_pk_bf16_f32 v150, v144, v145
	v_pk_mul_f32 v[146:147], v[102:103], v[132:133] op_sel_hi:[1,0]
	v_cvt_pk_bf16_f32 v151, v146, v147
	v_pk_mul_f32 v[140:141], v[104:105], v[132:133] op_sel_hi:[1,0]
	v_cvt_pk_bf16_f32 v152, v140, v141
	v_pk_mul_f32 v[142:143], v[106:107], v[132:133] op_sel_hi:[1,0]
	v_cvt_pk_bf16_f32 v153, v142, v143
	v_pk_mul_f32 v[144:145], v[108:109], v[132:133] op_sel_hi:[1,0]
	v_cvt_pk_bf16_f32 v154, v144, v145
	v_pk_mul_f32 v[146:147], v[110:111], v[132:133] op_sel_hi:[1,0]
	v_cvt_pk_bf16_f32 v155, v146, v147
	global_store_dwordx4 v173, v[148:151], s[98:99]
	global_store_dwordx4 v173, v[152:155], s[98:99] offset:1024
	v_add_u32_e32 v173, 0x400000, v173
	v_pk_mul_f32 v[140:141], v[112:113], v[134:135] op_sel_hi:[1,0]
	v_cvt_pk_bf16_f32 v156, v140, v141
	v_pk_mul_f32 v[142:143], v[114:115], v[134:135] op_sel_hi:[1,0]
	v_cvt_pk_bf16_f32 v157, v142, v143
	v_pk_mul_f32 v[144:145], v[116:117], v[134:135] op_sel_hi:[1,0]
	v_cvt_pk_bf16_f32 v158, v144, v145
	v_pk_mul_f32 v[146:147], v[118:119], v[134:135] op_sel_hi:[1,0]
	v_cvt_pk_bf16_f32 v159, v146, v147
	v_pk_mul_f32 v[140:141], v[120:121], v[134:135] op_sel_hi:[1,0]
	v_cvt_pk_bf16_f32 v160, v140, v141
	v_pk_mul_f32 v[142:143], v[122:123], v[134:135] op_sel_hi:[1,0]
	v_cvt_pk_bf16_f32 v161, v142, v143
	v_pk_mul_f32 v[144:145], v[124:125], v[134:135] op_sel_hi:[1,0]
;     __device__ __forceinline__ float* out() const { return (float*)karg_in(33); }
; __device__ __forceinline__ const float* xrow_ptr(const Ctx& C, int row) { return row < MPROMPT ? C.in(0) + (size_t)row * DM : C.in(1) + (size_t)(row - MPROMPT) * DM; }
; template <int R, bool BASE_F32, bool OUT_F32>
; __device__ __forceinline__ void rows_res(const Ctx& C, int m0, int stride, int mx, const float* gpost, float scale, int lane) {
;     ...
;     for (int r = 0; r < R; ++r) { mr[r] = (r == 4) ? mx : m0 + r * stride; ok[r] = (r == 4) ? (mx < M) : (mr[r] < MPROMPT); const int mm = ok[r] ? mr[r] : 0;
; #pragma unroll
;         for (int j = 0; j < 4; ++j) d[r][j] = ld4_bf16(D + (size_t)mm * DM + 4 * lane + 256 * j);
;         if (BASE_F32) { const float* x = xrow_ptr(C, mm);
; #pragma unroll
;             for (int j = 0; j < 4; ++j) b[r][j] = ld4_f32(x + 4 * lane + 256 * j);
;         } else { const float inv = C.RS()[mm];
; #pragma unroll
;             for (int j = 0; j < 4; ++j) b[r][j] = ld4_bf16(XN + (size_t)mm * DM + 4 * lane + 256 * j) * inv;
;         } }
; #pragma unroll
;     for (int r = 0; r < R; ++r) { float s = 0.f;
; #pragma unroll
;         for (int j = 0; j < 4; ++j) s += ssq4(d[r][j]);
;         r1[r] = s; }
; #pragma unroll
;     for (int r = 0; r < R; ++r) r1[r] = rsqrtf(wave_sum(r1[r]) * (1.f / DM) + EPS) * scale;
; #pragma unroll
;     for (int j = 0; j < 4; ++j) { const v4f gp = ld4_f32(gpost + 4 * lane + 256 * j);
; #pragma unroll
;         for (int r = 0; r < R; ++r) d[r][j] = b[r][j] + d[r][j] * r1[r] * gp; }
;     if (OUT_F32) { float* Y = C.out();
; #pragma unroll
;         for (int r = 0; r < R; ++r)
; #pragma unroll
;             for (int j = 0; j < 4; ++j) if (ok[r]) *(v4f*)(Y + (size_t)mr[r] * DM + 4 * lane + 256 * j) = d[r][j];
;     } else { float* rs = C.RS(); float t[R];
; #pragma unroll
;         for (int r = 0; r < R; ++r) { float s = 0.f;
; #pragma unroll
;             for (int j = 0; j < 4; ++j) s += ssq4(d[r][j]);
;             t[r] = s; }
; #pragma unroll
;         for (int r = 0; r < R; ++r) t[r] = wave_sum(t[r]) * (1.f / DM) + EPS;
; #pragma unroll
;         for (int r = 0; r < R; ++r) { const float rstd = rsqrtf(t[r]);
; #pragma unroll
;             for (int j = 0; j < 4; ++j) if (ok[r]) st4_bf16(XN + (size_t)mr[r] * DM + 4 * lane + 256 * j, d[r][j] * rstd);
;             if (lane == 0 && ok[r]) rs[mr[r]] = sqrtf(t[r]); }
	v_cvt_pk_bf16_f32 v162, v144, v145
	v_pk_mul_f32 v[146:147], v[126:127], v[134:135] op_sel_hi:[1,0]
	v_cvt_pk_bf16_f32 v163, v146, v147
	global_store_dwordx4 v173, v[156:159], s[98:99]
	global_store_dwordx4 v173, v[160:163], s[98:99] offset:1024
	v_add_u32_e32 v173, 0x400000, v173
	v_add_u32_e32 v166, -1, v165
	v_fma_f32 v140, -v166, v165, v164
	v_cmp_ge_f32_e32 vcc, 0, v140
	v_add_u32_e32 v141, 1, v165
	v_cndmask_b32_e32 v166, v165, v166, vcc
	v_fma_f32 v140, -v141, v165, v164
	v_cmp_lt_f32_e32 vcc, 0, v140
	s_nop 1
	v_cndmask_b32_e32 v165, v166, v141, vcc
	v_add_u32_e32 v169, -1, v168
	v_fma_f32 v142, -v169, v168, v167
	v_cmp_ge_f32_e32 vcc, 0, v142
	v_add_u32_e32 v143, 1, v168
	v_cndmask_b32_e32 v169, v168, v169, vcc
	v_fma_f32 v142, -v143, v168, v167
	v_cmp_lt_f32_e32 vcc, 0, v142
	s_nop 1
	v_cndmask_b32_e32 v168, v169, v143, vcc
	s_mov_b64 exec, 1
	global_store_dword v174, v165, s[98:99]
	v_add_u32_e32 v174, 0x2000, v174
	global_store_dword v174, v168, s[98:99]
	v_add_u32_e32 v174, 0x2000, v174
	s_mov_b64 exec, -1
	global_load_dword v12, v172, s[98:99]
	global_load_dwordx4 v[208:211], v170, s[98:99]
	global_load_dwordx4 v[212:215], v170, s[98:99] offset:1024
	global_load_dwordx4 v[224:227], v171, s[98:99]
	global_load_dwordx4 v[228:231], v171, s[98:99] offset:1024
	v_add_u32_e32 v170, 0x400000, v170
	v_add_u32_e32 v171, 0x400000, v171
	v_add_u32_e32 v172, 0x2000, v172
	global_load_dword v14, v172, s[98:99]
	global_load_dwordx4 v[216:219], v170, s[98:99]
	global_load_dwordx4 v[220:223], v170, s[98:99] offset:1024
	global_load_dwordx4 v[4:7], v171, s[98:99]
	global_load_dwordx4 v[8:11], v171, s[98:99] offset:1024
	v_add_u32_e32 v170, 0x400000, v170
	v_add_u32_e32 v171, 0x400000, v171
	v_add_u32_e32 v172, 0x2000, v172
	s_waitcnt vmcnt(39)
	v_lshlrev_b32_e32 v96, 16, v20
	v_and_b32_e32 v97, 0xffff0000, v20
	v_lshlrev_b32_e32 v98, 16, v21
	v_and_b32_e32 v99, 0xffff0000, v21
	v_lshlrev_b32_e32 v100, 16, v22
	v_and_b32_e32 v101, 0xffff0000, v22
	v_lshlrev_b32_e32 v102, 16, v23
	v_and_b32_e32 v103, 0xffff0000, v23
	v_lshlrev_b32_e32 v104, 16, v24
	v_and_b32_e32 v105, 0xffff0000, v24
	v_lshlrev_b32_e32 v106, 16, v25
	v_and_b32_e32 v107, 0xffff0000, v25
	v_lshlrev_b32_e32 v108, 16, v26
	v_and_b32_e32 v109, 0xffff0000, v26
	v_lshlrev_b32_e32 v110, 16, v27
	v_and_b32_e32 v111, 0xffff0000, v27
	v_pk_mul_f32 v[128:129], v[96:97], v[96:97]
	v_pk_fma_f32 v[128:129], v[98:99], v[98:99], v[128:129]
	v_pk_fma_f32 v[128:129], v[100:101], v[100:101], v[128:129]
	v_pk_fma_f32 v[128:129], v[102:103], v[102:103], v[128:129]
	v_pk_fma_f32 v[128:129], v[104:105], v[104:105], v[128:129]
	v_pk_fma_f32 v[128:129], v[106:107], v[106:107], v[128:129]
	v_pk_fma_f32 v[128:129], v[108:109], v[108:109], v[128:129]
	v_pk_fma_f32 v[128:129], v[110:111], v[110:111], v[128:129]
	s_nop 0
	v_add_f32_e32 v128, v128, v129
	s_waitcnt vmcnt(34)
	v_lshlrev_b32_e32 v112, 16, v28
	v_and_b32_e32 v113, 0xffff0000, v28
	v_lshlrev_b32_e32 v114, 16, v29
	v_and_b32_e32 v115, 0xffff0000, v29
	v_lshlrev_b32_e32 v116, 16, v30
	v_and_b32_e32 v117, 0xffff0000, v30
	v_lshlrev_b32_e32 v118, 16, v31
	v_and_b32_e32 v119, 0xffff0000, v31
	v_lshlrev_b32_e32 v120, 16, v32
	v_and_b32_e32 v121, 0xffff0000, v32
	v_lshlrev_b32_e32 v122, 16, v33
	v_and_b32_e32 v123, 0xffff0000, v33
	v_lshlrev_b32_e32 v124, 16, v34
	v_and_b32_e32 v125, 0xffff0000, v34
	v_lshlrev_b32_e32 v126, 16, v35
	v_and_b32_e32 v127, 0xffff0000, v35
	v_pk_mul_f32 v[130:131], v[112:113], v[112:113]
	v_pk_fma_f32 v[130:131], v[114:115], v[114:115], v[130:131]
	v_pk_fma_f32 v[130:131], v[116:117], v[116:117], v[130:131]
	v_pk_fma_f32 v[130:131], v[118:119], v[118:119], v[130:131]
	v_pk_fma_f32 v[130:131], v[120:121], v[120:121], v[130:131]
	v_pk_fma_f32 v[130:131], v[122:123], v[122:123], v[130:131]
	v_pk_fma_f32 v[130:131], v[124:125], v[124:125], v[130:131]
	v_pk_fma_f32 v[130:131], v[126:127], v[126:127], v[130:131]
	s_nop 0
	v_add_f32_e32 v130, v130, v131
	s_nop 1
	v_add_f32_dpp v128, v128, v128 quad_perm:[1,0,3,2] row_mask:0xf bank_mask:0xf
	v_add_f32_dpp v130, v130, v130 quad_perm:[1,0,3,2] row_mask:0xf bank_mask:0xf
	s_nop 0
	v_add_f32_dpp v128, v128, v128 quad_perm:[2,3,0,1] row_mask:0xf bank_mask:0xf
	v_add_f32_dpp v130, v130, v130 quad_perm:[2,3,0,1] row_mask:0xf bank_mask:0xf
	s_nop 0
	v_add_f32_dpp v128, v128, v128 row_half_mirror row_mask:0xf bank_mask:0xf
	v_add_f32_dpp v130, v130, v130 row_half_mirror row_mask:0xf bank_mask:0xf
	s_nop 0
	v_add_f32_dpp v128, v128, v128 row_mirror row_mask:0xf bank_mask:0xf
	v_add_f32_dpp v130, v130, v130 row_mirror row_mask:0xf bank_mask:0xf
	s_nop 0
	ds_bpermute_b32 v136, v187, v128
	ds_bpermute_b32 v137, v187, v130
	s_waitcnt lgkmcnt(0)
	v_add_f32_e32 v128, v128, v136
	v_add_f32_e32 v130, v130, v137
	ds_bpermute_b32 v136, v188, v128
	ds_bpermute_b32 v137, v188, v130
	s_waitcnt lgkmcnt(0)
	v_add_f32_e32 v128, v128, v136
	v_add_f32_e32 v130, v130, v137
	v_fmamk_f32 v128, v128, 0x3a800000, v138
	v_fmamk_f32 v130, v130, 0x3a800000, v138
	s_nop 0
	v_rsq_f32_e32 v128, v128
	v_rsq_f32_e32 v130, v130
	s_nop 1
	s_waitcnt vmcnt(32)
;     __device__ __forceinline__ float* out() const { return (float*)karg_in(33); }
; __device__ __forceinline__ float ssq4(v4f v) { return (v.x * v.x + v.y * v.y) + (v.z * v.z + v.w * v.w); }
; template <int R, bool BASE_F32, bool OUT_F32>
; __device__ __forceinline__ void rows_res(const Ctx& C, int m0, int stride, int mx, const float* gpost, float scale, int lane) {
;     ...
;     for (int r = 0; r < R; ++r) r1[r] = rsqrtf(wave_sum(r1[r]) * (1.f / DM) + EPS) * scale;
; #pragma unroll
;     for (int j = 0; j < 4; ++j) { const v4f gp = ld4_f32(gpost + 4 * lane + 256 * j);
; #pragma unroll
;         for (int r = 0; r < R; ++r) d[r][j] = b[r][j] + d[r][j] * r1[r] * gp; }
;     if (OUT_F32) { float* Y = C.out();
; #pragma unroll
;         for (int r = 0; r < R; ++r)
; #pragma unroll
;             for (int j = 0; j < 4; ++j) if (ok[r]) *(v4f*)(Y + (size_t)mr[r] * DM + 4 * lane + 256 * j) = d[r][j];
;     } else { float* rs = C.RS(); float t[R];
; #pragma unroll
;         for (int r = 0; r < R; ++r) { float s = 0.f;
; #pragma unroll
;             for (int j = 0; j < 4; ++j) s += ssq4(d[r][j]);
;             t[r] = s; }
	v_pk_mul_f32 v[96:97], v[128:129], v[96:97] op_sel_hi:[0,1]
	v_pk_mul_f32 v[98:99], v[128:129], v[98:99] op_sel_hi:[0,1]
	v_pk_mul_f32 v[100:101], v[128:129], v[100:101] op_sel_hi:[0,1]
	v_pk_mul_f32 v[102:103], v[128:129], v[102:103] op_sel_hi:[0,1]
	v_pk_mul_f32 v[104:105], v[128:129], v[104:105] op_sel_hi:[0,1]
	v_pk_mul_f32 v[106:107], v[128:129], v[106:107] op_sel_hi:[0,1]
	v_pk_mul_f32 v[108:109], v[128:129], v[108:109] op_sel_hi:[0,1]
	v_pk_mul_f32 v[110:111], v[128:129], v[110:111] op_sel_hi:[0,1]
	v_pk_mul_f32 v[96:97], v[96:97], v[192:193]
	v_pk_mul_f32 v[98:99], v[98:99], v[194:195]
	v_pk_mul_f32 v[100:101], v[100:101], v[196:197]
	v_pk_mul_f32 v[102:103], v[102:103], v[198:199]
	v_pk_mul_f32 v[104:105], v[104:105], v[200:201]
	v_pk_mul_f32 v[106:107], v[106:107], v[202:203]
	v_pk_mul_f32 v[108:109], v[108:109], v[204:205]
	v_pk_mul_f32 v[110:111], v[110:111], v[206:207]
	v_lshlrev_b32_e32 v20, 16, v36
	v_and_b32_e32 v21, 0xffff0000, v36
	v_lshlrev_b32_e32 v22, 16, v37
	v_and_b32_e32 v23, 0xffff0000, v37
	v_lshlrev_b32_e32 v24, 16, v38
	v_and_b32_e32 v25, 0xffff0000, v38
	v_lshlrev_b32_e32 v26, 16, v39
	v_and_b32_e32 v27, 0xffff0000, v39
	v_pk_fma_f32 v[96:97], v[52:53], v[20:21], v[96:97] op_sel_hi:[0,1,1]
	v_pk_fma_f32 v[98:99], v[52:53], v[22:23], v[98:99] op_sel_hi:[0,1,1]
	v_pk_fma_f32 v[100:101], v[52:53], v[24:25], v[100:101] op_sel_hi:[0,1,1]
	v_pk_fma_f32 v[102:103], v[52:53], v[26:27], v[102:103] op_sel_hi:[0,1,1]
	v_lshlrev_b32_e32 v20, 16, v40
	v_and_b32_e32 v21, 0xffff0000, v40
	v_lshlrev_b32_e32 v22, 16, v41
	v_and_b32_e32 v23, 0xffff0000, v41
	v_lshlrev_b32_e32 v24, 16, v42
	v_and_b32_e32 v25, 0xffff0000, v42
	v_lshlrev_b32_e32 v26, 16, v43
	v_and_b32_e32 v27, 0xffff0000, v43
	v_pk_fma_f32 v[104:105], v[52:53], v[20:21], v[104:105] op_sel_hi:[0,1,1]
	v_pk_fma_f32 v[106:107], v[52:53], v[22:23], v[106:107] op_sel_hi:[0,1,1]
	v_pk_fma_f32 v[108:109], v[52:53], v[24:25], v[108:109] op_sel_hi:[0,1,1]
	v_pk_fma_f32 v[110:111], v[52:53], v[26:27], v[110:111] op_sel_hi:[0,1,1]
	v_pk_mul_f32 v[132:133], v[96:97], v[96:97]
	v_pk_fma_f32 v[132:133], v[98:99], v[98:99], v[132:133]
	v_pk_fma_f32 v[132:133], v[100:101], v[100:101], v[132:133]
	v_pk_fma_f32 v[132:133], v[102:103], v[102:103], v[132:133]
	v_pk_fma_f32 v[132:133], v[104:105], v[104:105], v[132:133]
	v_pk_fma_f32 v[132:133], v[106:107], v[106:107], v[132:133]
	v_pk_fma_f32 v[132:133], v[108:109], v[108:109], v[132:133]
	v_pk_fma_f32 v[132:133], v[110:111], v[110:111], v[132:133]
	s_nop 0
	v_add_f32_e32 v132, v132, v133
	v_pk_mul_f32 v[112:113], v[130:131], v[112:113] op_sel_hi:[0,1]
	v_pk_mul_f32 v[114:115], v[130:131], v[114:115] op_sel_hi:[0,1]
	v_pk_mul_f32 v[116:117], v[130:131], v[116:117] op_sel_hi:[0,1]
	v_pk_mul_f32 v[118:119], v[130:131], v[118:119] op_sel_hi:[0,1]
	v_pk_mul_f32 v[120:121], v[130:131], v[120:121] op_sel_hi:[0,1]
	v_pk_mul_f32 v[122:123], v[130:131], v[122:123] op_sel_hi:[0,1]
	v_pk_mul_f32 v[124:125], v[130:131], v[124:125] op_sel_hi:[0,1]
	v_pk_mul_f32 v[126:127], v[130:131], v[126:127] op_sel_hi:[0,1]
	v_pk_mul_f32 v[112:113], v[112:113], v[192:193]
	v_pk_mul_f32 v[114:115], v[114:115], v[194:195]
	v_pk_mul_f32 v[116:117], v[116:117], v[196:197]
	v_pk_mul_f32 v[118:119], v[118:119], v[198:199]
	v_pk_mul_f32 v[120:121], v[120:121], v[200:201]
	v_pk_mul_f32 v[122:123], v[122:123], v[202:203]
	v_pk_mul_f32 v[124:125], v[124:125], v[204:205]
	v_pk_mul_f32 v[126:127], v[126:127], v[206:207]
	v_lshlrev_b32_e32 v28, 16, v44
	v_and_b32_e32 v29, 0xffff0000, v44
	v_lshlrev_b32_e32 v30, 16, v45
	v_and_b32_e32 v31, 0xffff0000, v45
	v_lshlrev_b32_e32 v32, 16, v46
	v_and_b32_e32 v33, 0xffff0000, v46
	v_lshlrev_b32_e32 v34, 16, v47
	v_and_b32_e32 v35, 0xffff0000, v47
	v_pk_fma_f32 v[112:113], v[54:55], v[28:29], v[112:113] op_sel_hi:[0,1,1]
	v_pk_fma_f32 v[114:115], v[54:55], v[30:31], v[114:115] op_sel_hi:[0,1,1]
	v_pk_fma_f32 v[116:117], v[54:55], v[32:33], v[116:117] op_sel_hi:[0,1,1]
	v_pk_fma_f32 v[118:119], v[54:55], v[34:35], v[118:119] op_sel_hi:[0,1,1]
	v_lshlrev_b32_e32 v28, 16, v48
	v_and_b32_e32 v29, 0xffff0000, v48
	v_lshlrev_b32_e32 v30, 16, v49
	v_and_b32_e32 v31, 0xffff0000, v49
	v_lshlrev_b32_e32 v32, 16, v50
	v_and_b32_e32 v33, 0xffff0000, v50
	v_lshlrev_b32_e32 v34, 16, v51
	v_and_b32_e32 v35, 0xffff0000, v51
	v_pk_fma_f32 v[120:121], v[54:55], v[28:29], v[120:121] op_sel_hi:[0,1,1]
	v_pk_fma_f32 v[122:123], v[54:55], v[30:31], v[122:123] op_sel_hi:[0,1,1]
	v_pk_fma_f32 v[124:125], v[54:55], v[32:33], v[124:125] op_sel_hi:[0,1,1]
	v_pk_fma_f32 v[126:127], v[54:55], v[34:35], v[126:127] op_sel_hi:[0,1,1]
	v_pk_mul_f32 v[134:135], v[112:113], v[112:113]
	v_pk_fma_f32 v[134:135], v[114:115], v[114:115], v[134:135]
	v_pk_fma_f32 v[134:135], v[116:117], v[116:117], v[134:135]
	v_pk_fma_f32 v[134:135], v[118:119], v[118:119], v[134:135]
	v_pk_fma_f32 v[134:135], v[120:121], v[120:121], v[134:135]
	v_pk_fma_f32 v[134:135], v[122:123], v[122:123], v[134:135]
	v_pk_fma_f32 v[134:135], v[124:125], v[124:125], v[134:135]
	v_pk_fma_f32 v[134:135], v[126:127], v[126:127], v[134:135]
	s_nop 0
	v_add_f32_e32 v134, v134, v135
	s_nop 1
	v_add_f32_dpp v132, v132, v132 quad_perm:[1,0,3,2] row_mask:0xf bank_mask:0xf
	v_add_f32_dpp v134, v134, v134 quad_perm:[1,0,3,2] row_mask:0xf bank_mask:0xf
	s_nop 0
	v_add_f32_dpp v132, v132, v132 quad_perm:[2,3,0,1] row_mask:0xf bank_mask:0xf
	v_add_f32_dpp v134, v134, v134 quad_perm:[2,3,0,1] row_mask:0xf bank_mask:0xf
	s_nop 0
	v_add_f32_dpp v132, v132, v132 row_half_mirror row_mask:0xf bank_mask:0xf
	v_add_f32_dpp v134, v134, v134 row_half_mirror row_mask:0xf bank_mask:0xf
	s_nop 0
	v_add_f32_dpp v132, v132, v132 row_mirror row_mask:0xf bank_mask:0xf
	v_add_f32_dpp v134, v134, v134 row_mirror row_mask:0xf bank_mask:0xf
	s_nop 0
	ds_bpermute_b32 v136, v187, v132
	ds_bpermute_b32 v137, v187, v134
	s_waitcnt lgkmcnt(0)
;     __device__ __forceinline__ float* out() const { return (float*)karg_in(33); }
; __device__ __forceinline__ void st4_bf16(bf16* p, v4f o) { v2u w; w.x = cvt_pk_nv(o.x, o.y); w.y = cvt_pk_nv(o.z, o.w); *(v2u*)p = w; }
; __device__ __forceinline__ float ssq4(v4f v) { return (v.x * v.x + v.y * v.y) + (v.z * v.z + v.w * v.w); }
; template <int R, bool BASE_F32, bool OUT_F32>
; __device__ __forceinline__ void rows_res(const Ctx& C, int m0, int stride, int mx, const float* gpost, float scale, int lane) {
;     ...
;     for (int r = 0; r < R; ++r) { float s = 0.f;
; #pragma unroll
;         for (int j = 0; j < 4; ++j) s += ssq4(d[r][j]);
;         r1[r] = s; }
; #pragma unroll
;     for (int r = 0; r < R; ++r) r1[r] = rsqrtf(wave_sum(r1[r]) * (1.f / DM) + EPS) * scale;
; #pragma unroll
;     for (int j = 0; j < 4; ++j) { const v4f gp = ld4_f32(gpost + 4 * lane + 256 * j);
; #pragma unroll
;         for (int r = 0; r < R; ++r) d[r][j] = b[r][j] + d[r][j] * r1[r] * gp; }
;     if (OUT_F32) { float* Y = C.out();
; #pragma unroll
;         for (int r = 0; r < R; ++r)
; #pragma unroll
;             for (int j = 0; j < 4; ++j) if (ok[r]) *(v4f*)(Y + (size_t)mr[r] * DM + 4 * lane + 256 * j) = d[r][j];
;     } else { float* rs = C.RS(); float t[R];
; #pragma unroll
;         for (int r = 0; r < R; ++r) { float s = 0.f;
; #pragma unroll
;             for (int j = 0; j < 4; ++j) s += ssq4(d[r][j]);
;             t[r] = s; }
; #pragma unroll
;         for (int r = 0; r < R; ++r) t[r] = wave_sum(t[r]) * (1.f / DM) + EPS;
; #pragma unroll
;         for (int r = 0; r < R; ++r) { const float rstd = rsqrtf(t[r]);
; #pragma unroll
;             for (int j = 0; j < 4; ++j) if (ok[r]) st4_bf16(XN + (size_t)mr[r] * DM + 4 * lane + 256 * j, d[r][j] * rstd);
;             if (lane == 0 && ok[r]) rs[mr[r]] = sqrtf(t[r]); }
	v_add_f32_e32 v132, v132, v136
	v_add_f32_e32 v134, v134, v137
	ds_bpermute_b32 v136, v188, v132
	ds_bpermute_b32 v137, v188, v134
	s_waitcnt lgkmcnt(0)
	v_add_f32_e32 v132, v132, v136
	v_add_f32_e32 v134, v134, v137
	v_fmamk_f32 v164, v132, 0x3a800000, v138
	v_fmamk_f32 v167, v134, 0x3a800000, v138
	s_nop 0
	v_rsq_f32_e32 v132, v164
	v_rsq_f32_e32 v134, v167
	v_sqrt_f32_e32 v165, v164
	v_sqrt_f32_e32 v168, v167
	s_nop 1
	v_pk_mul_f32 v[140:141], v[96:97], v[132:133] op_sel_hi:[1,0]
	v_cvt_pk_bf16_f32 v148, v140, v141
	v_pk_mul_f32 v[142:143], v[98:99], v[132:133] op_sel_hi:[1,0]
	v_cvt_pk_bf16_f32 v149, v142, v143
	v_pk_mul_f32 v[144:145], v[100:101], v[132:133] op_sel_hi:[1,0]
	v_cvt_pk_bf16_f32 v150, v144, v145
	v_pk_mul_f32 v[146:147], v[102:103], v[132:133] op_sel_hi:[1,0]
	v_cvt_pk_bf16_f32 v151, v146, v147
	v_pk_mul_f32 v[140:141], v[104:105], v[132:133] op_sel_hi:[1,0]
	v_cvt_pk_bf16_f32 v152, v140, v141
	v_pk_mul_f32 v[142:143], v[106:107], v[132:133] op_sel_hi:[1,0]
	v_cvt_pk_bf16_f32 v153, v142, v143
	v_pk_mul_f32 v[144:145], v[108:109], v[132:133] op_sel_hi:[1,0]
	v_cvt_pk_bf16_f32 v154, v144, v145
	v_pk_mul_f32 v[146:147], v[110:111], v[132:133] op_sel_hi:[1,0]
	v_cvt_pk_bf16_f32 v155, v146, v147
	global_store_dwordx4 v173, v[148:151], s[98:99]
	global_store_dwordx4 v173, v[152:155], s[98:99] offset:1024
	v_add_u32_e32 v173, 0x400000, v173
	v_pk_mul_f32 v[140:141], v[112:113], v[134:135] op_sel_hi:[1,0]
	v_cvt_pk_bf16_f32 v156, v140, v141
	v_pk_mul_f32 v[142:143], v[114:115], v[134:135] op_sel_hi:[1,0]
	v_cvt_pk_bf16_f32 v157, v142, v143
	v_pk_mul_f32 v[144:145], v[116:117], v[134:135] op_sel_hi:[1,0]
	v_cvt_pk_bf16_f32 v158, v144, v145
	v_pk_mul_f32 v[146:147], v[118:119], v[134:135] op_sel_hi:[1,0]
	v_cvt_pk_bf16_f32 v159, v146, v147
	v_pk_mul_f32 v[140:141], v[120:121], v[134:135] op_sel_hi:[1,0]
	v_cvt_pk_bf16_f32 v160, v140, v141
	v_pk_mul_f32 v[142:143], v[122:123], v[134:135] op_sel_hi:[1,0]
	v_cvt_pk_bf16_f32 v161, v142, v143
	v_pk_mul_f32 v[144:145], v[124:125], v[134:135] op_sel_hi:[1,0]
	v_cvt_pk_bf16_f32 v162, v144, v145
	v_pk_mul_f32 v[146:147], v[126:127], v[134:135] op_sel_hi:[1,0]
	v_cvt_pk_bf16_f32 v163, v146, v147
	global_store_dwordx4 v173, v[156:159], s[98:99]
	global_store_dwordx4 v173, v[160:163], s[98:99] offset:1024
	v_add_u32_e32 v173, 0x400000, v173
	v_add_u32_e32 v166, -1, v165
	v_fma_f32 v140, -v166, v165, v164
	v_cmp_ge_f32_e32 vcc, 0, v140
	v_add_u32_e32 v141, 1, v165
	v_cndmask_b32_e32 v166, v165, v166, vcc
	v_fma_f32 v140, -v141, v165, v164
	v_cmp_lt_f32_e32 vcc, 0, v140
	s_nop 1
	v_cndmask_b32_e32 v165, v166, v141, vcc
	v_add_u32_e32 v169, -1, v168
	v_fma_f32 v142, -v169, v168, v167
	v_cmp_ge_f32_e32 vcc, 0, v142
	v_add_u32_e32 v143, 1, v168
	v_cndmask_b32_e32 v169, v168, v169, vcc
	v_fma_f32 v142, -v143, v168, v167
	v_cmp_lt_f32_e32 vcc, 0, v142
	s_nop 1
	v_cndmask_b32_e32 v168, v169, v143, vcc
	s_mov_b64 exec, 1
	global_store_dword v174, v165, s[98:99]
	v_add_u32_e32 v174, 0x2000, v174
	global_store_dword v174, v168, s[98:99]
	v_add_u32_e32 v174, 0x2000, v174
	s_mov_b64 exec, -1
	s_waitcnt vmcnt(29)
	v_lshlrev_b32_e32 v96, 16, v56
	v_and_b32_e32 v97, 0xffff0000, v56
	v_lshlrev_b32_e32 v98, 16, v57
	v_and_b32_e32 v99, 0xffff0000, v57
	v_lshlrev_b32_e32 v100, 16, v58
	v_and_b32_e32 v101, 0xffff0000, v58
	v_lshlrev_b32_e32 v102, 16, v59
	v_and_b32_e32 v103, 0xffff0000, v59
	v_lshlrev_b32_e32 v104, 16, v60
	v_and_b32_e32 v105, 0xffff0000, v60
	v_lshlrev_b32_e32 v106, 16, v61
	v_and_b32_e32 v107, 0xffff0000, v61
	v_lshlrev_b32_e32 v108, 16, v62
	v_and_b32_e32 v109, 0xffff0000, v62
	v_lshlrev_b32_e32 v110, 16, v63
	v_and_b32_e32 v111, 0xffff0000, v63
	v_pk_mul_f32 v[128:129], v[96:97], v[96:97]
	v_pk_fma_f32 v[128:129], v[98:99], v[98:99], v[128:129]
	v_pk_fma_f32 v[128:129], v[100:101], v[100:101], v[128:129]
	v_pk_fma_f32 v[128:129], v[102:103], v[102:103], v[128:129]
	v_pk_fma_f32 v[128:129], v[104:105], v[104:105], v[128:129]
	v_pk_fma_f32 v[128:129], v[106:107], v[106:107], v[128:129]
	v_pk_fma_f32 v[128:129], v[108:109], v[108:109], v[128:129]
	v_pk_fma_f32 v[128:129], v[110:111], v[110:111], v[128:129]
	s_nop 0
	v_add_f32_e32 v128, v128, v129
	s_waitcnt vmcnt(24)
	v_lshlrev_b32_e32 v112, 16, v64
	v_and_b32_e32 v113, 0xffff0000, v64
	v_lshlrev_b32_e32 v114, 16, v65
	v_and_b32_e32 v115, 0xffff0000, v65
	v_lshlrev_b32_e32 v116, 16, v66
	v_and_b32_e32 v117, 0xffff0000, v66
	v_lshlrev_b32_e32 v118, 16, v67
	v_and_b32_e32 v119, 0xffff0000, v67
	v_lshlrev_b32_e32 v120, 16, v68
	v_and_b32_e32 v121, 0xffff0000, v68
	v_lshlrev_b32_e32 v122, 16, v69
	v_and_b32_e32 v123, 0xffff0000, v69
	v_lshlrev_b32_e32 v124, 16, v70
	v_and_b32_e32 v125, 0xffff0000, v70
	v_lshlrev_b32_e32 v126, 16, v71
	v_and_b32_e32 v127, 0xffff0000, v71
	v_pk_mul_f32 v[130:131], v[112:113], v[112:113]
	v_pk_fma_f32 v[130:131], v[114:115], v[114:115], v[130:131]
	v_pk_fma_f32 v[130:131], v[116:117], v[116:117], v[130:131]
	v_pk_fma_f32 v[130:131], v[118:119], v[118:119], v[130:131]
	v_pk_fma_f32 v[130:131], v[120:121], v[120:121], v[130:131]
	v_pk_fma_f32 v[130:131], v[122:123], v[122:123], v[130:131]
	v_pk_fma_f32 v[130:131], v[124:125], v[124:125], v[130:131]
	v_pk_fma_f32 v[130:131], v[126:127], v[126:127], v[130:131]
	s_nop 0
	v_add_f32_e32 v130, v130, v131
	s_nop 1
	v_add_f32_dpp v128, v128, v128 quad_perm:[1,0,3,2] row_mask:0xf bank_mask:0xf
	v_add_f32_dpp v130, v130, v130 quad_perm:[1,0,3,2] row_mask:0xf bank_mask:0xf
	s_nop 0
	v_add_f32_dpp v128, v128, v128 quad_perm:[2,3,0,1] row_mask:0xf bank_mask:0xf
	v_add_f32_dpp v130, v130, v130 quad_perm:[2,3,0,1] row_mask:0xf bank_mask:0xf
	s_nop 0
	v_add_f32_dpp v128, v128, v128 row_half_mirror row_mask:0xf bank_mask:0xf
	v_add_f32_dpp v130, v130, v130 row_half_mirror row_mask:0xf bank_mask:0xf
	s_nop 0
	v_add_f32_dpp v128, v128, v128 row_mirror row_mask:0xf bank_mask:0xf
	v_add_f32_dpp v130, v130, v130 row_mirror row_mask:0xf bank_mask:0xf
	s_nop 0
	ds_bpermute_b32 v136, v187, v128
	ds_bpermute_b32 v137, v187, v130
	s_waitcnt lgkmcnt(0)
;     __device__ __forceinline__ float* out() const { return (float*)karg_in(33); }
; __device__ __forceinline__ float ssq4(v4f v) { return (v.x * v.x + v.y * v.y) + (v.z * v.z + v.w * v.w); }
; template <int R, bool BASE_F32, bool OUT_F32>
; __device__ __forceinline__ void rows_res(const Ctx& C, int m0, int stride, int mx, const float* gpost, float scale, int lane) {
;     ...
;     for (int r = 0; r < R; ++r) r1[r] = rsqrtf(wave_sum(r1[r]) * (1.f / DM) + EPS) * scale;
; #pragma unroll
;     for (int j = 0; j < 4; ++j) { const v4f gp = ld4_f32(gpost + 4 * lane + 256 * j);
; #pragma unroll
;         for (int r = 0; r < R; ++r) d[r][j] = b[r][j] + d[r][j] * r1[r] * gp; }
;     if (OUT_F32) { float* Y = C.out();
; #pragma unroll
;         for (int r = 0; r < R; ++r)
; #pragma unroll
;             for (int j = 0; j < 4; ++j) if (ok[r]) *(v4f*)(Y + (size_t)mr[r] * DM + 4 * lane + 256 * j) = d[r][j];
;     } else { float* rs = C.RS(); float t[R];
; #pragma unroll
;         for (int r = 0; r < R; ++r) { float s = 0.f;
; #pragma unroll
;             for (int j = 0; j < 4; ++j) s += ssq4(d[r][j]);
;             t[r] = s; }
	v_add_f32_e32 v128, v128, v136
	v_add_f32_e32 v130, v130, v137
	ds_bpermute_b32 v136, v188, v128
	ds_bpermute_b32 v137, v188, v130
	s_waitcnt lgkmcnt(0)
	v_add_f32_e32 v128, v128, v136
	v_add_f32_e32 v130, v130, v137
	v_fmamk_f32 v128, v128, 0x3a800000, v138
	v_fmamk_f32 v130, v130, 0x3a800000, v138
	s_nop 0
	v_rsq_f32_e32 v128, v128
	v_rsq_f32_e32 v130, v130
	s_nop 1
	s_waitcnt vmcnt(22)
	v_pk_mul_f32 v[96:97], v[128:129], v[96:97] op_sel_hi:[0,1]
	v_pk_mul_f32 v[98:99], v[128:129], v[98:99] op_sel_hi:[0,1]
	v_pk_mul_f32 v[100:101], v[128:129], v[100:101] op_sel_hi:[0,1]
	v_pk_mul_f32 v[102:103], v[128:129], v[102:103] op_sel_hi:[0,1]
	v_pk_mul_f32 v[104:105], v[128:129], v[104:105] op_sel_hi:[0,1]
	v_pk_mul_f32 v[106:107], v[128:129], v[106:107] op_sel_hi:[0,1]
	v_pk_mul_f32 v[108:109], v[128:129], v[108:109] op_sel_hi:[0,1]
	v_pk_mul_f32 v[110:111], v[128:129], v[110:111] op_sel_hi:[0,1]
	v_pk_mul_f32 v[96:97], v[96:97], v[192:193]
	v_pk_mul_f32 v[98:99], v[98:99], v[194:195]
	v_pk_mul_f32 v[100:101], v[100:101], v[196:197]
	v_pk_mul_f32 v[102:103], v[102:103], v[198:199]
	v_pk_mul_f32 v[104:105], v[104:105], v[200:201]
	v_pk_mul_f32 v[106:107], v[106:107], v[202:203]
	v_pk_mul_f32 v[108:109], v[108:109], v[204:205]
	v_pk_mul_f32 v[110:111], v[110:111], v[206:207]
	v_lshlrev_b32_e32 v56, 16, v72
	v_and_b32_e32 v57, 0xffff0000, v72
	v_lshlrev_b32_e32 v58, 16, v73
	v_and_b32_e32 v59, 0xffff0000, v73
	v_lshlrev_b32_e32 v60, 16, v74
	v_and_b32_e32 v61, 0xffff0000, v74
	v_lshlrev_b32_e32 v62, 16, v75
	v_and_b32_e32 v63, 0xffff0000, v75
	v_pk_fma_f32 v[96:97], v[88:89], v[56:57], v[96:97] op_sel_hi:[0,1,1]
	v_pk_fma_f32 v[98:99], v[88:89], v[58:59], v[98:99] op_sel_hi:[0,1,1]
	v_pk_fma_f32 v[100:101], v[88:89], v[60:61], v[100:101] op_sel_hi:[0,1,1]
	v_pk_fma_f32 v[102:103], v[88:89], v[62:63], v[102:103] op_sel_hi:[0,1,1]
	v_lshlrev_b32_e32 v56, 16, v76
	v_and_b32_e32 v57, 0xffff0000, v76
	v_lshlrev_b32_e32 v58, 16, v77
	v_and_b32_e32 v59, 0xffff0000, v77
	v_lshlrev_b32_e32 v60, 16, v78
	v_and_b32_e32 v61, 0xffff0000, v78
	v_lshlrev_b32_e32 v62, 16, v79
	v_and_b32_e32 v63, 0xffff0000, v79
	v_pk_fma_f32 v[104:105], v[88:89], v[56:57], v[104:105] op_sel_hi:[0,1,1]
	v_pk_fma_f32 v[106:107], v[88:89], v[58:59], v[106:107] op_sel_hi:[0,1,1]
	v_pk_fma_f32 v[108:109], v[88:89], v[60:61], v[108:109] op_sel_hi:[0,1,1]
	v_pk_fma_f32 v[110:111], v[88:89], v[62:63], v[110:111] op_sel_hi:[0,1,1]
	v_pk_mul_f32 v[132:133], v[96:97], v[96:97]
	v_pk_fma_f32 v[132:133], v[98:99], v[98:99], v[132:133]
	v_pk_fma_f32 v[132:133], v[100:101], v[100:101], v[132:133]
	v_pk_fma_f32 v[132:133], v[102:103], v[102:103], v[132:133]
	v_pk_fma_f32 v[132:133], v[104:105], v[104:105], v[132:133]
	v_pk_fma_f32 v[132:133], v[106:107], v[106:107], v[132:133]
	v_pk_fma_f32 v[132:133], v[108:109], v[108:109], v[132:133]
	v_pk_fma_f32 v[132:133], v[110:111], v[110:111], v[132:133]
	s_nop 0
	v_add_f32_e32 v132, v132, v133
	v_pk_mul_f32 v[112:113], v[130:131], v[112:113] op_sel_hi:[0,1]
	v_pk_mul_f32 v[114:115], v[130:131], v[114:115] op_sel_hi:[0,1]
	v_pk_mul_f32 v[116:117], v[130:131], v[116:117] op_sel_hi:[0,1]
	v_pk_mul_f32 v[118:119], v[130:131], v[118:119] op_sel_hi:[0,1]
	v_pk_mul_f32 v[120:121], v[130:131], v[120:121] op_sel_hi:[0,1]
	v_pk_mul_f32 v[122:123], v[130:131], v[122:123] op_sel_hi:[0,1]
	v_pk_mul_f32 v[124:125], v[130:131], v[124:125] op_sel_hi:[0,1]
	v_pk_mul_f32 v[126:127], v[130:131], v[126:127] op_sel_hi:[0,1]
	v_pk_mul_f32 v[112:113], v[112:113], v[192:193]
	v_pk_mul_f32 v[114:115], v[114:115], v[194:195]
	v_pk_mul_f32 v[116:117], v[116:117], v[196:197]
	v_pk_mul_f32 v[118:119], v[118:119], v[198:199]
	v_pk_mul_f32 v[120:121], v[120:121], v[200:201]
	v_pk_mul_f32 v[122:123], v[122:123], v[202:203]
	v_pk_mul_f32 v[124:125], v[124:125], v[204:205]
	v_pk_mul_f32 v[126:127], v[126:127], v[206:207]
	v_lshlrev_b32_e32 v64, 16, v80
	v_and_b32_e32 v65, 0xffff0000, v80
	v_lshlrev_b32_e32 v66, 16, v81
	v_and_b32_e32 v67, 0xffff0000, v81
	v_lshlrev_b32_e32 v68, 16, v82
	v_and_b32_e32 v69, 0xffff0000, v82
	v_lshlrev_b32_e32 v70, 16, v83
	v_and_b32_e32 v71, 0xffff0000, v83
	v_pk_fma_f32 v[112:113], v[90:91], v[64:65], v[112:113] op_sel_hi:[0,1,1]
	v_pk_fma_f32 v[114:115], v[90:91], v[66:67], v[114:115] op_sel_hi:[0,1,1]
	v_pk_fma_f32 v[116:117], v[90:91], v[68:69], v[116:117] op_sel_hi:[0,1,1]
	v_pk_fma_f32 v[118:119], v[90:91], v[70:71], v[118:119] op_sel_hi:[0,1,1]
	v_lshlrev_b32_e32 v64, 16, v84
	v_and_b32_e32 v65, 0xffff0000, v84
	v_lshlrev_b32_e32 v66, 16, v85
	v_and_b32_e32 v67, 0xffff0000, v85
	v_lshlrev_b32_e32 v68, 16, v86
	v_and_b32_e32 v69, 0xffff0000, v86
	v_lshlrev_b32_e32 v70, 16, v87
	v_and_b32_e32 v71, 0xffff0000, v87
	v_pk_fma_f32 v[120:121], v[90:91], v[64:65], v[120:121] op_sel_hi:[0,1,1]
	v_pk_fma_f32 v[122:123], v[90:91], v[66:67], v[122:123] op_sel_hi:[0,1,1]
	v_pk_fma_f32 v[124:125], v[90:91], v[68:69], v[124:125] op_sel_hi:[0,1,1]
	v_pk_fma_f32 v[126:127], v[90:91], v[70:71], v[126:127] op_sel_hi:[0,1,1]
	v_pk_mul_f32 v[134:135], v[112:113], v[112:113]
	v_pk_fma_f32 v[134:135], v[114:115], v[114:115], v[134:135]
	v_pk_fma_f32 v[134:135], v[116:117], v[116:117], v[134:135]
	v_pk_fma_f32 v[134:135], v[118:119], v[118:119], v[134:135]
	v_pk_fma_f32 v[134:135], v[120:121], v[120:121], v[134:135]
	v_pk_fma_f32 v[134:135], v[122:123], v[122:123], v[134:135]
	v_pk_fma_f32 v[134:135], v[124:125], v[124:125], v[134:135]
	v_pk_fma_f32 v[134:135], v[126:127], v[126:127], v[134:135]
	s_nop 0
	v_add_f32_e32 v134, v134, v135
	s_nop 1
	v_add_f32_dpp v132, v132, v132 quad_perm:[1,0,3,2] row_mask:0xf bank_mask:0xf
	v_add_f32_dpp v134, v134, v134 quad_perm:[1,0,3,2] row_mask:0xf bank_mask:0xf
	s_nop 0
	v_add_f32_dpp v132, v132, v132 quad_perm:[2,3,0,1] row_mask:0xf bank_mask:0xf
	v_add_f32_dpp v134, v134, v134 quad_perm:[2,3,0,1] row_mask:0xf bank_mask:0xf
	s_nop 0
	v_add_f32_dpp v132, v132, v132 row_half_mirror row_mask:0xf bank_mask:0xf
	v_add_f32_dpp v134, v134, v134 row_half_mirror row_mask:0xf bank_mask:0xf
	s_nop 0
	v_add_f32_dpp v132, v132, v132 row_mirror row_mask:0xf bank_mask:0xf
	v_add_f32_dpp v134, v134, v134 row_mirror row_mask:0xf bank_mask:0xf
	s_nop 0
	ds_bpermute_b32 v136, v187, v132
	ds_bpermute_b32 v137, v187, v134
	s_waitcnt lgkmcnt(0)
;     __device__ __forceinline__ float* out() const { return (float*)karg_in(33); }
; __device__ __forceinline__ void st4_bf16(bf16* p, v4f o) { v2u w; w.x = cvt_pk_nv(o.x, o.y); w.y = cvt_pk_nv(o.z, o.w); *(v2u*)p = w; }
; __device__ __forceinline__ float ssq4(v4f v) { return (v.x * v.x + v.y * v.y) + (v.z * v.z + v.w * v.w); }
; template <int R, bool BASE_F32, bool OUT_F32>
; __device__ __forceinline__ void rows_res(const Ctx& C, int m0, int stride, int mx, const float* gpost, float scale, int lane) {
;     ...
;     for (int r = 0; r < R; ++r) { float s = 0.f;
; #pragma unroll
;         for (int j = 0; j < 4; ++j) s += ssq4(d[r][j]);
;         r1[r] = s; }
; #pragma unroll
;     for (int r = 0; r < R; ++r) r1[r] = rsqrtf(wave_sum(r1[r]) * (1.f / DM) + EPS) * scale;
; #pragma unroll
;     for (int j = 0; j < 4; ++j) { const v4f gp = ld4_f32(gpost + 4 * lane + 256 * j);
; #pragma unroll
;         for (int r = 0; r < R; ++r) d[r][j] = b[r][j] + d[r][j] * r1[r] * gp; }
;     if (OUT_F32) { float* Y = C.out();
; #pragma unroll
;         for (int r = 0; r < R; ++r)
; #pragma unroll
;             for (int j = 0; j < 4; ++j) if (ok[r]) *(v4f*)(Y + (size_t)mr[r] * DM + 4 * lane + 256 * j) = d[r][j];
;     } else { float* rs = C.RS(); float t[R];
; #pragma unroll
;         for (int r = 0; r < R; ++r) { float s = 0.f;
; #pragma unroll
;             for (int j = 0; j < 4; ++j) s += ssq4(d[r][j]);
;             t[r] = s; }
; #pragma unroll
;         for (int r = 0; r < R; ++r) t[r] = wave_sum(t[r]) * (1.f / DM) + EPS;
; #pragma unroll
;         for (int r = 0; r < R; ++r) { const float rstd = rsqrtf(t[r]);
; #pragma unroll
;             for (int j = 0; j < 4; ++j) if (ok[r]) st4_bf16(XN + (size_t)mr[r] * DM + 4 * lane + 256 * j, d[r][j] * rstd);
;             if (lane == 0 && ok[r]) rs[mr[r]] = sqrtf(t[r]); }
	v_add_f32_e32 v132, v132, v136
	v_add_f32_e32 v134, v134, v137
	ds_bpermute_b32 v136, v188, v132
	ds_bpermute_b32 v137, v188, v134
	s_waitcnt lgkmcnt(0)
	v_add_f32_e32 v132, v132, v136
	v_add_f32_e32 v134, v134, v137
	v_fmamk_f32 v164, v132, 0x3a800000, v138
	v_fmamk_f32 v167, v134, 0x3a800000, v138
	s_nop 0
	v_rsq_f32_e32 v132, v164
	v_rsq_f32_e32 v134, v167
	v_sqrt_f32_e32 v165, v164
	v_sqrt_f32_e32 v168, v167
	s_nop 1
	v_pk_mul_f32 v[140:141], v[96:97], v[132:133] op_sel_hi:[1,0]
	v_cvt_pk_bf16_f32 v148, v140, v141
	v_pk_mul_f32 v[142:143], v[98:99], v[132:133] op_sel_hi:[1,0]
	v_cvt_pk_bf16_f32 v149, v142, v143
	v_pk_mul_f32 v[144:145], v[100:101], v[132:133] op_sel_hi:[1,0]
	v_cvt_pk_bf16_f32 v150, v144, v145
	v_pk_mul_f32 v[146:147], v[102:103], v[132:133] op_sel_hi:[1,0]
	v_cvt_pk_bf16_f32 v151, v146, v147
	v_pk_mul_f32 v[140:141], v[104:105], v[132:133] op_sel_hi:[1,0]
	v_cvt_pk_bf16_f32 v152, v140, v141
	v_pk_mul_f32 v[142:143], v[106:107], v[132:133] op_sel_hi:[1,0]
	v_cvt_pk_bf16_f32 v153, v142, v143
	v_pk_mul_f32 v[144:145], v[108:109], v[132:133] op_sel_hi:[1,0]
	v_cvt_pk_bf16_f32 v154, v144, v145
	v_pk_mul_f32 v[146:147], v[110:111], v[132:133] op_sel_hi:[1,0]
	v_cvt_pk_bf16_f32 v155, v146, v147
	global_store_dwordx4 v173, v[148:151], s[98:99]
	global_store_dwordx4 v173, v[152:155], s[98:99] offset:1024
	v_add_u32_e32 v173, 0x400000, v173
	v_pk_mul_f32 v[140:141], v[112:113], v[134:135] op_sel_hi:[1,0]
	v_cvt_pk_bf16_f32 v156, v140, v141
	v_pk_mul_f32 v[142:143], v[114:115], v[134:135] op_sel_hi:[1,0]
	v_cvt_pk_bf16_f32 v157, v142, v143
	v_pk_mul_f32 v[144:145], v[116:117], v[134:135] op_sel_hi:[1,0]
	v_cvt_pk_bf16_f32 v158, v144, v145
	v_pk_mul_f32 v[146:147], v[118:119], v[134:135] op_sel_hi:[1,0]
	v_cvt_pk_bf16_f32 v159, v146, v147
	v_pk_mul_f32 v[140:141], v[120:121], v[134:135] op_sel_hi:[1,0]
	v_cvt_pk_bf16_f32 v160, v140, v141
	v_pk_mul_f32 v[142:143], v[122:123], v[134:135] op_sel_hi:[1,0]
	v_cvt_pk_bf16_f32 v161, v142, v143
	v_pk_mul_f32 v[144:145], v[124:125], v[134:135] op_sel_hi:[1,0]
	v_cvt_pk_bf16_f32 v162, v144, v145
	v_pk_mul_f32 v[146:147], v[126:127], v[134:135] op_sel_hi:[1,0]
	v_cvt_pk_bf16_f32 v163, v146, v147
	global_store_dwordx4 v173, v[156:159], s[98:99]
	global_store_dwordx4 v173, v[160:163], s[98:99] offset:1024
	v_add_u32_e32 v173, 0x400000, v173
	v_add_u32_e32 v166, -1, v165
	v_fma_f32 v140, -v166, v165, v164
	v_cmp_ge_f32_e32 vcc, 0, v140
	v_add_u32_e32 v141, 1, v165
	v_cndmask_b32_e32 v166, v165, v166, vcc
	v_fma_f32 v140, -v141, v165, v164
	v_cmp_lt_f32_e32 vcc, 0, v140
	s_nop 1
	v_cndmask_b32_e32 v165, v166, v141, vcc
	v_add_u32_e32 v169, -1, v168
	v_fma_f32 v142, -v169, v168, v167
	v_cmp_ge_f32_e32 vcc, 0, v142
	v_add_u32_e32 v143, 1, v168
	v_cndmask_b32_e32 v169, v168, v169, vcc
	v_fma_f32 v142, -v143, v168, v167
	v_cmp_lt_f32_e32 vcc, 0, v142
	s_nop 1
	v_cndmask_b32_e32 v168, v169, v143, vcc
	s_mov_b64 exec, 1
	global_store_dword v174, v165, s[98:99]
	v_add_u32_e32 v174, 0x2000, v174
	global_store_dword v174, v168, s[98:99]
	v_add_u32_e32 v174, 0x2000, v174
	s_mov_b64 exec, -1
	s_waitcnt vmcnt(19)
	v_lshlrev_b32_e32 v96, 16, v208
	v_and_b32_e32 v97, 0xffff0000, v208
	v_lshlrev_b32_e32 v98, 16, v209
	v_and_b32_e32 v99, 0xffff0000, v209
	v_lshlrev_b32_e32 v100, 16, v210
	v_and_b32_e32 v101, 0xffff0000, v210
	v_lshlrev_b32_e32 v102, 16, v211
	v_and_b32_e32 v103, 0xffff0000, v211
	v_lshlrev_b32_e32 v104, 16, v212
	v_and_b32_e32 v105, 0xffff0000, v212
	v_lshlrev_b32_e32 v106, 16, v213
	v_and_b32_e32 v107, 0xffff0000, v213
	v_lshlrev_b32_e32 v108, 16, v214
	v_and_b32_e32 v109, 0xffff0000, v214
	v_lshlrev_b32_e32 v110, 16, v215
	v_and_b32_e32 v111, 0xffff0000, v215
	v_pk_mul_f32 v[128:129], v[96:97], v[96:97]
	v_pk_fma_f32 v[128:129], v[98:99], v[98:99], v[128:129]
	v_pk_fma_f32 v[128:129], v[100:101], v[100:101], v[128:129]
	v_pk_fma_f32 v[128:129], v[102:103], v[102:103], v[128:129]
	v_pk_fma_f32 v[128:129], v[104:105], v[104:105], v[128:129]
	v_pk_fma_f32 v[128:129], v[106:107], v[106:107], v[128:129]
	v_pk_fma_f32 v[128:129], v[108:109], v[108:109], v[128:129]
	v_pk_fma_f32 v[128:129], v[110:111], v[110:111], v[128:129]
	s_nop 0
	v_add_f32_e32 v128, v128, v129
	s_waitcnt vmcnt(14)
	v_lshlrev_b32_e32 v112, 16, v216
	v_and_b32_e32 v113, 0xffff0000, v216
	v_lshlrev_b32_e32 v114, 16, v217
	v_and_b32_e32 v115, 0xffff0000, v217
	v_lshlrev_b32_e32 v116, 16, v218
	v_and_b32_e32 v117, 0xffff0000, v218
	v_lshlrev_b32_e32 v118, 16, v219
	v_and_b32_e32 v119, 0xffff0000, v219
	v_lshlrev_b32_e32 v120, 16, v220
	v_and_b32_e32 v121, 0xffff0000, v220
	v_lshlrev_b32_e32 v122, 16, v221
	v_and_b32_e32 v123, 0xffff0000, v221
	v_lshlrev_b32_e32 v124, 16, v222
	v_and_b32_e32 v125, 0xffff0000, v222
	v_lshlrev_b32_e32 v126, 16, v223
	v_and_b32_e32 v127, 0xffff0000, v223
	v_pk_mul_f32 v[130:131], v[112:113], v[112:113]
	v_pk_fma_f32 v[130:131], v[114:115], v[114:115], v[130:131]
	v_pk_fma_f32 v[130:131], v[116:117], v[116:117], v[130:131]
	v_pk_fma_f32 v[130:131], v[118:119], v[118:119], v[130:131]
	v_pk_fma_f32 v[130:131], v[120:121], v[120:121], v[130:131]
	v_pk_fma_f32 v[130:131], v[122:123], v[122:123], v[130:131]
	v_pk_fma_f32 v[130:131], v[124:125], v[124:125], v[130:131]
	v_pk_fma_f32 v[130:131], v[126:127], v[126:127], v[130:131]
	s_nop 0
	v_add_f32_e32 v130, v130, v131
	s_nop 1
	v_add_f32_dpp v128, v128, v128 quad_perm:[1,0,3,2] row_mask:0xf bank_mask:0xf
	v_add_f32_dpp v130, v130, v130 quad_perm:[1,0,3,2] row_mask:0xf bank_mask:0xf
	s_nop 0
	v_add_f32_dpp v128, v128, v128 quad_perm:[2,3,0,1] row_mask:0xf bank_mask:0xf
	v_add_f32_dpp v130, v130, v130 quad_perm:[2,3,0,1] row_mask:0xf bank_mask:0xf
	s_nop 0
	v_add_f32_dpp v128, v128, v128 row_half_mirror row_mask:0xf bank_mask:0xf
	v_add_f32_dpp v130, v130, v130 row_half_mirror row_mask:0xf bank_mask:0xf
	s_nop 0
	v_add_f32_dpp v128, v128, v128 row_mirror row_mask:0xf bank_mask:0xf
	v_add_f32_dpp v130, v130, v130 row_mirror row_mask:0xf bank_mask:0xf
	s_nop 0
	ds_bpermute_b32 v136, v187, v128
	ds_bpermute_b32 v137, v187, v130
	s_waitcnt lgkmcnt(0)
;     __device__ __forceinline__ float* out() const { return (float*)karg_in(33); }
; __device__ __forceinline__ float ssq4(v4f v) { return (v.x * v.x + v.y * v.y) + (v.z * v.z + v.w * v.w); }
; template <int R, bool BASE_F32, bool OUT_F32>
; __device__ __forceinline__ void rows_res(const Ctx& C, int m0, int stride, int mx, const float* gpost, float scale, int lane) {
;     ...
;     for (int r = 0; r < R; ++r) r1[r] = rsqrtf(wave_sum(r1[r]) * (1.f / DM) + EPS) * scale;
; #pragma unroll
;     for (int j = 0; j < 4; ++j) { const v4f gp = ld4_f32(gpost + 4 * lane + 256 * j);
; #pragma unroll
;         for (int r = 0; r < R; ++r) d[r][j] = b[r][j] + d[r][j] * r1[r] * gp; }
;     if (OUT_F32) { float* Y = C.out();
; #pragma unroll
;         for (int r = 0; r < R; ++r)
; #pragma unroll
;             for (int j = 0; j < 4; ++j) if (ok[r]) *(v4f*)(Y + (size_t)mr[r] * DM + 4 * lane + 256 * j) = d[r][j];
;     } else { float* rs = C.RS(); float t[R];
; #pragma unroll
;         for (int r = 0; r < R; ++r) { float s = 0.f;
; #pragma unroll
;             for (int j = 0; j < 4; ++j) s += ssq4(d[r][j]);
;             t[r] = s; }
	v_add_f32_e32 v128, v128, v136
	v_add_f32_e32 v130, v130, v137
	ds_bpermute_b32 v136, v188, v128
	ds_bpermute_b32 v137, v188, v130
	s_waitcnt lgkmcnt(0)
	v_add_f32_e32 v128, v128, v136
	v_add_f32_e32 v130, v130, v137
	v_fmamk_f32 v128, v128, 0x3a800000, v138
	v_fmamk_f32 v130, v130, 0x3a800000, v138
	s_nop 0
	v_rsq_f32_e32 v128, v128
	v_rsq_f32_e32 v130, v130
	s_nop 1
	s_waitcnt vmcnt(12)
	v_pk_mul_f32 v[96:97], v[128:129], v[96:97] op_sel_hi:[0,1]
	v_pk_mul_f32 v[98:99], v[128:129], v[98:99] op_sel_hi:[0,1]
	v_pk_mul_f32 v[100:101], v[128:129], v[100:101] op_sel_hi:[0,1]
	v_pk_mul_f32 v[102:103], v[128:129], v[102:103] op_sel_hi:[0,1]
	v_pk_mul_f32 v[104:105], v[128:129], v[104:105] op_sel_hi:[0,1]
	v_pk_mul_f32 v[106:107], v[128:129], v[106:107] op_sel_hi:[0,1]
	v_pk_mul_f32 v[108:109], v[128:129], v[108:109] op_sel_hi:[0,1]
	v_pk_mul_f32 v[110:111], v[128:129], v[110:111] op_sel_hi:[0,1]
	v_pk_mul_f32 v[96:97], v[96:97], v[192:193]
	v_pk_mul_f32 v[98:99], v[98:99], v[194:195]
	v_pk_mul_f32 v[100:101], v[100:101], v[196:197]
	v_pk_mul_f32 v[102:103], v[102:103], v[198:199]
	v_pk_mul_f32 v[104:105], v[104:105], v[200:201]
	v_pk_mul_f32 v[106:107], v[106:107], v[202:203]
	v_pk_mul_f32 v[108:109], v[108:109], v[204:205]
	v_pk_mul_f32 v[110:111], v[110:111], v[206:207]
	v_lshlrev_b32_e32 v208, 16, v224
	v_and_b32_e32 v209, 0xffff0000, v224
	v_lshlrev_b32_e32 v210, 16, v225
	v_and_b32_e32 v211, 0xffff0000, v225
	v_lshlrev_b32_e32 v212, 16, v226
	v_and_b32_e32 v213, 0xffff0000, v226
	v_lshlrev_b32_e32 v214, 16, v227
	v_and_b32_e32 v215, 0xffff0000, v227
	v_pk_fma_f32 v[96:97], v[12:13], v[208:209], v[96:97] op_sel_hi:[0,1,1]
	v_pk_fma_f32 v[98:99], v[12:13], v[210:211], v[98:99] op_sel_hi:[0,1,1]
	v_pk_fma_f32 v[100:101], v[12:13], v[212:213], v[100:101] op_sel_hi:[0,1,1]
	v_pk_fma_f32 v[102:103], v[12:13], v[214:215], v[102:103] op_sel_hi:[0,1,1]
	v_lshlrev_b32_e32 v208, 16, v228
	v_and_b32_e32 v209, 0xffff0000, v228
	v_lshlrev_b32_e32 v210, 16, v229
	v_and_b32_e32 v211, 0xffff0000, v229
	v_lshlrev_b32_e32 v212, 16, v230
	v_and_b32_e32 v213, 0xffff0000, v230
	v_lshlrev_b32_e32 v214, 16, v231
	v_and_b32_e32 v215, 0xffff0000, v231
	v_pk_fma_f32 v[104:105], v[12:13], v[208:209], v[104:105] op_sel_hi:[0,1,1]
	v_pk_fma_f32 v[106:107], v[12:13], v[210:211], v[106:107] op_sel_hi:[0,1,1]
	v_pk_fma_f32 v[108:109], v[12:13], v[212:213], v[108:109] op_sel_hi:[0,1,1]
	v_pk_fma_f32 v[110:111], v[12:13], v[214:215], v[110:111] op_sel_hi:[0,1,1]
	v_pk_mul_f32 v[132:133], v[96:97], v[96:97]
	v_pk_fma_f32 v[132:133], v[98:99], v[98:99], v[132:133]
	v_pk_fma_f32 v[132:133], v[100:101], v[100:101], v[132:133]
	v_pk_fma_f32 v[132:133], v[102:103], v[102:103], v[132:133]
	v_pk_fma_f32 v[132:133], v[104:105], v[104:105], v[132:133]
	v_pk_fma_f32 v[132:133], v[106:107], v[106:107], v[132:133]
	v_pk_fma_f32 v[132:133], v[108:109], v[108:109], v[132:133]
	v_pk_fma_f32 v[132:133], v[110:111], v[110:111], v[132:133]
	s_nop 0
	v_add_f32_e32 v132, v132, v133
	v_pk_mul_f32 v[112:113], v[130:131], v[112:113] op_sel_hi:[0,1]
	v_pk_mul_f32 v[114:115], v[130:131], v[114:115] op_sel_hi:[0,1]
	v_pk_mul_f32 v[116:117], v[130:131], v[116:117] op_sel_hi:[0,1]
	v_pk_mul_f32 v[118:119], v[130:131], v[118:119] op_sel_hi:[0,1]
	v_pk_mul_f32 v[120:121], v[130:131], v[120:121] op_sel_hi:[0,1]
	v_pk_mul_f32 v[122:123], v[130:131], v[122:123] op_sel_hi:[0,1]
	v_pk_mul_f32 v[124:125], v[130:131], v[124:125] op_sel_hi:[0,1]
	v_pk_mul_f32 v[126:127], v[130:131], v[126:127] op_sel_hi:[0,1]
	v_pk_mul_f32 v[112:113], v[112:113], v[192:193]
	v_pk_mul_f32 v[114:115], v[114:115], v[194:195]
	v_pk_mul_f32 v[116:117], v[116:117], v[196:197]
	v_pk_mul_f32 v[118:119], v[118:119], v[198:199]
	v_pk_mul_f32 v[120:121], v[120:121], v[200:201]
	v_pk_mul_f32 v[122:123], v[122:123], v[202:203]
	v_pk_mul_f32 v[124:125], v[124:125], v[204:205]
	v_pk_mul_f32 v[126:127], v[126:127], v[206:207]
	v_lshlrev_b32_e32 v216, 16, v4
	v_and_b32_e32 v217, 0xffff0000, v4
	v_lshlrev_b32_e32 v218, 16, v5
	v_and_b32_e32 v219, 0xffff0000, v5
	v_lshlrev_b32_e32 v220, 16, v6
	v_and_b32_e32 v221, 0xffff0000, v6
	v_lshlrev_b32_e32 v222, 16, v7
	v_and_b32_e32 v223, 0xffff0000, v7
	v_pk_fma_f32 v[112:113], v[14:15], v[216:217], v[112:113] op_sel_hi:[0,1,1]
	v_pk_fma_f32 v[114:115], v[14:15], v[218:219], v[114:115] op_sel_hi:[0,1,1]
	v_pk_fma_f32 v[116:117], v[14:15], v[220:221], v[116:117] op_sel_hi:[0,1,1]
	v_pk_fma_f32 v[118:119], v[14:15], v[222:223], v[118:119] op_sel_hi:[0,1,1]
	v_lshlrev_b32_e32 v216, 16, v8
	v_and_b32_e32 v217, 0xffff0000, v8
	v_lshlrev_b32_e32 v218, 16, v9
	v_and_b32_e32 v219, 0xffff0000, v9
	v_lshlrev_b32_e32 v220, 16, v10
	v_and_b32_e32 v221, 0xffff0000, v10
	v_lshlrev_b32_e32 v222, 16, v11
	v_and_b32_e32 v223, 0xffff0000, v11
	v_pk_fma_f32 v[120:121], v[14:15], v[216:217], v[120:121] op_sel_hi:[0,1,1]
	v_pk_fma_f32 v[122:123], v[14:15], v[218:219], v[122:123] op_sel_hi:[0,1,1]
	v_pk_fma_f32 v[124:125], v[14:15], v[220:221], v[124:125] op_sel_hi:[0,1,1]
	v_pk_fma_f32 v[126:127], v[14:15], v[222:223], v[126:127] op_sel_hi:[0,1,1]
	v_pk_mul_f32 v[134:135], v[112:113], v[112:113]
	v_pk_fma_f32 v[134:135], v[114:115], v[114:115], v[134:135]
	v_pk_fma_f32 v[134:135], v[116:117], v[116:117], v[134:135]
	v_pk_fma_f32 v[134:135], v[118:119], v[118:119], v[134:135]
	v_pk_fma_f32 v[134:135], v[120:121], v[120:121], v[134:135]
	v_pk_fma_f32 v[134:135], v[122:123], v[122:123], v[134:135]
	v_pk_fma_f32 v[134:135], v[124:125], v[124:125], v[134:135]
	v_pk_fma_f32 v[134:135], v[126:127], v[126:127], v[134:135]
	s_nop 0
	v_add_f32_e32 v134, v134, v135
	s_nop 1
	v_add_f32_dpp v132, v132, v132 quad_perm:[1,0,3,2] row_mask:0xf bank_mask:0xf
	v_add_f32_dpp v134, v134, v134 quad_perm:[1,0,3,2] row_mask:0xf bank_mask:0xf
	s_nop 0
	v_add_f32_dpp v132, v132, v132 quad_perm:[2,3,0,1] row_mask:0xf bank_mask:0xf
	v_add_f32_dpp v134, v134, v134 quad_perm:[2,3,0,1] row_mask:0xf bank_mask:0xf
	s_nop 0
	v_add_f32_dpp v132, v132, v132 row_half_mirror row_mask:0xf bank_mask:0xf
	v_add_f32_dpp v134, v134, v134 row_half_mirror row_mask:0xf bank_mask:0xf
	s_nop 0
	v_add_f32_dpp v132, v132, v132 row_mirror row_mask:0xf bank_mask:0xf
	v_add_f32_dpp v134, v134, v134 row_mirror row_mask:0xf bank_mask:0xf
	s_nop 0
	ds_bpermute_b32 v136, v187, v132
	ds_bpermute_b32 v137, v187, v134
	s_waitcnt lgkmcnt(0)
; __device__ __forceinline__ void st4_bf16(bf16* p, v4f o) { v2u w; w.x = cvt_pk_nv(o.x, o.y); w.y = cvt_pk_nv(o.z, o.w); *(v2u*)p = w; }
; template <int R, bool BASE_F32, bool OUT_F32>
; __device__ __forceinline__ void rows_res(const Ctx& C, int m0, int stride, int mx, const float* gpost, float scale, int lane) {
;     ...
;         for (int r = 0; r < R; ++r) t[r] = wave_sum(t[r]) * (1.f / DM) + EPS;
; #pragma unroll
;         for (int r = 0; r < R; ++r) { const float rstd = rsqrtf(t[r]);
; #pragma unroll
;             for (int j = 0; j < 4; ++j) if (ok[r]) st4_bf16(XN + (size_t)mr[r] * DM + 4 * lane + 256 * j, d[r][j] * rstd);
;             if (lane == 0 && ok[r]) rs[mr[r]] = sqrtf(t[r]); }
	v_add_f32_e32 v132, v132, v136
	v_add_f32_e32 v134, v134, v137
	ds_bpermute_b32 v136, v188, v132
	ds_bpermute_b32 v137, v188, v134
	s_waitcnt lgkmcnt(0)
	v_add_f32_e32 v132, v132, v136
	v_add_f32_e32 v134, v134, v137
	v_fmamk_f32 v164, v132, 0x3a800000, v138
	v_fmamk_f32 v167, v134, 0x3a800000, v138
	s_nop 0
	v_rsq_f32_e32 v132, v164
	v_rsq_f32_e32 v134, v167
	v_sqrt_f32_e32 v165, v164
	v_sqrt_f32_e32 v168, v167
	s_nop 1
	v_pk_mul_f32 v[140:141], v[96:97], v[132:133] op_sel_hi:[1,0]
	v_cvt_pk_bf16_f32 v148, v140, v141
	v_pk_mul_f32 v[142:143], v[98:99], v[132:133] op_sel_hi:[1,0]
	v_cvt_pk_bf16_f32 v149, v142, v143
	v_pk_mul_f32 v[144:145], v[100:101], v[132:133] op_sel_hi:[1,0]
	v_cvt_pk_bf16_f32 v150, v144, v145
	v_pk_mul_f32 v[146:147], v[102:103], v[132:133] op_sel_hi:[1,0]
	v_cvt_pk_bf16_f32 v151, v146, v147
	v_pk_mul_f32 v[140:141], v[104:105], v[132:133] op_sel_hi:[1,0]
	v_cvt_pk_bf16_f32 v152, v140, v141
	v_pk_mul_f32 v[142:143], v[106:107], v[132:133] op_sel_hi:[1,0]
	v_cvt_pk_bf16_f32 v153, v142, v143
	v_pk_mul_f32 v[144:145], v[108:109], v[132:133] op_sel_hi:[1,0]
	v_cvt_pk_bf16_f32 v154, v144, v145
	v_pk_mul_f32 v[146:147], v[110:111], v[132:133] op_sel_hi:[1,0]
	v_cvt_pk_bf16_f32 v155, v146, v147
	global_store_dwordx4 v173, v[148:151], s[98:99]
	global_store_dwordx4 v173, v[152:155], s[98:99] offset:1024
	v_add_u32_e32 v173, 0x400000, v173
	v_pk_mul_f32 v[140:141], v[112:113], v[134:135] op_sel_hi:[1,0]
	v_cvt_pk_bf16_f32 v156, v140, v141
	v_pk_mul_f32 v[142:143], v[114:115], v[134:135] op_sel_hi:[1,0]
	v_cvt_pk_bf16_f32 v157, v142, v143
	v_pk_mul_f32 v[144:145], v[116:117], v[134:135] op_sel_hi:[1,0]
	v_cvt_pk_bf16_f32 v158, v144, v145
	v_pk_mul_f32 v[146:147], v[118:119], v[134:135] op_sel_hi:[1,0]
	v_cvt_pk_bf16_f32 v159, v146, v147
	v_pk_mul_f32 v[140:141], v[120:121], v[134:135] op_sel_hi:[1,0]
	v_cvt_pk_bf16_f32 v160, v140, v141
	v_pk_mul_f32 v[142:143], v[122:123], v[134:135] op_sel_hi:[1,0]
	v_cvt_pk_bf16_f32 v161, v142, v143
	v_pk_mul_f32 v[144:145], v[124:125], v[134:135] op_sel_hi:[1,0]
	v_cvt_pk_bf16_f32 v162, v144, v145
	v_pk_mul_f32 v[146:147], v[126:127], v[134:135] op_sel_hi:[1,0]
	v_cvt_pk_bf16_f32 v163, v146, v147
	global_store_dwordx4 v173, v[156:159], s[98:99]
	global_store_dwordx4 v173, v[160:163], s[98:99] offset:1024
	v_add_u32_e32 v173, 0x400000, v173
	v_add_u32_e32 v166, -1, v165
	v_fma_f32 v140, -v166, v165, v164
	v_cmp_ge_f32_e32 vcc, 0, v140
	v_add_u32_e32 v141, 1, v165
	v_cndmask_b32_e32 v166, v165, v166, vcc
	v_fma_f32 v140, -v141, v165, v164
	v_cmp_lt_f32_e32 vcc, 0, v140
	s_nop 1
	v_cndmask_b32_e32 v165, v166, v141, vcc
	v_add_u32_e32 v169, -1, v168
	v_fma_f32 v142, -v169, v168, v167
	v_cmp_ge_f32_e32 vcc, 0, v142
	v_add_u32_e32 v143, 1, v168
	v_cndmask_b32_e32 v169, v168, v169, vcc
	v_fma_f32 v142, -v143, v168, v167
	v_cmp_lt_f32_e32 vcc, 0, v142
	s_nop 1
	v_cndmask_b32_e32 v168, v169, v143, vcc
	s_mov_b64 exec, 1
	global_store_dword v174, v165, s[98:99]
	v_add_u32_e32 v174, 0x2000, v174
	global_store_dword v174, v168, s[98:99]
	v_add_u32_e32 v174, 0x2000, v174
	s_mov_b64 exec, -1
	s_branch .LBB0_1013
	v_mov_b32_e32 v3, v1
	s_mov_b32 s0, 0x358637bd
	s_waitcnt lgkmcnt(0)
	v_lshl_add_u64 v[4:5], s[16:17], 0, v[2:3]
	s_mov_b64 s[18:19], 0x7100000
	s_mov_b64 s[20:21], 0x3000000
	v_mov_b32_e32 v3, 0x2a80000
	s_mov_b32 s22, 0x3a800000
	v_mov_b64_e32 v[6:7], s[0:1]
	s_mov_b32 s42, 0x800000
	v_mov_b32_e32 v41, 0x358637bd
	s_mov_b32 s43, 0xf800000
	v_mov_b32_e32 v148, 0x260
	s_mov_b32 s24, s23
	v_readlane_b32 s56, v232, 5
	s_branch .LBB0_997
